# attention loop: barrier rotated so 4 PV MFMAs cover post-barrier LDS latency, DMA issue moved to phase B; P4 conv epilogue: dead zero-inits before full-mask DPP movs removed
# speedup vs baseline: 1.0036x; 1.0036x over previous
; __device__ __forceinline__ void attn_phase_fast(LAS unsigned char* lds, const bf16_t* q, const bf16_t* k, const bf16_t* vT, bf16_t* mixed, float lam, const int wave_s) {
;     ...
;                 ATT_DMA(nb, Kg + (size_t)(t + 1) * 64 * 512, Vg + (t + 1) * 64);
;             }
;             const LAS unsigned char* Qs = lds + 2 * ABUF + wid * (32 * QROW) + r32 * QROW + hi * 16;
;             int kxh = (kx >> 1) << 5, vxh = (vx >> 1) << 5, kq = cb + r32 * KROW + ((hi ^ (kx & 1)) << 4), vq = cb + KBUF + r32 * VROW + ((hi ^ (vx & 1)) << 4);
;             asm volatile("" : "+v"(kxh), "+v"(vxh), "+v"(kq), "+v"(vq));
;             const LAS unsigned char* Kb = lds + kq;
;             const LAS unsigned char* Vb = lds + vq;
; #pragma unroll
;             for (int m = 0; m < 2; ++m) {
;                 f32x16 s0, s1;
; #pragma unroll
;                 for (int i = 0; i < 16; ++i) { s0[i] = 0.f; s1[i] = 0.f; }
; #pragma unroll
;                 for (int d0 = 0; d0 < 4; ++d0) {
;                     const int kpos = ((m * 4 + d0) << 5) ^ kxh;
;                     const bf16x8 k0 = *(const LAS bf16x8*)(Kb + kpos), k1 = *(const LAS bf16x8*)(Kb + 32 * KROW + kpos);
;                     const bf16x8 qv = *(const LAS bf16x8*)(Qs + m * 128 + d0 * 32);
;                     s0 = MFMA32(k0, qv, s0); s1 = MFMA32(k1, qv, s1);
;                 }
;                 __builtin_amdgcn_sched_barrier(0);
;                 float ls = 0.f, ls2 = 0.f;
; #pragma unroll
;                 for (int i = 0; i < 16; ++i) { float e0 = __builtin_amdgcn_exp2f(s0[i]), e1 = __builtin_amdgcn_exp2f(s1[i]); asm volatile("" : "+v"(e0), "+v"(e1)); s0[i] = e0; s1[i] = e1; ls += e0; ls2 += e1; }
;                 ls += ls2;
;                 l[m] += ls;
;                 const bf16x8 p0 = packp(s0, 0), p1 = packp(s0, 1), p2 = packp(s1, 0), p3 = packp(s1, 1);
; #pragma unroll
;                 for (int db = 0; db < 4; ++db) {
;                     const LAS unsigned char* vb = Vb + db * 32 * VROW;
;                     const bf16x8 v0 = *(const LAS bf16x8*)(vb + (0 ^ vxh)), v1 = *(const LAS bf16x8*)(vb + (32 ^ vxh)), v2 = *(const LAS bf16x8*)(vb + (64 ^ vxh)), v3 = *(const LAS bf16x8*)(vb + (96 ^ vxh));
;                     o[m][db] = MFMA32(v0, p0, o[m][db]); o[m][db] = MFMA32(v1, p1, o[m][db]); o[m][db] = MFMA32(v2, p2, o[m][db]); o[m][db] = MFMA32(v3, p3, o[m][db]);
.Lattn_tile_loop:
	ds_read_b128 v[144:147], v196
	ds_read_b128 v[148:151], v197
	ds_read_b128 v[152:155], v198
	ds_read_b128 v[156:159], v199
	ds_read_b128 v[164:167], v196 offset:8192
	ds_read_b128 v[168:171], v197 offset:8192
	ds_read_b128 v[172:175], v198 offset:8192
	ds_read_b128 v[212:215], v199 offset:8192
	s_cmp_eq_u32 s44, 0
	s_cbranch_scc1 .Lattn_skip_tail
	v_mfma_f32_32x32x16_bf16 v[96:111], v[216:219], v[176:179], v[96:111]
	v_mfma_f32_32x32x16_bf16 v[64:79], v[238:241], v[176:179], v[64:79]
	v_mfma_f32_32x32x16_bf16 v[32:47], v[220:223], v[176:179], v[32:47]
	v_mfma_f32_32x32x16_bf16 v[0:15], v[242:245], v[176:179], v[0:15]
.Lattn_skip_tail:
	s_waitcnt lgkmcnt(7)
	v_mfma_f32_32x32x16_bf16 v[128:143], v[144:147], v[180:183], 0
	ds_read_b128 v[216:219], v228 offset:128
	s_waitcnt lgkmcnt(7)
	v_mfma_f32_32x32x16_bf16 v[128:143], v[148:151], v[184:187], v[128:143]
	ds_read_b128 v[220:223], v228 offset:160
	s_waitcnt lgkmcnt(7)
	v_mfma_f32_32x32x16_bf16 v[128:143], v[152:155], v[188:191], v[128:143]
	ds_read_b128 v[224:227], v228 offset:192
	s_waitcnt lgkmcnt(7)
	v_mfma_f32_32x32x16_bf16 v[128:143], v[156:159], v[192:195], v[128:143]
	ds_read_b128 v[234:237], v228 offset:224
	s_waitcnt lgkmcnt(7)
	v_mfma_f32_32x32x16_bf16 v[144:159], v[164:167], v[180:183], 0
	ds_read_b128 v[180:183], v200
	ds_read_b128 v[238:241], v200 offset:8192
	s_waitcnt lgkmcnt(8)
	v_mfma_f32_32x32x16_bf16 v[144:159], v[168:171], v[184:187], v[144:159]
	ds_read_b128 v[184:187], v201
	ds_read_b128 v[242:245], v201 offset:8192
	s_waitcnt lgkmcnt(9)
	v_mfma_f32_32x32x16_bf16 v[144:159], v[172:175], v[188:191], v[144:159]
	ds_read_b128 v[188:191], v202
	ds_read_b128 v[246:249], v202 offset:8192
	s_waitcnt lgkmcnt(10)
	v_mfma_f32_32x32x16_bf16 v[144:159], v[212:215], v[192:195], v[144:159]
	ds_read_b128 v[192:195], v203
	ds_read_b128 v[212:215], v203 offset:8192
	v_exp_f32_e32 v128, v128
	v_exp_f32_e32 v129, v129
	v_add_f32_e32 v162, v162, v128
	v_exp_f32_e32 v130, v130
	v_add_f32_e32 v162, v162, v129
	s_waitcnt lgkmcnt(7)
	v_mfma_f32_32x32x16_bf16 v[164:179], v[180:183], v[216:219], 0
	ds_read_b128 v[250:253], v204
	s_add_i32 m0, s22, 0x8000
	s_nop 0
	global_load_lds_dwordx4 v208, s[6:7]
	v_exp_f32_e32 v131, v131
	v_add_f32_e32 v162, v162, v130
	v_cvt_pk_bf16_f32 v128, v128, v129
	v_exp_f32_e32 v132, v132
	v_add_f32_e32 v162, v162, v131
	s_waitcnt lgkmcnt(6)
	v_mfma_f32_32x32x16_bf16 v[164:179], v[184:187], v[220:223], v[164:179]
	s_add_i32 m0, s24, 0x8000
	s_nop 0
	global_load_lds_dwordx4 v209, s[2:3]
	v_exp_f32_e32 v133, v133
	v_add_f32_e32 v162, v162, v132
	v_cvt_pk_bf16_f32 v129, v130, v131
	v_exp_f32_e32 v134, v134
	v_add_f32_e32 v162, v162, v133
	s_waitcnt lgkmcnt(4)
	v_mfma_f32_32x32x16_bf16 v[164:179], v[188:191], v[224:227], v[164:179]
	s_add_i32 m0, s26, 0x8000
	s_nop 0
	global_load_lds_dwordx4 v210, s[6:7]
	v_exp_f32_e32 v135, v135
	v_add_f32_e32 v162, v162, v134
	v_cvt_pk_bf16_f32 v130, v132, v133
	v_exp_f32_e32 v136, v136
	v_add_f32_e32 v162, v162, v135
	s_waitcnt lgkmcnt(2)
	v_mfma_f32_32x32x16_bf16 v[164:179], v[192:195], v[234:237], v[164:179]
	s_add_i32 m0, s27, 0x8000
	s_nop 0
	global_load_lds_dwordx4 v211, s[2:3]
	s_add_u32 s6, s6, 0x10000
	s_addc_u32 s7, s7, 0
	s_add_u32 s2, s2, 0x80
	s_addc_u32 s3, s3, 0
	v_exp_f32_e32 v137, v137
	v_add_f32_e32 v162, v162, v136
	v_cvt_pk_bf16_f32 v131, v134, v135
	v_exp_f32_e32 v138, v138
	v_add_f32_e32 v162, v162, v137
	v_mfma_f32_32x32x16_bf16 v[180:195], v[238:241], v[216:219], 0
	ds_read_b128 v[216:219], v204 offset:4096
	ds_read_b128 v[238:241], v204 offset:8192
	v_exp_f32_e32 v139, v139
	v_add_f32_e32 v162, v162, v138
	v_cvt_pk_bf16_f32 v132, v136, v137
	v_exp_f32_e32 v140, v140
	v_add_f32_e32 v162, v162, v139
	v_mfma_f32_32x32x16_bf16 v[180:195], v[242:245], v[220:223], v[180:195]
	ds_read_b128 v[220:223], v204 offset:12288
	ds_read_b128 v[242:245], v205
	v_exp_f32_e32 v141, v141
	v_add_f32_e32 v162, v162, v140
	v_cvt_pk_bf16_f32 v133, v138, v139
	v_exp_f32_e32 v142, v142
	v_add_f32_e32 v162, v162, v141
	v_mfma_f32_32x32x16_bf16 v[180:195], v[246:249], v[224:227], v[180:195]
	ds_read_b128 v[224:227], v205 offset:4096
	ds_read_b128 v[246:249], v205 offset:8192
	v_exp_f32_e32 v143, v143
	v_add_f32_e32 v162, v162, v142
	v_cvt_pk_bf16_f32 v134, v140, v141
	v_add_f32_e32 v162, v162, v143
	v_cvt_pk_bf16_f32 v135, v142, v143
	s_waitcnt lgkmcnt(7)
	v_mfma_f32_32x32x16_bf16 v[180:195], v[212:215], v[234:237], v[180:195]
	ds_read_b128 v[212:215], v205 offset:12288
	ds_read_b128 v[234:237], v206
	v_exp_f32_e32 v144, v144
	v_exp_f32_e32 v145, v145
	v_add_f32_e32 v162, v162, v144
	v_exp_f32_e32 v146, v146
	v_add_f32_e32 v162, v162, v145
	s_waitcnt lgkmcnt(8)
	v_mfma_f32_32x32x16_bf16 v[112:127], v[250:253], v[128:131], v[112:127]
	ds_read_b128 v[250:253], v206 offset:4096
	v_exp_f32_e32 v147, v147
	v_add_f32_e32 v162, v162, v146
	v_cvt_pk_bf16_f32 v136, v144, v145
	v_exp_f32_e32 v148, v148
	v_add_f32_e32 v162, v162, v147
	s_waitcnt lgkmcnt(8)
	v_mfma_f32_32x32x16_bf16 v[80:95], v[216:219], v[128:131], v[80:95]
	ds_read_b128 v[216:219], v206 offset:8192
	v_exp_f32_e32 v149, v149
	v_add_f32_e32 v162, v162, v148
	v_cvt_pk_bf16_f32 v137, v146, v147
	v_exp_f32_e32 v150, v150
	v_add_f32_e32 v162, v162, v149
	s_waitcnt lgkmcnt(8)
	v_mfma_f32_32x32x16_bf16 v[48:63], v[238:241], v[128:131], v[48:63]
	ds_read_b128 v[238:241], v206 offset:12288
	v_exp_f32_e32 v151, v151
	v_add_f32_e32 v162, v162, v150
	v_cvt_pk_bf16_f32 v138, v148, v149
	v_exp_f32_e32 v152, v152
	v_add_f32_e32 v162, v162, v151
	s_waitcnt lgkmcnt(8)
; #define LAS __attribute__((address_space(3)))
; #define MFMA32(a, b, c) __builtin_amdgcn_mfma_f32_32x32x16_bf16((a), (b), (c), 0, 0, 0)
; __device__ __forceinline__ void attn_phase_fast(LAS unsigned char* lds, const bf16_t* q, const bf16_t* k, const bf16_t* vT, bf16_t* mixed, float lam, const int wave_s) {
;     ...
; #pragma unroll
;                 for (int i = 0; i < 16; ++i) { float e0 = __builtin_amdgcn_exp2f(s0[i]), e1 = __builtin_amdgcn_exp2f(s1[i]); asm volatile("" : "+v"(e0), "+v"(e1)); s0[i] = e0; s1[i] = e1; ls += e0; ls2 += e1; }
;                 ls += ls2;
;                 l[m] += ls;
;                 const bf16x8 p0 = packp(s0, 0), p1 = packp(s0, 1), p2 = packp(s1, 0), p3 = packp(s1, 1);
; #pragma unroll
;                 for (int db = 0; db < 4; ++db) {
;                     const LAS unsigned char* vb = Vb + db * 32 * VROW;
;                     const bf16x8 v0 = *(const LAS bf16x8*)(vb + (0 ^ vxh)), v1 = *(const LAS bf16x8*)(vb + (32 ^ vxh)), v2 = *(const LAS bf16x8*)(vb + (64 ^ vxh)), v3 = *(const LAS bf16x8*)(vb + (96 ^ vxh));
;                     o[m][db] = MFMA32(v0, p0, o[m][db]); o[m][db] = MFMA32(v1, p1, o[m][db]); o[m][db] = MFMA32(v2, p2, o[m][db]); o[m][db] = MFMA32(v3, p3, o[m][db]);
;                     if (db == 1) __builtin_amdgcn_sched_barrier(0);
;                 }
;                 __builtin_amdgcn_sched_barrier(0);
;             }
;             asm volatile("s_waitcnt vmcnt(0)" ::: "memory");
;             __syncthreads();
	v_mfma_f32_32x32x16_bf16 v[16:31], v[220:223], v[128:131], v[16:31]
	ds_read_b128 v[220:223], v207
	v_exp_f32_e32 v153, v153
	v_add_f32_e32 v162, v162, v152
	v_cvt_pk_bf16_f32 v139, v150, v151
	v_exp_f32_e32 v154, v154
	v_add_f32_e32 v162, v162, v153
	s_waitcnt lgkmcnt(8)
	v_mfma_f32_32x32x16_bf16 v[112:127], v[242:245], v[132:135], v[112:127]
	ds_read_b128 v[242:245], v207 offset:4096
	v_exp_f32_e32 v155, v155
	v_add_f32_e32 v162, v162, v154
	v_cvt_pk_bf16_f32 v140, v152, v153
	v_exp_f32_e32 v156, v156
	v_add_f32_e32 v162, v162, v155
	s_waitcnt lgkmcnt(8)
	v_mfma_f32_32x32x16_bf16 v[80:95], v[224:227], v[132:135], v[80:95]
	ds_read_b128 v[224:227], v207 offset:8192
	v_exp_f32_e32 v157, v157
	v_add_f32_e32 v162, v162, v156
	v_cvt_pk_bf16_f32 v141, v154, v155
	v_exp_f32_e32 v158, v158
	v_add_f32_e32 v162, v162, v157
	s_waitcnt lgkmcnt(8)
	v_mfma_f32_32x32x16_bf16 v[48:63], v[246:249], v[132:135], v[48:63]
	ds_read_b128 v[246:249], v207 offset:12288
	v_exp_f32_e32 v159, v159
	v_add_f32_e32 v162, v162, v158
	v_cvt_pk_bf16_f32 v142, v156, v157
	v_add_f32_e32 v162, v162, v159
	v_cvt_pk_bf16_f32 v143, v158, v159
	s_waitcnt lgkmcnt(8)
	v_mfma_f32_32x32x16_bf16 v[16:31], v[212:215], v[132:135], v[16:31]
	ds_read_b128 v[212:215], v204
	v_exp_f32_e32 v164, v164
	v_exp_f32_e32 v165, v165
	v_add_f32_e32 v163, v163, v164
	v_exp_f32_e32 v166, v166
	v_add_f32_e32 v163, v163, v165
	s_waitcnt lgkmcnt(8)
	v_mfma_f32_32x32x16_bf16 v[112:127], v[234:237], v[136:139], v[112:127]
	ds_read_b128 v[234:237], v204 offset:4096
	v_exp_f32_e32 v167, v167
	v_add_f32_e32 v163, v163, v166
	v_cvt_pk_bf16_f32 v164, v164, v165
	v_exp_f32_e32 v168, v168
	v_add_f32_e32 v163, v163, v167
	s_waitcnt lgkmcnt(8)
	v_mfma_f32_32x32x16_bf16 v[80:95], v[250:253], v[136:139], v[80:95]
	ds_read_b128 v[250:253], v204 offset:8192
	v_exp_f32_e32 v169, v169
	v_add_f32_e32 v163, v163, v168
	v_cvt_pk_bf16_f32 v165, v166, v167
	v_exp_f32_e32 v170, v170
	v_add_f32_e32 v163, v163, v169
	s_waitcnt lgkmcnt(8)
	v_mfma_f32_32x32x16_bf16 v[48:63], v[216:219], v[136:139], v[48:63]
	ds_read_b128 v[216:219], v204 offset:12288
	v_exp_f32_e32 v171, v171
	v_add_f32_e32 v163, v163, v170
	v_cvt_pk_bf16_f32 v166, v168, v169
	v_exp_f32_e32 v172, v172
	v_add_f32_e32 v163, v163, v171
	s_waitcnt lgkmcnt(8)
	v_mfma_f32_32x32x16_bf16 v[16:31], v[238:241], v[136:139], v[16:31]
	ds_read_b128 v[238:241], v205
	v_exp_f32_e32 v173, v173
	v_add_f32_e32 v163, v163, v172
	v_cvt_pk_bf16_f32 v167, v170, v171
	v_exp_f32_e32 v174, v174
	v_add_f32_e32 v163, v163, v173
	s_waitcnt lgkmcnt(8)
	v_mfma_f32_32x32x16_bf16 v[112:127], v[220:223], v[140:143], v[112:127]
	ds_read_b128 v[220:223], v205 offset:4096
	v_exp_f32_e32 v175, v175
	v_add_f32_e32 v163, v163, v174
	v_cvt_pk_bf16_f32 v168, v172, v173
	v_exp_f32_e32 v176, v176
	v_add_f32_e32 v163, v163, v175
	s_waitcnt lgkmcnt(8)
	v_mfma_f32_32x32x16_bf16 v[80:95], v[242:245], v[140:143], v[80:95]
	ds_read_b128 v[242:245], v205 offset:8192
	v_exp_f32_e32 v177, v177
	v_add_f32_e32 v163, v163, v176
	v_cvt_pk_bf16_f32 v169, v174, v175
	v_exp_f32_e32 v178, v178
	v_add_f32_e32 v163, v163, v177
	s_waitcnt lgkmcnt(8)
	v_mfma_f32_32x32x16_bf16 v[48:63], v[224:227], v[140:143], v[48:63]
	ds_read_b128 v[224:227], v205 offset:12288
	v_exp_f32_e32 v179, v179
	v_add_f32_e32 v163, v163, v178
	v_cvt_pk_bf16_f32 v170, v176, v177
	v_add_f32_e32 v163, v163, v179
	v_cvt_pk_bf16_f32 v171, v178, v179
	s_waitcnt lgkmcnt(8)
	v_mfma_f32_32x32x16_bf16 v[16:31], v[246:249], v[140:143], v[16:31]
	ds_read_b128 v[246:249], v206
	v_exp_f32_e32 v180, v180
	v_exp_f32_e32 v181, v181
	v_add_f32_e32 v163, v163, v180
	v_exp_f32_e32 v182, v182
	v_add_f32_e32 v163, v163, v181
	s_waitcnt lgkmcnt(8)
	v_mfma_f32_32x32x16_bf16 v[96:111], v[212:215], v[164:167], v[96:111]
	ds_read_b128 v[212:215], v206 offset:4096
	v_exp_f32_e32 v183, v183
	v_add_f32_e32 v163, v163, v182
	v_cvt_pk_bf16_f32 v172, v180, v181
	v_exp_f32_e32 v184, v184
	v_add_f32_e32 v163, v163, v183
	s_waitcnt lgkmcnt(8)
	v_mfma_f32_32x32x16_bf16 v[64:79], v[234:237], v[164:167], v[64:79]
	ds_read_b128 v[234:237], v206 offset:8192
	v_exp_f32_e32 v185, v185
	v_add_f32_e32 v163, v163, v184
	v_cvt_pk_bf16_f32 v173, v182, v183
	v_exp_f32_e32 v186, v186
	v_add_f32_e32 v163, v163, v185
	s_waitcnt lgkmcnt(8)
	v_mfma_f32_32x32x16_bf16 v[32:47], v[250:253], v[164:167], v[32:47]
	ds_read_b128 v[250:253], v206 offset:12288
	v_exp_f32_e32 v187, v187
	v_add_f32_e32 v163, v163, v186
	v_cvt_pk_bf16_f32 v174, v184, v185
	v_exp_f32_e32 v188, v188
	v_add_f32_e32 v163, v163, v187
	s_waitcnt lgkmcnt(8)
	v_mfma_f32_32x32x16_bf16 v[0:15], v[216:219], v[164:167], v[0:15]
	ds_read_b128 v[216:219], v207
	v_exp_f32_e32 v189, v189
	v_add_f32_e32 v163, v163, v188
	v_cvt_pk_bf16_f32 v175, v186, v187
	v_exp_f32_e32 v190, v190
	v_add_f32_e32 v163, v163, v189
	s_waitcnt lgkmcnt(8)
	v_mfma_f32_32x32x16_bf16 v[96:111], v[238:241], v[168:171], v[96:111]
	ds_read_b128 v[238:241], v207 offset:4096
	v_exp_f32_e32 v191, v191
	v_add_f32_e32 v163, v163, v190
	v_cvt_pk_bf16_f32 v176, v188, v189
	v_exp_f32_e32 v192, v192
	v_add_f32_e32 v163, v163, v191
	s_waitcnt lgkmcnt(8)
	v_mfma_f32_32x32x16_bf16 v[64:79], v[220:223], v[168:171], v[64:79]
	ds_read_b128 v[220:223], v207 offset:8192
	v_exp_f32_e32 v193, v193
	v_add_f32_e32 v163, v163, v192
	v_cvt_pk_bf16_f32 v177, v190, v191
	v_exp_f32_e32 v194, v194
	v_add_f32_e32 v163, v163, v193
	s_waitcnt lgkmcnt(8)
	v_mfma_f32_32x32x16_bf16 v[32:47], v[242:245], v[168:171], v[32:47]
	ds_read_b128 v[242:245], v207 offset:12288
	v_exp_f32_e32 v195, v195
	v_add_f32_e32 v163, v163, v194
	v_cvt_pk_bf16_f32 v178, v192, v193
	v_add_f32_e32 v163, v163, v195
	v_cvt_pk_bf16_f32 v179, v194, v195
	s_waitcnt lgkmcnt(8)
	v_mfma_f32_32x32x16_bf16 v[0:15], v[224:227], v[168:171], v[0:15]
	ds_read_b128 v[180:183], v228
	s_waitcnt lgkmcnt(8)
	v_mfma_f32_32x32x16_bf16 v[96:111], v[246:249], v[172:175], v[96:111]
	ds_read_b128 v[184:187], v228 offset:32
	s_waitcnt lgkmcnt(8)
	v_mfma_f32_32x32x16_bf16 v[64:79], v[212:215], v[172:175], v[64:79]
	ds_read_b128 v[188:191], v228 offset:64
	s_waitcnt lgkmcnt(8)
	v_mfma_f32_32x32x16_bf16 v[32:47], v[234:237], v[172:175], v[32:47]
	ds_read_b128 v[192:195], v228 offset:96
	s_waitcnt lgkmcnt(8)
	v_mfma_f32_32x32x16_bf16 v[0:15], v[250:253], v[172:175], v[0:15]
	s_waitcnt lgkmcnt(4)
	s_waitcnt vmcnt(0)
	s_barrier
; __device__ __forceinline__ void attn_phase_fast(LAS unsigned char* lds, const bf16_t* q, const bf16_t* k, const bf16_t* vT, bf16_t* mixed, float lam, const int wave_s) {
;     ...
;                 ATT_DMA(nb, Kg + (size_t)(t + 1) * 64 * 512, Vg + (t + 1) * 64);
;             }
;             const LAS unsigned char* Qs = lds + 2 * ABUF + wid * (32 * QROW) + r32 * QROW + hi * 16;
;             int kxh = (kx >> 1) << 5, vxh = (vx >> 1) << 5, kq = cb + r32 * KROW + ((hi ^ (kx & 1)) << 4), vq = cb + KBUF + r32 * VROW + ((hi ^ (vx & 1)) << 4);
;             asm volatile("" : "+v"(kxh), "+v"(vxh), "+v"(kq), "+v"(vq));
;             const LAS unsigned char* Kb = lds + kq;
;             const LAS unsigned char* Vb = lds + vq;
; #pragma unroll
;             for (int m = 0; m < 2; ++m) {
;                 f32x16 s0, s1;
; #pragma unroll
;                 for (int i = 0; i < 16; ++i) { s0[i] = 0.f; s1[i] = 0.f; }
; #pragma unroll
;                 for (int d0 = 0; d0 < 4; ++d0) {
;                     const int kpos = ((m * 4 + d0) << 5) ^ kxh;
;                     const bf16x8 k0 = *(const LAS bf16x8*)(Kb + kpos), k1 = *(const LAS bf16x8*)(Kb + 32 * KROW + kpos);
;                     const bf16x8 qv = *(const LAS bf16x8*)(Qs + m * 128 + d0 * 32);
;                     s0 = MFMA32(k0, qv, s0); s1 = MFMA32(k1, qv, s1);
;                 }
;                 __builtin_amdgcn_sched_barrier(0);
;                 float ls = 0.f, ls2 = 0.f;
; #pragma unroll
;                 for (int i = 0; i < 16; ++i) { float e0 = __builtin_amdgcn_exp2f(s0[i]), e1 = __builtin_amdgcn_exp2f(s1[i]); asm volatile("" : "+v"(e0), "+v"(e1)); s0[i] = e0; s1[i] = e1; ls += e0; ls2 += e1; }
;                 ls += ls2;
;                 l[m] += ls;
;                 const bf16x8 p0 = packp(s0, 0), p1 = packp(s0, 1), p2 = packp(s1, 0), p3 = packp(s1, 1);
; #pragma unroll
;                 for (int db = 0; db < 4; ++db) {
;                     const LAS unsigned char* vb = Vb + db * 32 * VROW;
;                     const bf16x8 v0 = *(const LAS bf16x8*)(vb + (0 ^ vxh)), v1 = *(const LAS bf16x8*)(vb + (32 ^ vxh)), v2 = *(const LAS bf16x8*)(vb + (64 ^ vxh)), v3 = *(const LAS bf16x8*)(vb + (96 ^ vxh));
;                     o[m][db] = MFMA32(v0, p0, o[m][db]); o[m][db] = MFMA32(v1, p1, o[m][db]); o[m][db] = MFMA32(v2, p2, o[m][db]); o[m][db] = MFMA32(v3, p3, o[m][db]);
	ds_read_b128 v[144:147], v196 offset:32768
	ds_read_b128 v[148:151], v197 offset:32768
	ds_read_b128 v[152:155], v198 offset:32768
	ds_read_b128 v[156:159], v199 offset:32768
	ds_read_b128 v[164:167], v196 offset:40960
	ds_read_b128 v[168:171], v197 offset:40960
	ds_read_b128 v[172:175], v198 offset:40960
	ds_read_b128 v[212:215], v199 offset:40960
	v_mfma_f32_32x32x16_bf16 v[96:111], v[216:219], v[176:179], v[96:111]
	v_mfma_f32_32x32x16_bf16 v[64:79], v[238:241], v[176:179], v[64:79]
	v_mfma_f32_32x32x16_bf16 v[32:47], v[220:223], v[176:179], v[32:47]
	v_mfma_f32_32x32x16_bf16 v[0:15], v[242:245], v[176:179], v[0:15]
	s_waitcnt lgkmcnt(7)
	v_mfma_f32_32x32x16_bf16 v[128:143], v[144:147], v[180:183], 0
	ds_read_b128 v[216:219], v228 offset:128
	s_waitcnt lgkmcnt(7)
	v_mfma_f32_32x32x16_bf16 v[128:143], v[148:151], v[184:187], v[128:143]
	ds_read_b128 v[220:223], v228 offset:160
	s_waitcnt lgkmcnt(7)
	v_mfma_f32_32x32x16_bf16 v[128:143], v[152:155], v[188:191], v[128:143]
	ds_read_b128 v[224:227], v228 offset:192
	s_waitcnt lgkmcnt(7)
	v_mfma_f32_32x32x16_bf16 v[128:143], v[156:159], v[192:195], v[128:143]
	ds_read_b128 v[234:237], v228 offset:224
	s_waitcnt lgkmcnt(7)
	v_mfma_f32_32x32x16_bf16 v[144:159], v[164:167], v[180:183], 0
	ds_read_b128 v[180:183], v200 offset:32768
	ds_read_b128 v[238:241], v200 offset:40960
	s_waitcnt lgkmcnt(8)
	v_mfma_f32_32x32x16_bf16 v[144:159], v[168:171], v[184:187], v[144:159]
	ds_read_b128 v[184:187], v201 offset:32768
	ds_read_b128 v[242:245], v201 offset:40960
	s_waitcnt lgkmcnt(9)
	v_mfma_f32_32x32x16_bf16 v[144:159], v[172:175], v[188:191], v[144:159]
	ds_read_b128 v[188:191], v202 offset:32768
	ds_read_b128 v[246:249], v202 offset:40960
	s_waitcnt lgkmcnt(10)
	v_mfma_f32_32x32x16_bf16 v[144:159], v[212:215], v[192:195], v[144:159]
	ds_read_b128 v[192:195], v203 offset:32768
	ds_read_b128 v[212:215], v203 offset:40960
	v_exp_f32_e32 v128, v128
	v_exp_f32_e32 v129, v129
	v_add_f32_e32 v162, v162, v128
	v_exp_f32_e32 v130, v130
	v_add_f32_e32 v162, v162, v129
	s_waitcnt lgkmcnt(7)
	v_mfma_f32_32x32x16_bf16 v[164:179], v[180:183], v[216:219], 0
	ds_read_b128 v[250:253], v204 offset:32768
	s_mov_b32 m0, s22
	s_nop 0
	global_load_lds_dwordx4 v208, s[6:7]
	v_exp_f32_e32 v131, v131
	v_add_f32_e32 v162, v162, v130
	v_cvt_pk_bf16_f32 v128, v128, v129
	v_exp_f32_e32 v132, v132
	v_add_f32_e32 v162, v162, v131
	s_waitcnt lgkmcnt(6)
	v_mfma_f32_32x32x16_bf16 v[164:179], v[184:187], v[220:223], v[164:179]
	s_mov_b32 m0, s24
	s_nop 0
	global_load_lds_dwordx4 v209, s[2:3]
	v_exp_f32_e32 v133, v133
	v_add_f32_e32 v162, v162, v132
	v_cvt_pk_bf16_f32 v129, v130, v131
	v_exp_f32_e32 v134, v134
	v_add_f32_e32 v162, v162, v133
	s_waitcnt lgkmcnt(4)
	v_mfma_f32_32x32x16_bf16 v[164:179], v[188:191], v[224:227], v[164:179]
	s_mov_b32 m0, s26
	s_nop 0
	global_load_lds_dwordx4 v210, s[6:7]
	v_exp_f32_e32 v135, v135
	v_add_f32_e32 v162, v162, v134
	v_cvt_pk_bf16_f32 v130, v132, v133
	v_exp_f32_e32 v136, v136
	v_add_f32_e32 v162, v162, v135
	s_waitcnt lgkmcnt(2)
	v_mfma_f32_32x32x16_bf16 v[164:179], v[192:195], v[234:237], v[164:179]
	s_mov_b32 m0, s27
	s_nop 0
	global_load_lds_dwordx4 v211, s[2:3]
	s_add_u32 s6, s6, 0x10000
	s_addc_u32 s7, s7, 0
	s_add_u32 s2, s2, 0x80
	s_addc_u32 s3, s3, 0
	v_exp_f32_e32 v137, v137
	v_add_f32_e32 v162, v162, v136
	v_cvt_pk_bf16_f32 v131, v134, v135
	v_exp_f32_e32 v138, v138
	v_add_f32_e32 v162, v162, v137
	v_mfma_f32_32x32x16_bf16 v[180:195], v[238:241], v[216:219], 0
	ds_read_b128 v[216:219], v204 offset:36864
	ds_read_b128 v[238:241], v204 offset:40960
	v_exp_f32_e32 v139, v139
	v_add_f32_e32 v162, v162, v138
	v_cvt_pk_bf16_f32 v132, v136, v137
	v_exp_f32_e32 v140, v140
	v_add_f32_e32 v162, v162, v139
	v_mfma_f32_32x32x16_bf16 v[180:195], v[242:245], v[220:223], v[180:195]
	ds_read_b128 v[220:223], v204 offset:45056
	ds_read_b128 v[242:245], v205 offset:32768
	v_exp_f32_e32 v141, v141
	v_add_f32_e32 v162, v162, v140
	v_cvt_pk_bf16_f32 v133, v138, v139
	v_exp_f32_e32 v142, v142
	v_add_f32_e32 v162, v162, v141
	v_mfma_f32_32x32x16_bf16 v[180:195], v[246:249], v[224:227], v[180:195]
	ds_read_b128 v[224:227], v205 offset:36864
	ds_read_b128 v[246:249], v205 offset:40960
	v_exp_f32_e32 v143, v143
	v_add_f32_e32 v162, v162, v142
	v_cvt_pk_bf16_f32 v134, v140, v141
	v_add_f32_e32 v162, v162, v143
	v_cvt_pk_bf16_f32 v135, v142, v143
	s_waitcnt lgkmcnt(7)
	v_mfma_f32_32x32x16_bf16 v[180:195], v[212:215], v[234:237], v[180:195]
	ds_read_b128 v[212:215], v205 offset:45056
	ds_read_b128 v[234:237], v206 offset:32768
	v_exp_f32_e32 v144, v144
	v_exp_f32_e32 v145, v145
	v_add_f32_e32 v162, v162, v144
	v_exp_f32_e32 v146, v146
	v_add_f32_e32 v162, v162, v145
	s_waitcnt lgkmcnt(8)
	v_mfma_f32_32x32x16_bf16 v[112:127], v[250:253], v[128:131], v[112:127]
	ds_read_b128 v[250:253], v206 offset:36864
	v_exp_f32_e32 v147, v147
	v_add_f32_e32 v162, v162, v146
	v_cvt_pk_bf16_f32 v136, v144, v145
	v_exp_f32_e32 v148, v148
	v_add_f32_e32 v162, v162, v147
	s_waitcnt lgkmcnt(8)
	v_mfma_f32_32x32x16_bf16 v[80:95], v[216:219], v[128:131], v[80:95]
	ds_read_b128 v[216:219], v206 offset:40960
	v_exp_f32_e32 v149, v149
	v_add_f32_e32 v162, v162, v148
	v_cvt_pk_bf16_f32 v137, v146, v147
	v_exp_f32_e32 v150, v150
	v_add_f32_e32 v162, v162, v149
	s_waitcnt lgkmcnt(8)
	v_mfma_f32_32x32x16_bf16 v[48:63], v[238:241], v[128:131], v[48:63]
	ds_read_b128 v[238:241], v206 offset:45056
	v_exp_f32_e32 v151, v151
	v_add_f32_e32 v162, v162, v150
	v_cvt_pk_bf16_f32 v138, v148, v149
	v_exp_f32_e32 v152, v152
	v_add_f32_e32 v162, v162, v151
	s_waitcnt lgkmcnt(8)
; #define LAS __attribute__((address_space(3)))
; #define MFMA32(a, b, c) __builtin_amdgcn_mfma_f32_32x32x16_bf16((a), (b), (c), 0, 0, 0)
; __device__ __forceinline__ void attn_phase_fast(LAS unsigned char* lds, const bf16_t* q, const bf16_t* k, const bf16_t* vT, bf16_t* mixed, float lam, const int wave_s) {
;     ...
; #pragma unroll
;                 for (int i = 0; i < 16; ++i) { float e0 = __builtin_amdgcn_exp2f(s0[i]), e1 = __builtin_amdgcn_exp2f(s1[i]); asm volatile("" : "+v"(e0), "+v"(e1)); s0[i] = e0; s1[i] = e1; ls += e0; ls2 += e1; }
;                 ls += ls2;
;                 l[m] += ls;
;                 const bf16x8 p0 = packp(s0, 0), p1 = packp(s0, 1), p2 = packp(s1, 0), p3 = packp(s1, 1);
; #pragma unroll
;                 for (int db = 0; db < 4; ++db) {
;                     const LAS unsigned char* vb = Vb + db * 32 * VROW;
;                     const bf16x8 v0 = *(const LAS bf16x8*)(vb + (0 ^ vxh)), v1 = *(const LAS bf16x8*)(vb + (32 ^ vxh)), v2 = *(const LAS bf16x8*)(vb + (64 ^ vxh)), v3 = *(const LAS bf16x8*)(vb + (96 ^ vxh));
;                     o[m][db] = MFMA32(v0, p0, o[m][db]); o[m][db] = MFMA32(v1, p1, o[m][db]); o[m][db] = MFMA32(v2, p2, o[m][db]); o[m][db] = MFMA32(v3, p3, o[m][db]);
;                     if (db == 1) __builtin_amdgcn_sched_barrier(0);
;                 }
;                 __builtin_amdgcn_sched_barrier(0);
;             }
;             asm volatile("s_waitcnt vmcnt(0)" ::: "memory");
;             __syncthreads();
	v_mfma_f32_32x32x16_bf16 v[16:31], v[220:223], v[128:131], v[16:31]
	ds_read_b128 v[220:223], v207 offset:32768
	v_exp_f32_e32 v153, v153
	v_add_f32_e32 v162, v162, v152
	v_cvt_pk_bf16_f32 v139, v150, v151
	v_exp_f32_e32 v154, v154
	v_add_f32_e32 v162, v162, v153
	s_waitcnt lgkmcnt(8)
	v_mfma_f32_32x32x16_bf16 v[112:127], v[242:245], v[132:135], v[112:127]
	ds_read_b128 v[242:245], v207 offset:36864
	v_exp_f32_e32 v155, v155
	v_add_f32_e32 v162, v162, v154
	v_cvt_pk_bf16_f32 v140, v152, v153
	v_exp_f32_e32 v156, v156
	v_add_f32_e32 v162, v162, v155
	s_waitcnt lgkmcnt(8)
	v_mfma_f32_32x32x16_bf16 v[80:95], v[224:227], v[132:135], v[80:95]
	ds_read_b128 v[224:227], v207 offset:40960
	v_exp_f32_e32 v157, v157
	v_add_f32_e32 v162, v162, v156
	v_cvt_pk_bf16_f32 v141, v154, v155
	v_exp_f32_e32 v158, v158
	v_add_f32_e32 v162, v162, v157
	s_waitcnt lgkmcnt(8)
	v_mfma_f32_32x32x16_bf16 v[48:63], v[246:249], v[132:135], v[48:63]
	ds_read_b128 v[246:249], v207 offset:45056
	v_exp_f32_e32 v159, v159
	v_add_f32_e32 v162, v162, v158
	v_cvt_pk_bf16_f32 v142, v156, v157
	v_add_f32_e32 v162, v162, v159
	v_cvt_pk_bf16_f32 v143, v158, v159
	s_waitcnt lgkmcnt(8)
	v_mfma_f32_32x32x16_bf16 v[16:31], v[212:215], v[132:135], v[16:31]
	ds_read_b128 v[212:215], v204 offset:32768
	v_exp_f32_e32 v164, v164
	v_exp_f32_e32 v165, v165
	v_add_f32_e32 v163, v163, v164
	v_exp_f32_e32 v166, v166
	v_add_f32_e32 v163, v163, v165
	s_waitcnt lgkmcnt(8)
	v_mfma_f32_32x32x16_bf16 v[112:127], v[234:237], v[136:139], v[112:127]
	ds_read_b128 v[234:237], v204 offset:36864
	v_exp_f32_e32 v167, v167
	v_add_f32_e32 v163, v163, v166
	v_cvt_pk_bf16_f32 v164, v164, v165
	v_exp_f32_e32 v168, v168
	v_add_f32_e32 v163, v163, v167
	s_waitcnt lgkmcnt(8)
	v_mfma_f32_32x32x16_bf16 v[80:95], v[250:253], v[136:139], v[80:95]
	ds_read_b128 v[250:253], v204 offset:40960
	v_exp_f32_e32 v169, v169
	v_add_f32_e32 v163, v163, v168
	v_cvt_pk_bf16_f32 v165, v166, v167
	v_exp_f32_e32 v170, v170
	v_add_f32_e32 v163, v163, v169
	s_waitcnt lgkmcnt(8)
	v_mfma_f32_32x32x16_bf16 v[48:63], v[216:219], v[136:139], v[48:63]
	ds_read_b128 v[216:219], v204 offset:45056
	v_exp_f32_e32 v171, v171
	v_add_f32_e32 v163, v163, v170
	v_cvt_pk_bf16_f32 v166, v168, v169
	v_exp_f32_e32 v172, v172
	v_add_f32_e32 v163, v163, v171
	s_waitcnt lgkmcnt(8)
	v_mfma_f32_32x32x16_bf16 v[16:31], v[238:241], v[136:139], v[16:31]
	ds_read_b128 v[238:241], v205 offset:32768
	v_exp_f32_e32 v173, v173
	v_add_f32_e32 v163, v163, v172
	v_cvt_pk_bf16_f32 v167, v170, v171
	v_exp_f32_e32 v174, v174
	v_add_f32_e32 v163, v163, v173
	s_waitcnt lgkmcnt(8)
	v_mfma_f32_32x32x16_bf16 v[112:127], v[220:223], v[140:143], v[112:127]
	ds_read_b128 v[220:223], v205 offset:36864
	v_exp_f32_e32 v175, v175
	v_add_f32_e32 v163, v163, v174
	v_cvt_pk_bf16_f32 v168, v172, v173
	v_exp_f32_e32 v176, v176
	v_add_f32_e32 v163, v163, v175
	s_waitcnt lgkmcnt(8)
	v_mfma_f32_32x32x16_bf16 v[80:95], v[242:245], v[140:143], v[80:95]
	ds_read_b128 v[242:245], v205 offset:40960
	v_exp_f32_e32 v177, v177
	v_add_f32_e32 v163, v163, v176
	v_cvt_pk_bf16_f32 v169, v174, v175
	v_exp_f32_e32 v178, v178
	v_add_f32_e32 v163, v163, v177
	s_waitcnt lgkmcnt(8)
	v_mfma_f32_32x32x16_bf16 v[48:63], v[224:227], v[140:143], v[48:63]
	ds_read_b128 v[224:227], v205 offset:45056
	v_exp_f32_e32 v179, v179
	v_add_f32_e32 v163, v163, v178
	v_cvt_pk_bf16_f32 v170, v176, v177
	v_add_f32_e32 v163, v163, v179
	v_cvt_pk_bf16_f32 v171, v178, v179
	s_waitcnt lgkmcnt(8)
	v_mfma_f32_32x32x16_bf16 v[16:31], v[246:249], v[140:143], v[16:31]
	ds_read_b128 v[246:249], v206 offset:32768
	v_exp_f32_e32 v180, v180
	v_exp_f32_e32 v181, v181
	v_add_f32_e32 v163, v163, v180
	v_exp_f32_e32 v182, v182
	v_add_f32_e32 v163, v163, v181
	s_waitcnt lgkmcnt(8)
	v_mfma_f32_32x32x16_bf16 v[96:111], v[212:215], v[164:167], v[96:111]
	ds_read_b128 v[212:215], v206 offset:36864
	v_exp_f32_e32 v183, v183
	v_add_f32_e32 v163, v163, v182
	v_cvt_pk_bf16_f32 v172, v180, v181
	v_exp_f32_e32 v184, v184
	v_add_f32_e32 v163, v163, v183
	s_waitcnt lgkmcnt(8)
	v_mfma_f32_32x32x16_bf16 v[64:79], v[234:237], v[164:167], v[64:79]
	ds_read_b128 v[234:237], v206 offset:40960
	v_exp_f32_e32 v185, v185
	v_add_f32_e32 v163, v163, v184
	v_cvt_pk_bf16_f32 v173, v182, v183
	v_exp_f32_e32 v186, v186
	v_add_f32_e32 v163, v163, v185
	s_waitcnt lgkmcnt(8)
	v_mfma_f32_32x32x16_bf16 v[32:47], v[250:253], v[164:167], v[32:47]
	ds_read_b128 v[250:253], v206 offset:45056
	v_exp_f32_e32 v187, v187
	v_add_f32_e32 v163, v163, v186
	v_cvt_pk_bf16_f32 v174, v184, v185
	v_exp_f32_e32 v188, v188
	v_add_f32_e32 v163, v163, v187
	s_waitcnt lgkmcnt(8)
	v_mfma_f32_32x32x16_bf16 v[0:15], v[216:219], v[164:167], v[0:15]
	ds_read_b128 v[216:219], v207 offset:32768
	v_exp_f32_e32 v189, v189
	v_add_f32_e32 v163, v163, v188
	v_cvt_pk_bf16_f32 v175, v186, v187
	v_exp_f32_e32 v190, v190
	v_add_f32_e32 v163, v163, v189
	s_waitcnt lgkmcnt(8)
	v_mfma_f32_32x32x16_bf16 v[96:111], v[238:241], v[168:171], v[96:111]
	ds_read_b128 v[238:241], v207 offset:36864
	v_exp_f32_e32 v191, v191
	v_add_f32_e32 v163, v163, v190
	v_cvt_pk_bf16_f32 v176, v188, v189
	v_exp_f32_e32 v192, v192
	v_add_f32_e32 v163, v163, v191
	s_waitcnt lgkmcnt(8)
	v_mfma_f32_32x32x16_bf16 v[64:79], v[220:223], v[168:171], v[64:79]
	ds_read_b128 v[220:223], v207 offset:40960
	v_exp_f32_e32 v193, v193
	v_add_f32_e32 v163, v163, v192
	v_cvt_pk_bf16_f32 v177, v190, v191
	v_exp_f32_e32 v194, v194
	v_add_f32_e32 v163, v163, v193
	s_waitcnt lgkmcnt(8)
	v_mfma_f32_32x32x16_bf16 v[32:47], v[242:245], v[168:171], v[32:47]
	ds_read_b128 v[242:245], v207 offset:45056
	v_exp_f32_e32 v195, v195
	v_add_f32_e32 v163, v163, v194
	v_cvt_pk_bf16_f32 v178, v192, v193
	v_add_f32_e32 v163, v163, v195
	v_cvt_pk_bf16_f32 v179, v194, v195
	s_waitcnt lgkmcnt(8)
	v_mfma_f32_32x32x16_bf16 v[0:15], v[224:227], v[168:171], v[0:15]
	ds_read_b128 v[180:183], v228
	s_waitcnt lgkmcnt(8)
	v_mfma_f32_32x32x16_bf16 v[96:111], v[246:249], v[172:175], v[96:111]
	ds_read_b128 v[184:187], v228 offset:32
	s_waitcnt lgkmcnt(8)
	v_mfma_f32_32x32x16_bf16 v[64:79], v[212:215], v[172:175], v[64:79]
	ds_read_b128 v[188:191], v228 offset:64
	s_waitcnt lgkmcnt(8)
	v_mfma_f32_32x32x16_bf16 v[32:47], v[234:237], v[172:175], v[32:47]
	ds_read_b128 v[192:195], v228 offset:96
	s_waitcnt lgkmcnt(8)
	v_mfma_f32_32x32x16_bf16 v[0:15], v[250:253], v[172:175], v[0:15]
	s_waitcnt lgkmcnt(4)
	s_waitcnt vmcnt(0)
	s_add_i32 s44, s44, 2
	s_cmp_gt_u32 s44, s45
	s_barrier
; #define LAS __attribute__((address_space(3)))
; #define MFMA32(a, b, c) __builtin_amdgcn_mfma_f32_32x32x16_bf16((a), (b), (c), 0, 0, 0)
; __device__ __forceinline__ void attn_phase_fast(LAS unsigned char* lds, const bf16_t* q, const bf16_t* k, const bf16_t* vT, bf16_t* mixed, float lam, const int wave_s) {
;     ...
;                     const LAS unsigned char* vb = Vb + db * 32 * VROW;
;                     const bf16x8 v0 = *(const LAS bf16x8*)(vb + (0 ^ vxh)), v1 = *(const LAS bf16x8*)(vb + (32 ^ vxh)), v2 = *(const LAS bf16x8*)(vb + (64 ^ vxh)), v3 = *(const LAS bf16x8*)(vb + (96 ^ vxh));
;                     o[m][db] = MFMA32(v0, p0, o[m][db]); o[m][db] = MFMA32(v1, p1, o[m][db]); o[m][db] = MFMA32(v2, p2, o[m][db]); o[m][db] = MFMA32(v3, p3, o[m][db]);
;     ...
;         const float l0 = l[0] + __shfl_xor(l[0], 32), l1 = l[1] + __shfl_xor(l[1], 32);
;         const float c0 = 1.0f / l0, c1 = lam / l1;
;         float ss = 0.f;
; #pragma unroll
;         for (int db = 0; db < 4; ++db)
; #pragma unroll
;             for (int i = 0; i < 16; ++i) { const float v = o[0][db][i] * c0 - o[1][db][i] * c1; o[0][db][i] = v; ss += v * v; }
	s_cbranch_scc0 .Lattn_tile_loop
	v_mfma_f32_32x32x16_bf16 v[96:111], v[216:219], v[176:179], v[96:111]
	v_mfma_f32_32x32x16_bf16 v[64:79], v[238:241], v[176:179], v[64:79]
	v_mfma_f32_32x32x16_bf16 v[32:47], v[220:223], v[176:179], v[32:47]
	v_mfma_f32_32x32x16_bf16 v[0:15], v[242:245], v[176:179], v[0:15]
	s_mov_b32 m0, s50
	s_waitcnt lgkmcnt(0)
	v_and_b32_e32 v129, 64, v231
	v_xor_b32_e32 v128, 32, v231
	v_add_u32_e32 v129, 64, v129
	v_cmp_lt_i32_e32 vcc, v128, v129
	s_nop 1
	v_cndmask_b32_e32 v128, v231, v128, vcc
	v_lshlrev_b32_e32 v130, 2, v128
	v_mov_b32_e32 v128, v162
	v_mov_b32_e32 v129, v163
	ds_bpermute_b32 v132, v130, v128
	ds_bpermute_b32 v133, v130, v129
	s_lshl_b32 s0, s0, 1
	s_add_i32 s43, s43, s82
	s_cmpk_gt_i32 s43, 0x7ff
	s_waitcnt lgkmcnt(0)
	v_pk_add_f32 v[128:129], v[128:129], v[132:133]
	s_nop 0
	v_div_scale_f32 v131, s[2:3], v129, v129, v229
	v_rcp_f32_e32 v132, v131
	s_nop 0
	v_fma_f32 v133, -v131, v132, 1.0
	v_fmac_f32_e32 v132, v133, v132
	v_div_scale_f32 v133, vcc, v229, v129, v229
	v_mul_f32_e32 v134, v133, v132
	v_fma_f32 v135, -v131, v134, v133
	v_fmac_f32_e32 v134, v135, v132
	v_fma_f32 v131, -v131, v134, v133
	v_div_scale_f32 v133, s[2:3], v128, v128, 1.0
	v_rcp_f32_e32 v135, v133
	v_div_fmas_f32 v131, v131, v132, v134
	v_div_fixup_f32 v129, v131, v129, v229
	v_fma_f32 v131, -v133, v135, 1.0
	v_fmac_f32_e32 v135, v131, v135
	v_div_scale_f32 v131, vcc, 1.0, v128, 1.0
	v_mul_f32_e32 v132, v131, v135
	v_fma_f32 v134, -v133, v132, v131
	v_fmac_f32_e32 v132, v134, v135
	v_fma_f32 v131, -v133, v132, v131
	v_div_fmas_f32 v131, v131, v135, v132
	v_div_fixup_f32 v128, v131, v128, 1.0
	v_mov_b32_e32 v133, v96
	v_mov_b32_e32 v96, v113
	v_pk_mul_f32 v[96:97], v[96:97], v[128:129]
	v_mov_b32_e32 v132, v112
	v_sub_f32_e32 v113, v96, v97
	v_mov_b32_e32 v96, v114
	v_mov_b32_e32 v97, v98
	v_pk_mul_f32 v[96:97], v[96:97], v[128:129]
	v_mov_b32_e32 v98, v115
	v_sub_f32_e32 v114, v96, v97
	v_pk_mul_f32 v[96:97], v[98:99], v[128:129]
	v_pk_mul_f32 v[132:133], v[132:133], v[128:129]
	v_sub_f32_e32 v98, v96, v97
	v_mov_b32_e32 v96, v116
	v_mov_b32_e32 v97, v100
	v_pk_mul_f32 v[96:97], v[96:97], v[128:129]
	v_mov_b32_e32 v100, v117
	v_sub_f32_e32 v99, v96, v97
	v_pk_mul_f32 v[96:97], v[100:101], v[128:129]
	v_sub_f32_e32 v112, v132, v133
	v_sub_f32_e32 v100, v96, v97
	v_mov_b32_e32 v96, v118
	v_mov_b32_e32 v97, v102
	v_pk_mul_f32 v[96:97], v[96:97], v[128:129]
	v_mov_b32_e32 v102, v119
	v_sub_f32_e32 v101, v96, v97
	v_pk_mul_f32 v[96:97], v[102:103], v[128:129]
	s_nop 0
	v_sub_f32_e32 v102, v96, v97
	v_mov_b32_e32 v96, v120
	v_mov_b32_e32 v97, v104
	v_pk_mul_f32 v[96:97], v[96:97], v[128:129]
	v_mov_b32_e32 v104, v121
	v_sub_f32_e32 v103, v96, v97
	v_pk_mul_f32 v[96:97], v[104:105], v[128:129]
	s_nop 0
	v_sub_f32_e32 v104, v96, v97
	v_mov_b32_e32 v96, v122
	v_mov_b32_e32 v97, v106
	v_pk_mul_f32 v[96:97], v[96:97], v[128:129]
	v_mov_b32_e32 v106, v123
	v_sub_f32_e32 v105, v96, v97
	v_pk_mul_f32 v[96:97], v[106:107], v[128:129]
	s_nop 0
	v_sub_f32_e32 v106, v96, v97
	v_mov_b32_e32 v96, v124
	v_mov_b32_e32 v97, v108
	v_pk_mul_f32 v[96:97], v[96:97], v[128:129]
	v_mov_b32_e32 v108, v125
	v_sub_f32_e32 v107, v96, v97
	v_pk_mul_f32 v[96:97], v[108:109], v[128:129]
	s_nop 0
	v_sub_f32_e32 v108, v96, v97
	v_mov_b32_e32 v96, v126
	v_mov_b32_e32 v97, v110
	v_pk_mul_f32 v[96:97], v[96:97], v[128:129]
	v_mov_b32_e32 v110, v127
	v_sub_f32_e32 v109, v96, v97
	v_pk_mul_f32 v[96:97], v[110:111], v[128:129]
	s_nop 0
	v_sub_f32_e32 v110, v96, v97
	v_mov_b32_e32 v97, v64
	v_mov_b32_e32 v64, v81
	v_pk_mul_f32 v[64:65], v[64:65], v[128:129]
	v_mov_b32_e32 v96, v80
	v_sub_f32_e32 v81, v64, v65
	v_mov_b32_e32 v64, v82
	v_mov_b32_e32 v65, v66
	v_pk_mul_f32 v[64:65], v[64:65], v[128:129]
	v_mov_b32_e32 v66, v83
	v_sub_f32_e32 v82, v64, v65
	v_pk_mul_f32 v[64:65], v[66:67], v[128:129]
	v_pk_mul_f32 v[96:97], v[96:97], v[128:129]
	v_sub_f32_e32 v66, v64, v65
	v_mov_b32_e32 v64, v84
	v_mov_b32_e32 v65, v68
	v_pk_mul_f32 v[64:65], v[64:65], v[128:129]
	v_mov_b32_e32 v68, v85
	v_sub_f32_e32 v67, v64, v65
	v_pk_mul_f32 v[64:65], v[68:69], v[128:129]
	v_sub_f32_e32 v80, v96, v97
	v_sub_f32_e32 v68, v64, v65
	v_mov_b32_e32 v64, v86
	v_mov_b32_e32 v65, v70
	v_pk_mul_f32 v[64:65], v[64:65], v[128:129]
	v_mov_b32_e32 v70, v87
	v_sub_f32_e32 v69, v64, v65
	v_pk_mul_f32 v[64:65], v[70:71], v[128:129]
	s_nop 0
	v_sub_f32_e32 v70, v64, v65
	v_mov_b32_e32 v64, v88
	v_mov_b32_e32 v65, v72
	v_pk_mul_f32 v[64:65], v[64:65], v[128:129]
	v_mov_b32_e32 v72, v89
	v_sub_f32_e32 v71, v64, v65
	v_pk_mul_f32 v[64:65], v[72:73], v[128:129]
	s_nop 0
	v_sub_f32_e32 v72, v64, v65
	v_mov_b32_e32 v64, v90
	v_mov_b32_e32 v65, v74
	v_pk_mul_f32 v[64:65], v[64:65], v[128:129]
	v_mov_b32_e32 v74, v91
	v_sub_f32_e32 v73, v64, v65
	v_pk_mul_f32 v[64:65], v[74:75], v[128:129]
	s_nop 0
	v_sub_f32_e32 v74, v64, v65
	v_mov_b32_e32 v64, v92
	v_mov_b32_e32 v65, v76
	v_pk_mul_f32 v[64:65], v[64:65], v[128:129]
	v_mov_b32_e32 v76, v93
	v_sub_f32_e32 v75, v64, v65
	v_pk_mul_f32 v[64:65], v[76:77], v[128:129]
	s_nop 0
	v_sub_f32_e32 v76, v64, v65
	v_mov_b32_e32 v64, v94
	v_mov_b32_e32 v65, v78
	v_pk_mul_f32 v[64:65], v[64:65], v[128:129]
	v_mov_b32_e32 v78, v95
	v_sub_f32_e32 v77, v64, v65
	v_pk_mul_f32 v[64:65], v[78:79], v[128:129]
	s_nop 0
	v_sub_f32_e32 v78, v64, v65
	v_mov_b32_e32 v65, v32
	v_mov_b32_e32 v32, v49
	v_pk_mul_f32 v[32:33], v[32:33], v[128:129]
	v_mov_b32_e32 v64, v48
	v_sub_f32_e32 v49, v32, v33
	v_mov_b32_e32 v32, v50
	v_mov_b32_e32 v33, v34
	v_pk_mul_f32 v[32:33], v[32:33], v[128:129]
	v_mov_b32_e32 v34, v51
	v_sub_f32_e32 v50, v32, v33
	v_pk_mul_f32 v[32:33], v[34:35], v[128:129]
; __device__ __forceinline__ void attn_phase_fast(LAS unsigned char* lds, const bf16_t* q, const bf16_t* k, const bf16_t* vT, bf16_t* mixed, float lam, const int wave_s) {
;     ...
;         for (int db = 0; db < 4; ++db)
; #pragma unroll
;             for (int i = 0; i < 16; ++i) { const float v = o[0][db][i] * c0 - o[1][db][i] * c1; o[0][db][i] = v; ss += v * v; }
;         ss += __shfl_xor(ss, 32);
;         const float rstd = rsqrtf(ss * (1.0f / 128.0f) + EPSV);
	v_pk_mul_f32 v[64:65], v[64:65], v[128:129]
	v_sub_f32_e32 v34, v32, v33
	v_mov_b32_e32 v32, v52
	v_mov_b32_e32 v33, v36
	v_pk_mul_f32 v[32:33], v[32:33], v[128:129]
	v_mov_b32_e32 v36, v53
	v_sub_f32_e32 v35, v32, v33
	v_pk_mul_f32 v[32:33], v[36:37], v[128:129]
	v_sub_f32_e32 v48, v64, v65
	v_sub_f32_e32 v36, v32, v33
	v_mov_b32_e32 v32, v54
	v_mov_b32_e32 v33, v38
	v_pk_mul_f32 v[32:33], v[32:33], v[128:129]
	v_mov_b32_e32 v38, v55
	v_sub_f32_e32 v37, v32, v33
	v_pk_mul_f32 v[32:33], v[38:39], v[128:129]
	s_nop 0
	v_sub_f32_e32 v38, v32, v33
	v_mov_b32_e32 v32, v56
	v_mov_b32_e32 v33, v40
	v_pk_mul_f32 v[32:33], v[32:33], v[128:129]
	v_mov_b32_e32 v40, v57
	v_sub_f32_e32 v39, v32, v33
	v_pk_mul_f32 v[32:33], v[40:41], v[128:129]
	s_nop 0
	v_sub_f32_e32 v40, v32, v33
	v_mov_b32_e32 v32, v58
	v_mov_b32_e32 v33, v42
	v_pk_mul_f32 v[32:33], v[32:33], v[128:129]
	v_mov_b32_e32 v42, v59
	v_sub_f32_e32 v41, v32, v33
	v_pk_mul_f32 v[32:33], v[42:43], v[128:129]
	s_nop 0
	v_sub_f32_e32 v42, v32, v33
	v_mov_b32_e32 v32, v60
	v_mov_b32_e32 v33, v44
	v_pk_mul_f32 v[32:33], v[32:33], v[128:129]
	v_mov_b32_e32 v44, v61
	v_sub_f32_e32 v43, v32, v33
	v_pk_mul_f32 v[32:33], v[44:45], v[128:129]
	s_nop 0
	v_sub_f32_e32 v44, v32, v33
	v_mov_b32_e32 v32, v62
	v_mov_b32_e32 v33, v46
	v_pk_mul_f32 v[32:33], v[32:33], v[128:129]
	v_mov_b32_e32 v46, v63
	v_sub_f32_e32 v45, v32, v33
	v_pk_mul_f32 v[32:33], v[46:47], v[128:129]
	s_nop 0
	v_sub_f32_e32 v46, v32, v33
	v_mov_b32_e32 v32, v16
	v_mov_b32_e32 v33, v0
	v_mov_b32_e32 v0, v17
	v_pk_mul_f32 v[32:33], v[32:33], v[128:129]
	v_pk_mul_f32 v[0:1], v[0:1], v[128:129]
	v_sub_f32_e32 v32, v32, v33
	v_sub_f32_e32 v33, v0, v1
	v_mov_b32_e32 v0, v18
	v_mov_b32_e32 v1, v2
	v_pk_mul_f32 v[0:1], v[0:1], v[128:129]
	v_mov_b32_e32 v2, v19
	v_sub_f32_e32 v47, v0, v1
	v_pk_mul_f32 v[0:1], v[2:3], v[128:129]
	s_nop 0
	v_sub_f32_e32 v51, v0, v1
	v_mov_b32_e32 v0, v20
	v_mov_b32_e32 v1, v4
	v_pk_mul_f32 v[0:1], v[0:1], v[128:129]
	v_mov_b32_e32 v4, v21
	v_sub_f32_e32 v20, v0, v1
	v_pk_mul_f32 v[0:1], v[4:5], v[128:129]
	s_nop 0
	v_sub_f32_e32 v21, v0, v1
	v_mov_b32_e32 v0, v22
	v_mul_f32_e32 v22, v112, v112
	v_fmac_f32_e32 v22, v113, v113
	v_fmac_f32_e32 v22, v114, v114
	v_fmac_f32_e32 v22, v98, v98
	v_fmac_f32_e32 v22, v99, v99
	v_fmac_f32_e32 v22, v100, v100
	v_fmac_f32_e32 v22, v101, v101
	v_fmac_f32_e32 v22, v102, v102
	v_fmac_f32_e32 v22, v103, v103
	v_fmac_f32_e32 v22, v104, v104
	v_fmac_f32_e32 v22, v105, v105
	v_fmac_f32_e32 v22, v106, v106
	v_fmac_f32_e32 v22, v107, v107
	v_fmac_f32_e32 v22, v108, v108
	v_fmac_f32_e32 v22, v109, v109
	v_fmac_f32_e32 v22, v110, v110
	v_fmac_f32_e32 v22, v80, v80
	v_fmac_f32_e32 v22, v81, v81
	v_fmac_f32_e32 v22, v82, v82
	v_fmac_f32_e32 v22, v66, v66
	v_fmac_f32_e32 v22, v67, v67
	v_fmac_f32_e32 v22, v68, v68
	v_fmac_f32_e32 v22, v69, v69
	v_fmac_f32_e32 v22, v70, v70
	v_fmac_f32_e32 v22, v71, v71
	v_fmac_f32_e32 v22, v72, v72
	v_fmac_f32_e32 v22, v73, v73
	v_fmac_f32_e32 v22, v74, v74
	v_fmac_f32_e32 v22, v75, v75
	v_fmac_f32_e32 v22, v76, v76
	v_fmac_f32_e32 v22, v77, v77
	v_fmac_f32_e32 v22, v78, v78
	v_fmac_f32_e32 v22, v48, v48
	v_fmac_f32_e32 v22, v49, v49
	v_fmac_f32_e32 v22, v50, v50
	v_fmac_f32_e32 v22, v34, v34
	v_fmac_f32_e32 v22, v35, v35
	v_fmac_f32_e32 v22, v36, v36
	v_fmac_f32_e32 v22, v37, v37
	v_fmac_f32_e32 v22, v38, v38
	v_fmac_f32_e32 v22, v39, v39
	v_fmac_f32_e32 v22, v40, v40
	v_fmac_f32_e32 v22, v41, v41
	v_fmac_f32_e32 v22, v42, v42
	v_fmac_f32_e32 v22, v43, v43
	v_fmac_f32_e32 v22, v44, v44
	v_fmac_f32_e32 v22, v45, v45
	v_fmac_f32_e32 v22, v46, v46
	v_fmac_f32_e32 v22, v32, v32
	v_mov_b32_e32 v1, v6
	v_mov_b32_e32 v6, v23
	v_fmac_f32_e32 v22, v33, v33
	v_pk_mul_f32 v[0:1], v[0:1], v[128:129]
	v_pk_mul_f32 v[2:3], v[6:7], v[128:129]
	v_fmac_f32_e32 v22, v47, v47
	v_mov_b32_e32 v4, v2
	v_mov_b32_e32 v5, v0
	v_mov_b32_e32 v0, v3
	v_mov_b32_e32 v2, v24
	v_mov_b32_e32 v3, v8
	v_mov_b32_e32 v8, v25
	v_fmac_f32_e32 v22, v51, v51
	v_pk_add_f32 v[0:1], v[4:5], v[0:1] neg_lo:[0,1] neg_hi:[0,1]
	v_pk_mul_f32 v[2:3], v[2:3], v[128:129]
	v_pk_mul_f32 v[4:5], v[8:9], v[128:129]
	v_fmac_f32_e32 v22, v20, v20
	v_pk_mul_f32 v[16:17], v[0:1], v[0:1]
	v_mov_b32_e32 v6, v4
	v_mov_b32_e32 v7, v2
	v_mov_b32_e32 v2, v5
	v_mov_b32_e32 v4, v26
	v_mov_b32_e32 v5, v10
	v_mov_b32_e32 v10, v27
	v_fmac_f32_e32 v22, v21, v21
	v_pk_add_f32 v[2:3], v[6:7], v[2:3] neg_lo:[0,1] neg_hi:[0,1]
	v_pk_mul_f32 v[4:5], v[4:5], v[128:129]
	v_pk_mul_f32 v[6:7], v[10:11], v[128:129]
	v_add_f32_e32 v17, v17, v22
	v_pk_mul_f32 v[18:19], v[2:3], v[2:3]
	v_mov_b32_e32 v8, v6
	v_mov_b32_e32 v9, v4
	v_mov_b32_e32 v4, v7
	v_add_f32_e32 v16, v16, v17
	v_pk_add_f32 v[4:5], v[8:9], v[4:5] neg_lo:[0,1] neg_hi:[0,1]
	v_mov_b32_e32 v8, v129
	v_add_f32_e32 v16, v19, v16
	v_pk_mul_f32 v[10:11], v[4:5], v[4:5]
	v_pk_mul_f32 v[6:7], v[12:13], v[8:9] op_sel_hi:[1,0]
	v_add_f32_e32 v16, v18, v16
	v_pk_fma_f32 v[6:7], v[28:29], v[128:129], v[6:7] op_sel_hi:[1,0,1] neg_lo:[0,0,1] neg_hi:[0,0,1]
	v_add_f32_e32 v11, v11, v16
	v_pk_mul_f32 v[12:13], v[6:7], v[6:7]
	v_pk_mul_f32 v[8:9], v[14:15], v[8:9] op_sel_hi:[1,0]
	v_add_f32_e32 v10, v10, v11
	v_pk_fma_f32 v[8:9], v[30:31], v[128:129], v[8:9] op_sel_hi:[1,0,1] neg_lo:[0,0,1] neg_hi:[0,0,1]
	v_add_f32_e32 v10, v12, v10
	v_pk_mul_f32 v[14:15], v[8:9], v[8:9]
	v_add_f32_e32 v10, v13, v10
	v_add_f32_e32 v10, v14, v10
	v_add_f32_e32 v10, v15, v10
	ds_bpermute_b32 v11, v130, v10
	v_mbcnt_lo_u32_b32 v12, -1, 0
	v_mbcnt_hi_u32_b32 v12, -1, v12
	s_waitcnt lgkmcnt(0)
; __device__ __forceinline__ unsigned cvt_pk_bf16(float lo, float hi) { unsigned r; asm volatile("v_cvt_pk_bf16_f32 %0, %1, %2" : "=v"(r) : "v"(lo), "v"(hi)); return r; }
; __device__ __forceinline__ int lane_id() { int l; asm volatile("v_mbcnt_lo_u32_b32 %0, -1, 0\n\tv_mbcnt_hi_u32_b32 %0, -1, %0" : "=v"(l)); return l; }
; __device__ __forceinline__ void attn_phase_fast(LAS unsigned char* lds, const bf16_t* q, const bf16_t* k, const bf16_t* vT, bf16_t* mixed, float lam, const int wave_s) {
;     ...
;         ss += __shfl_xor(ss, 32);
;         const float rstd = rsqrtf(ss * (1.0f / 128.0f) + EPSV);
;         int lane2 = lane_id(); asm volatile("" : "+v"(lane2));
;         bf16_t* orow = mixed + ((size_t)tok0 + qb * 256 + wid * 32 + (lane2 & 31)) * DM + h * 128 + 4 * (lane2 >> 5);
; #pragma unroll
;         for (int db = 0; db < 4; ++db)
; #pragma unroll
;             for (int i4 = 0; i4 < 4; ++i4) {
;                 u32x2 w; w.x = cvt_pk_bf16(o[0][db][4 * i4] * rstd, o[0][db][4 * i4 + 1] * rstd); w.y = cvt_pk_bf16(o[0][db][4 * i4 + 2] * rstd, o[0][db][4 * i4 + 3] * rstd);
;                 *(u32x2*)(orow + 32 * db + 8 * i4) = w;
;             }
	v_add_f32_e32 v10, v10, v11
	v_fmamk_f32 v10, v10, 0x3c000000, v232
	v_mul_f32_e32 v11, 0x4b800000, v10
	v_cmp_gt_f32_e32 vcc, s42, v10
	s_nop 0
	v_and_b32_e32 v160, 31, v12
	v_cndmask_b32_e32 v10, v10, v11, vcc
	v_rsq_f32_e32 v10, v10
	v_ashrrev_i32_e32 v12, 3, v12
	v_and_b32_e32 v12, -4, v12
	v_ashrrev_i32_e32 v13, 31, v12
	v_mul_f32_e32 v11, 0x45800000, v10
	v_cndmask_b32_e32 v14, v10, v11, vcc
	v_lshl_add_u64 v[10:11], s[4:5], 0, v[160:161]
	v_lshlrev_b64 v[10:11], 11, v[10:11]
	v_lshl_add_u64 v[10:11], s[20:21], 0, v[10:11]
	v_lshl_add_u64 v[10:11], v[10:11], 0, s[0:1]
	v_lshl_add_u64 v[10:11], v[12:13], 1, v[10:11]
	v_mul_f32_e32 v12, v112, v14
	v_mul_f32_e32 v13, v113, v14
	v_cvt_pk_bf16_f32 v12, v12, v13
	v_mul_f32_e32 v13, v114, v14
	v_mul_f32_e32 v15, v98, v14
	v_cvt_pk_bf16_f32 v13, v13, v15
	global_store_dwordx2 v[10:11], v[12:13], off
	v_mul_f32_e32 v12, v99, v14
	v_mul_f32_e32 v13, v100, v14
	v_cvt_pk_bf16_f32 v12, v12, v13
	v_mul_f32_e32 v13, v101, v14
	v_mul_f32_e32 v15, v102, v14
	v_cvt_pk_bf16_f32 v13, v13, v15
	global_store_dwordx2 v[10:11], v[12:13], off offset:16
	v_mul_f32_e32 v12, v103, v14
	v_mul_f32_e32 v13, v104, v14
	v_cvt_pk_bf16_f32 v12, v12, v13
	v_mul_f32_e32 v13, v105, v14
	v_mul_f32_e32 v15, v106, v14
	v_cvt_pk_bf16_f32 v13, v13, v15
	global_store_dwordx2 v[10:11], v[12:13], off offset:32
	v_mul_f32_e32 v12, v107, v14
	v_mul_f32_e32 v13, v108, v14
	v_cvt_pk_bf16_f32 v12, v12, v13
	v_mul_f32_e32 v13, v109, v14
	v_mul_f32_e32 v15, v110, v14
	v_cvt_pk_bf16_f32 v13, v13, v15
	global_store_dwordx2 v[10:11], v[12:13], off offset:48
	v_mul_f32_e32 v12, v80, v14
	v_mul_f32_e32 v13, v81, v14
	v_cvt_pk_bf16_f32 v12, v12, v13
	v_mul_f32_e32 v13, v82, v14
	v_mul_f32_e32 v15, v66, v14
	v_cvt_pk_bf16_f32 v13, v13, v15
	global_store_dwordx2 v[10:11], v[12:13], off offset:64
	v_mul_f32_e32 v12, v67, v14
	v_mul_f32_e32 v13, v68, v14
	v_cvt_pk_bf16_f32 v12, v12, v13
	v_mul_f32_e32 v13, v69, v14
	v_mul_f32_e32 v15, v70, v14
	v_cvt_pk_bf16_f32 v13, v13, v15
	global_store_dwordx2 v[10:11], v[12:13], off offset:80
	v_mul_f32_e32 v12, v71, v14
	v_mul_f32_e32 v13, v72, v14
	v_cvt_pk_bf16_f32 v12, v12, v13
	v_mul_f32_e32 v13, v73, v14
	v_mul_f32_e32 v15, v74, v14
	v_cvt_pk_bf16_f32 v13, v13, v15
	global_store_dwordx2 v[10:11], v[12:13], off offset:96
	v_mul_f32_e32 v12, v75, v14
	v_mul_f32_e32 v13, v76, v14
	v_cvt_pk_bf16_f32 v12, v12, v13
	v_mul_f32_e32 v13, v77, v14
	v_mul_f32_e32 v15, v78, v14
	v_cvt_pk_bf16_f32 v13, v13, v15
	global_store_dwordx2 v[10:11], v[12:13], off offset:112
	v_mul_f32_e32 v12, v48, v14
	v_mul_f32_e32 v13, v49, v14
	v_cvt_pk_bf16_f32 v12, v12, v13
	v_mul_f32_e32 v13, v50, v14
	v_mul_f32_e32 v15, v34, v14
	v_cvt_pk_bf16_f32 v13, v13, v15
	global_store_dwordx2 v[10:11], v[12:13], off offset:128
	v_mul_f32_e32 v12, v35, v14
	v_mul_f32_e32 v13, v36, v14
	v_cvt_pk_bf16_f32 v12, v12, v13
	v_mul_f32_e32 v13, v37, v14
	v_mul_f32_e32 v15, v38, v14
	v_cvt_pk_bf16_f32 v13, v13, v15
	global_store_dwordx2 v[10:11], v[12:13], off offset:144
	v_mul_f32_e32 v12, v39, v14
	v_mul_f32_e32 v13, v40, v14
	v_cvt_pk_bf16_f32 v12, v12, v13
	v_mul_f32_e32 v13, v41, v14
	v_mul_f32_e32 v15, v42, v14
	v_cvt_pk_bf16_f32 v13, v13, v15
	global_store_dwordx2 v[10:11], v[12:13], off offset:160
	v_mul_f32_e32 v12, v43, v14
	v_mul_f32_e32 v13, v44, v14
	v_cvt_pk_bf16_f32 v12, v12, v13
	v_mul_f32_e32 v13, v45, v14
	v_mul_f32_e32 v15, v46, v14
	v_cvt_pk_bf16_f32 v13, v13, v15
	global_store_dwordx2 v[10:11], v[12:13], off offset:176
	v_mul_f32_e32 v12, v32, v14
	v_mul_f32_e32 v13, v33, v14
	v_cvt_pk_bf16_f32 v12, v12, v13
	v_mul_f32_e32 v13, v47, v14
	v_mul_f32_e32 v15, v51, v14
	v_cvt_pk_bf16_f32 v13, v13, v15
	global_store_dwordx2 v[10:11], v[12:13], off offset:192
	v_mul_f32_e32 v12, v20, v14
	v_mul_f32_e32 v13, v21, v14
	v_mul_f32_e32 v1, v1, v14
	v_mul_f32_e32 v0, v0, v14
	v_cvt_pk_bf16_f32 v12, v12, v13
	v_cvt_pk_bf16_f32 v13, v1, v0
	v_mul_f32_e32 v0, v3, v14
	v_mul_f32_e32 v1, v2, v14
	global_store_dwordx2 v[10:11], v[12:13], off offset:208
	v_cvt_pk_bf16_f32 v0, v0, v1
	v_mul_f32_e32 v1, v5, v14
	v_mul_f32_e32 v2, v4, v14
	v_cvt_pk_bf16_f32 v1, v1, v2
	global_store_dwordx2 v[10:11], v[0:1], off offset:224
	v_mul_f32_e32 v0, v6, v14
	v_mul_f32_e32 v1, v7, v14
	v_cvt_pk_bf16_f32 v0, v0, v1
	v_mul_f32_e32 v1, v8, v14
	v_mul_f32_e32 v2, v9, v14
	v_cvt_pk_bf16_f32 v1, v1, v2
	global_store_dwordx2 v[10:11], v[0:1], off offset:240
	s_cbranch_scc0 .LBB0_390

; __device__ __forceinline__ u32x2 pack4(f32x4 a) { u32x2 w; w.x = cvt_pk_bf16(a[0], a[1]); w.y = cvt_pk_bf16(a[2], a[3]); return w; }
; __device__ __forceinline__ float dpp_ror1(float v) { return __builtin_bit_cast(float, __builtin_amdgcn_update_dpp(0, __builtin_bit_cast(int, v), 0x121, 0xf, 0xf, false)); }
; __device__ __forceinline__ float dpp_ror15(float v) { return __builtin_bit_cast(float, __builtin_amdgcn_update_dpp(0, __builtin_bit_cast(int, v), 0x12F, 0xf, 0xf, false)); }
;     template <bool BND> __device__ __forceinline__ void conv_gate(f32x4 (&acc)[2][2][4][2], const Unit& u, int wr, int wc, int fr, int fq, int tok0, int pcol) const {
;     ...
;                 for (int m = 0; m < 4; ++m) {
;                     const int r = ai * 128 + wr * 64 + m * 16 + fr, tok = tok0 + r;
;                     bool isfirst = false, islast = false;
;                     if (BND) { const int S1 = (tok < NPROMPT ? SEQP : SEQS) - 1, pos = tok & S1; isfirst = pos == 0; islast = pos == S1; }
;                     f32x4 cv[2];
; #pragma unroll
;                     for (int bj = 0; bj < 2; ++bj) {
;                         const f32x4 cur = acc[ai][bj][m][n];
;                         const f32x4 ups = m > 0 ? acc[ai][bj][m > 0 ? m - 1 : 0][n] : pe[bj];
;                         const f32x4 dns = m < 3 ? acc[ai][bj][m < 3 ? m + 1 : 3][n] : ne[bj];
;                         f32x4 prev, next;
; #pragma unroll
;                         for (int j = 0; j < 4; ++j) {
;                             const float t1 = fr == 15 ? ups[j] : cur[j]; float pv = dpp_ror1(t1);
;                             const float t2 = fr == 0 ? dns[j] : cur[j]; float nx = dpp_ror15(t2);
;                             if (BND) { prev[j] = isfirst ? 0.f : pv; next[j] = islast ? 0.f : nx; } else { prev[j] = pv; next[j] = nx; }
;                         }
;                         cv[bj] = w0[bj] * prev + w1[bj] * cur + w2[bj] * next + bb[bj];
;                     }
;                     f32x4 a;
; #pragma unroll
;                     for (int j = 0; j < 4; ++j) { const float g = cv[0][j]; const float sg = __builtin_amdgcn_rcpf(1.0f + __builtin_amdgcn_exp2f(-1.4426950408889634f * g)); a[j] = g * sg * cv[1][j]; }
;                     if (r >= 1 && r <= 254 && (!BND || tok < MTOK)) *(u32x2*)(act + (size_t)tok * DFF + fcol + 4 * n) = pack4(a);
;                     asm volatile("" ::: "memory");
.LBB0_638:
	s_waitcnt lgkmcnt(0)
	v_cndmask_b32_e64 v112, v32, v104, s[8:9]
	v_cndmask_b32_e64 v113, v32, v194, s[6:7]
	v_cndmask_b32_e64 v114, v33, v195, s[6:7]
	v_mov_b32_dpp v104, v112 row_ror:1 row_mask:0xf bank_mask:0xf
	v_cndmask_b32_e64 v106, v34, v106, s[8:9]
	v_cndmask_b32_e64 v115, v34, v192, s[6:7]
	v_mov_b32_dpp v112, v113 row_ror:15 row_mask:0xf bank_mask:0xf
	v_cndmask_b32_e64 v113, v33, v105, s[8:9]
	v_cndmask_b32_e64 v107, v35, v107, s[8:9]
	v_cndmask_b32_e64 v116, v35, v193, s[6:7]
	v_mov_b32_dpp v105, v113 row_ror:1 row_mask:0xf bank_mask:0xf
	v_cndmask_b32_e64 v108, v36, v108, s[8:9]
	v_cndmask_b32_e64 v117, v36, v198, s[6:7]
	v_mov_b32_dpp v113, v114 row_ror:15 row_mask:0xf bank_mask:0xf
	v_cndmask_b32_e64 v109, v37, v109, s[8:9]
	v_cndmask_b32_e64 v118, v37, v199, s[6:7]
	v_mov_b32_dpp v114, v106 row_ror:1 row_mask:0xf bank_mask:0xf
	v_cndmask_b32_e64 v110, v38, v110, s[8:9]
	v_cndmask_b32_e64 v119, v38, v196, s[6:7]
	v_mov_b32_dpp v106, v115 row_ror:15 row_mask:0xf bank_mask:0xf
	v_cndmask_b32_e64 v111, v39, v111, s[8:9]
	v_cndmask_b32_e64 v120, v39, v197, s[6:7]
	v_mov_b32_dpp v115, v107 row_ror:1 row_mask:0xf bank_mask:0xf
	v_mov_b32_dpp v107, v116 row_ror:15 row_mask:0xf bank_mask:0xf
	v_mov_b32_dpp v116, v108 row_ror:1 row_mask:0xf bank_mask:0xf
	v_mov_b32_dpp v108, v117 row_ror:15 row_mask:0xf bank_mask:0xf
	v_mov_b32_dpp v117, v109 row_ror:1 row_mask:0xf bank_mask:0xf
	v_mov_b32_dpp v109, v118 row_ror:15 row_mask:0xf bank_mask:0xf
	v_mov_b32_dpp v118, v110 row_ror:1 row_mask:0xf bank_mask:0xf
	v_mov_b32_dpp v110, v119 row_ror:15 row_mask:0xf bank_mask:0xf
	v_mov_b32_dpp v119, v111 row_ror:1 row_mask:0xf bank_mask:0xf
	v_mov_b32_dpp v111, v120 row_ror:15 row_mask:0xf bank_mask:0xf
	v_add_u32_e32 v120, -1, v245
	v_cmp_gt_u32_e64 s[18:19], s84, v120
	s_and_saveexec_b64 s[0:1], s[18:19]
	s_cbranch_execz .LBB0_640
	s_waitcnt vmcnt(0)
	v_pk_mul_f32 v[114:115], v[74:75], v[114:115]
	v_pk_mul_f32 v[104:105], v[72:73], v[104:105]
	v_pk_fma_f32 v[114:115], v[34:35], v[78:79], v[114:115]
	v_pk_fma_f32 v[104:105], v[32:33], v[76:77], v[104:105]
	v_pk_fma_f32 v[106:107], v[70:71], v[106:107], v[114:115]
	v_pk_fma_f32 v[104:105], v[68:69], v[112:113], v[104:105]
	v_pk_add_f32 v[106:107], v[66:67], v[106:107]
	v_pk_mul_f32 v[118:119], v[94:95], v[118:119]
	v_mul_f32_e32 v114, 0xbfb8aa3b, v107
	v_exp_f32_e32 v114, v114
	v_mul_f32_e32 v113, 0xbfb8aa3b, v106
	v_exp_f32_e32 v113, v113
	v_pk_fma_f32 v[118:119], v[38:39], v[90:91], v[118:119]
	v_add_f32_e32 v112, 1.0, v114
	v_rcp_f32_e32 v112, v112
	v_pk_fma_f32 v[110:111], v[86:87], v[110:111], v[118:119]
	v_pk_add_f32 v[104:105], v[64:65], v[104:105]
	v_pk_add_f32 v[110:111], v[82:83], v[110:111]
	v_mul_f32_e32 v107, v107, v112
	v_mul_f32_e32 v107, v107, v111
	v_add_f32_e32 v111, 1.0, v113
	v_mul_f32_e32 v112, 0xbfb8aa3b, v105
	v_mul_f32_e32 v113, 0xbfb8aa3b, v104
	v_rcp_f32_e32 v111, v111
	v_exp_f32_e32 v112, v112
	v_exp_f32_e32 v113, v113
	v_pk_mul_f32 v[116:117], v[92:93], v[116:117]
	v_mul_f32_e32 v106, v106, v111
	v_add_f32_e32 v111, 1.0, v112
	v_add_f32_e32 v112, 1.0, v113
	v_rcp_f32_e32 v111, v111
	v_rcp_f32_e32 v112, v112
	v_pk_fma_f32 v[116:117], v[36:37], v[88:89], v[116:117]
	v_mul_f32_e32 v106, v106, v110
	v_pk_fma_f32 v[108:109], v[84:85], v[108:109], v[116:117]
	v_mul_f32_e32 v105, v105, v111
	v_pk_add_f32 v[108:109], v[80:81], v[108:109]
	v_mul_f32_e32 v104, v104, v112
	v_mul_f32_e32 v105, v105, v109
	v_mul_f32_e32 v104, v104, v108
	v_cvt_pk_bf16_f32 v104, v104, v105
	v_cvt_pk_bf16_f32 v105, v106, v107
	v_mov_b64_e32 v[106:107], s[88:89]
	s_movk_i32 s4, 0x1600
	v_mad_i64_i32 v[106:107], s[4:5], v152, s4, v[106:107]
	v_lshl_add_u64 v[106:107], v[190:191], 1, v[106:107]
	global_store_dwordx2 v[106:107], v[104:105], off
.LBB0_640:
	s_or_b64 exec, exec, s[0:1]
	v_cndmask_b32_e64 v105, v194, v32, s[8:9]
	v_cndmask_b32_e64 v107, v195, v33, s[8:9]
	s_nop 0
	v_mov_b32_dpp v104, v105 row_ror:1 row_mask:0xf bank_mask:0xf
	v_cndmask_b32_e64 v105, v194, v202, s[6:7]
	v_cndmask_b32_e64 v108, v195, v203, s[6:7]
	s_nop 0
	v_mov_b32_dpp v106, v105 row_ror:15 row_mask:0xf bank_mask:0xf
	v_cndmask_b32_e64 v109, v192, v200, s[6:7]
	v_mov_b32_dpp v105, v107 row_ror:1 row_mask:0xf bank_mask:0xf
	v_cndmask_b32_e64 v112, v193, v201, s[6:7]
	v_mov_b32_dpp v107, v108 row_ror:15 row_mask:0xf bank_mask:0xf
	v_cndmask_b32_e64 v108, v192, v34, s[8:9]
	v_cndmask_b32_e64 v113, v198, v206, s[6:7]
	s_nop 0
	v_mov_b32_dpp v110, v108 row_ror:1 row_mask:0xf bank_mask:0xf
	v_cndmask_b32_e64 v116, v199, v207, s[6:7]
	v_mov_b32_dpp v108, v109 row_ror:15 row_mask:0xf bank_mask:0xf
	v_cndmask_b32_e64 v109, v193, v35, s[8:9]
	v_cndmask_b32_e64 v117, v196, v204, s[6:7]
	s_nop 0
	v_mov_b32_dpp v111, v109 row_ror:1 row_mask:0xf bank_mask:0xf
	v_cndmask_b32_e64 v120, v197, v205, s[6:7]
	v_add_u32_e32 v121, 15, v245
	v_mov_b32_dpp v109, v112 row_ror:15 row_mask:0xf bank_mask:0xf
	v_cndmask_b32_e64 v112, v198, v36, s[8:9]
	v_cmp_gt_u32_e64 s[20:21], s84, v121
	s_nop 0
	v_mov_b32_dpp v114, v112 row_ror:1 row_mask:0xf bank_mask:0xf
	v_mov_b32_dpp v112, v113 row_ror:15 row_mask:0xf bank_mask:0xf
	v_cndmask_b32_e64 v113, v199, v37, s[8:9]
	s_nop 1
	v_mov_b32_dpp v115, v113 row_ror:1 row_mask:0xf bank_mask:0xf
	v_mov_b32_dpp v113, v116 row_ror:15 row_mask:0xf bank_mask:0xf
	v_cndmask_b32_e64 v116, v196, v38, s[8:9]
	s_nop 1
	v_mov_b32_dpp v118, v116 row_ror:1 row_mask:0xf bank_mask:0xf
	v_mov_b32_dpp v116, v117 row_ror:15 row_mask:0xf bank_mask:0xf
	v_cndmask_b32_e64 v117, v197, v39, s[8:9]
	s_nop 1
	v_mov_b32_dpp v119, v117 row_ror:1 row_mask:0xf bank_mask:0xf
	v_mov_b32_dpp v117, v120 row_ror:15 row_mask:0xf bank_mask:0xf
	v_add_u32_e32 v120, s36, v245
	v_add_u32_e32 v248, 15, v120
	s_and_saveexec_b64 s[0:1], s[20:21]
	s_cbranch_execz .LBB0_642
; __device__ __forceinline__ u32x2 pack4(f32x4 a) { u32x2 w; w.x = cvt_pk_bf16(a[0], a[1]); w.y = cvt_pk_bf16(a[2], a[3]); return w; }
; __device__ __forceinline__ float dpp_ror1(float v) { return __builtin_bit_cast(float, __builtin_amdgcn_update_dpp(0, __builtin_bit_cast(int, v), 0x121, 0xf, 0xf, false)); }
; __device__ __forceinline__ float dpp_ror15(float v) { return __builtin_bit_cast(float, __builtin_amdgcn_update_dpp(0, __builtin_bit_cast(int, v), 0x12F, 0xf, 0xf, false)); }
;     template <bool BND> __device__ __forceinline__ void conv_gate(f32x4 (&acc)[2][2][4][2], const Unit& u, int wr, int wc, int fr, int fq, int tok0, int pcol) const {
;     ...
;                 for (int m = 0; m < 4; ++m) {
;                     const int r = ai * 128 + wr * 64 + m * 16 + fr, tok = tok0 + r;
;                     bool isfirst = false, islast = false;
;                     if (BND) { const int S1 = (tok < NPROMPT ? SEQP : SEQS) - 1, pos = tok & S1; isfirst = pos == 0; islast = pos == S1; }
;                     f32x4 cv[2];
; #pragma unroll
;                     for (int bj = 0; bj < 2; ++bj) {
;                         const f32x4 cur = acc[ai][bj][m][n];
;                         const f32x4 ups = m > 0 ? acc[ai][bj][m > 0 ? m - 1 : 0][n] : pe[bj];
;                         const f32x4 dns = m < 3 ? acc[ai][bj][m < 3 ? m + 1 : 3][n] : ne[bj];
;                         f32x4 prev, next;
; #pragma unroll
;                         for (int j = 0; j < 4; ++j) {
;                             const float t1 = fr == 15 ? ups[j] : cur[j]; float pv = dpp_ror1(t1);
;                             const float t2 = fr == 0 ? dns[j] : cur[j]; float nx = dpp_ror15(t2);
;                             if (BND) { prev[j] = isfirst ? 0.f : pv; next[j] = islast ? 0.f : nx; } else { prev[j] = pv; next[j] = nx; }
;                         }
;                         cv[bj] = w0[bj] * prev + w1[bj] * cur + w2[bj] * next + bb[bj];
;                     }
;                     f32x4 a;
; #pragma unroll
;                     for (int j = 0; j < 4; ++j) { const float g = cv[0][j]; const float sg = __builtin_amdgcn_rcpf(1.0f + __builtin_amdgcn_exp2f(-1.4426950408889634f * g)); a[j] = g * sg * cv[1][j]; }
;                     if (r >= 1 && r <= 254 && (!BND || tok < MTOK)) *(u32x2*)(act + (size_t)tok * DFF + fcol + 4 * n) = pack4(a);
;                     asm volatile("" ::: "memory");
	s_waitcnt vmcnt(0)
	v_pk_mul_f32 v[110:111], v[74:75], v[110:111]
	v_pk_mul_f32 v[104:105], v[72:73], v[104:105]
	v_pk_fma_f32 v[110:111], v[192:193], v[78:79], v[110:111]
	v_pk_fma_f32 v[104:105], v[194:195], v[76:77], v[104:105]
	v_pk_fma_f32 v[108:109], v[70:71], v[108:109], v[110:111]
	v_pk_fma_f32 v[104:105], v[68:69], v[106:107], v[104:105]
	v_pk_add_f32 v[108:109], v[66:67], v[108:109]
	v_pk_add_f32 v[104:105], v[64:65], v[104:105]
	v_mul_f32_e32 v110, 0xbfb8aa3b, v109
	v_exp_f32_e32 v110, v110
	v_mul_f32_e32 v107, 0xbfb8aa3b, v108
	v_exp_f32_e32 v107, v107
	v_pk_mul_f32 v[118:119], v[94:95], v[118:119]
	v_add_f32_e32 v106, 1.0, v110
	v_rcp_f32_e32 v106, v106
	v_add_f32_e32 v107, 1.0, v107
	v_mul_f32_e32 v110, 0xbfb8aa3b, v104
	v_rcp_f32_e32 v107, v107
	v_mul_f32_e32 v106, v109, v106
	v_mul_f32_e32 v109, 0xbfb8aa3b, v105
	v_exp_f32_e32 v109, v109
	v_exp_f32_e32 v110, v110
	v_mul_f32_e32 v107, v108, v107
	v_pk_mul_f32 v[114:115], v[92:93], v[114:115]
	v_add_f32_e32 v108, 1.0, v109
	v_add_f32_e32 v109, 1.0, v110
	v_rcp_f32_e32 v108, v108
	v_rcp_f32_e32 v109, v109
	v_pk_fma_f32 v[118:119], v[196:197], v[90:91], v[118:119]
	v_pk_fma_f32 v[114:115], v[198:199], v[88:89], v[114:115]
	v_pk_fma_f32 v[116:117], v[86:87], v[116:117], v[118:119]
	v_pk_fma_f32 v[112:113], v[84:85], v[112:113], v[114:115]
	v_pk_add_f32 v[114:115], v[82:83], v[116:117]
	v_pk_add_f32 v[112:113], v[80:81], v[112:113]
	v_mul_f32_e32 v105, v105, v108
	v_mul_f32_e32 v104, v104, v109
	v_mul_f32_e32 v106, v106, v115
	v_mul_f32_e32 v107, v107, v114
	v_mul_f32_e32 v105, v105, v113
	v_mul_f32_e32 v104, v104, v112
	v_cvt_pk_bf16_f32 v104, v104, v105
	v_cvt_pk_bf16_f32 v105, v107, v106
	v_mov_b64_e32 v[106:107], s[88:89]
	s_movk_i32 s4, 0x1600
	v_mad_i64_i32 v[106:107], s[4:5], v248, s4, v[106:107]
	v_lshl_add_u64 v[106:107], v[190:191], 1, v[106:107]
	global_store_dwordx2 v[106:107], v[104:105], off
.LBB0_642:
	s_or_b64 exec, exec, s[0:1]
	v_cndmask_b32_e64 v105, v202, v194, s[8:9]
	v_cndmask_b32_e64 v107, v203, v195, s[8:9]
	s_nop 0
	v_mov_b32_dpp v104, v105 row_ror:1 row_mask:0xf bank_mask:0xf
	v_cndmask_b32_e64 v105, v202, v48, s[6:7]
	v_cndmask_b32_e64 v108, v203, v49, s[6:7]
	s_nop 0
	v_mov_b32_dpp v106, v105 row_ror:15 row_mask:0xf bank_mask:0xf
	v_cndmask_b32_e64 v109, v200, v50, s[6:7]
	v_mov_b32_dpp v105, v107 row_ror:1 row_mask:0xf bank_mask:0xf
	v_cndmask_b32_e64 v112, v201, v51, s[6:7]
	v_mov_b32_dpp v107, v108 row_ror:15 row_mask:0xf bank_mask:0xf
	v_cndmask_b32_e64 v108, v200, v192, s[8:9]
	v_cndmask_b32_e64 v113, v206, v52, s[6:7]
	s_nop 0
	v_mov_b32_dpp v110, v108 row_ror:1 row_mask:0xf bank_mask:0xf
	v_cndmask_b32_e64 v116, v207, v53, s[6:7]
	v_mov_b32_dpp v108, v109 row_ror:15 row_mask:0xf bank_mask:0xf
	v_cndmask_b32_e64 v109, v201, v193, s[8:9]
	v_cndmask_b32_e64 v117, v204, v54, s[6:7]
	s_nop 0
	v_mov_b32_dpp v111, v109 row_ror:1 row_mask:0xf bank_mask:0xf
	v_cndmask_b32_e64 v121, v205, v55, s[6:7]
	v_add_u32_e32 v249, 31, v120
	v_mov_b32_dpp v109, v112 row_ror:15 row_mask:0xf bank_mask:0xf
	v_cndmask_b32_e64 v112, v206, v198, s[8:9]
	s_nop 1
	v_mov_b32_dpp v114, v112 row_ror:1 row_mask:0xf bank_mask:0xf
	v_mov_b32_dpp v112, v113 row_ror:15 row_mask:0xf bank_mask:0xf
	v_cndmask_b32_e64 v113, v207, v199, s[8:9]
	s_nop 1
	v_mov_b32_dpp v115, v113 row_ror:1 row_mask:0xf bank_mask:0xf
	v_mov_b32_dpp v113, v116 row_ror:15 row_mask:0xf bank_mask:0xf
	v_cndmask_b32_e64 v116, v204, v196, s[8:9]
	s_nop 1
	v_mov_b32_dpp v118, v116 row_ror:1 row_mask:0xf bank_mask:0xf
	v_mov_b32_dpp v116, v117 row_ror:15 row_mask:0xf bank_mask:0xf
	v_cndmask_b32_e64 v117, v205, v197, s[8:9]
	s_nop 1
	v_mov_b32_dpp v119, v117 row_ror:1 row_mask:0xf bank_mask:0xf
	v_mov_b32_dpp v117, v121 row_ror:15 row_mask:0xf bank_mask:0xf
	v_add_u32_e32 v121, 31, v245
	v_cmp_gt_u32_e64 s[22:23], s84, v121
	s_and_saveexec_b64 s[0:1], s[22:23]
	s_cbranch_execz .LBB0_644
	s_waitcnt vmcnt(0)
	v_pk_mul_f32 v[110:111], v[74:75], v[110:111]
	v_pk_mul_f32 v[104:105], v[72:73], v[104:105]
	v_pk_fma_f32 v[110:111], v[200:201], v[78:79], v[110:111]
	v_pk_fma_f32 v[104:105], v[202:203], v[76:77], v[104:105]
	v_pk_fma_f32 v[108:109], v[70:71], v[108:109], v[110:111]
	v_pk_fma_f32 v[104:105], v[68:69], v[106:107], v[104:105]
	v_pk_add_f32 v[108:109], v[66:67], v[108:109]
	v_pk_add_f32 v[104:105], v[64:65], v[104:105]
	v_mul_f32_e32 v110, 0xbfb8aa3b, v109
	v_exp_f32_e32 v110, v110
	v_mul_f32_e32 v107, 0xbfb8aa3b, v108
	v_exp_f32_e32 v107, v107
	v_pk_mul_f32 v[118:119], v[94:95], v[118:119]
	v_add_f32_e32 v106, 1.0, v110
	v_rcp_f32_e32 v106, v106
	v_add_f32_e32 v107, 1.0, v107
	v_mul_f32_e32 v110, 0xbfb8aa3b, v104
	v_rcp_f32_e32 v107, v107
	v_mul_f32_e32 v106, v109, v106
	v_mul_f32_e32 v109, 0xbfb8aa3b, v105
	v_exp_f32_e32 v109, v109
	v_exp_f32_e32 v110, v110
	v_mul_f32_e32 v107, v108, v107
	v_pk_mul_f32 v[114:115], v[92:93], v[114:115]
	v_add_f32_e32 v108, 1.0, v109
	v_add_f32_e32 v109, 1.0, v110
	v_rcp_f32_e32 v108, v108
	v_rcp_f32_e32 v109, v109
	v_pk_fma_f32 v[118:119], v[204:205], v[90:91], v[118:119]
	v_pk_fma_f32 v[114:115], v[206:207], v[88:89], v[114:115]
	v_pk_fma_f32 v[116:117], v[86:87], v[116:117], v[118:119]
	v_pk_fma_f32 v[112:113], v[84:85], v[112:113], v[114:115]
	v_pk_add_f32 v[114:115], v[82:83], v[116:117]
	v_pk_add_f32 v[112:113], v[80:81], v[112:113]
	v_mul_f32_e32 v105, v105, v108
	v_mul_f32_e32 v104, v104, v109
	v_mul_f32_e32 v106, v106, v115
	v_mul_f32_e32 v107, v107, v114
	v_mul_f32_e32 v105, v105, v113
	v_mul_f32_e32 v104, v104, v112
	v_cvt_pk_bf16_f32 v104, v104, v105
	v_cvt_pk_bf16_f32 v105, v107, v106
	v_mov_b64_e32 v[106:107], s[88:89]
	s_movk_i32 s4, 0x1600
	v_mad_i64_i32 v[106:107], s[4:5], v249, s4, v[106:107]
	v_lshl_add_u64 v[106:107], v[190:191], 1, v[106:107]
	global_store_dwordx2 v[106:107], v[104:105], off
; __device__ __forceinline__ u32x2 pack4(f32x4 a) { u32x2 w; w.x = cvt_pk_bf16(a[0], a[1]); w.y = cvt_pk_bf16(a[2], a[3]); return w; }
; __device__ __forceinline__ float dpp_ror1(float v) { return __builtin_bit_cast(float, __builtin_amdgcn_update_dpp(0, __builtin_bit_cast(int, v), 0x121, 0xf, 0xf, false)); }
; __device__ __forceinline__ float dpp_ror15(float v) { return __builtin_bit_cast(float, __builtin_amdgcn_update_dpp(0, __builtin_bit_cast(int, v), 0x12F, 0xf, 0xf, false)); }
;     template <bool BND> __device__ __forceinline__ void conv_gate(f32x4 (&acc)[2][2][4][2], const Unit& u, int wr, int wc, int fr, int fq, int tok0, int pcol) const {
;     ...
;                 for (int m = 0; m < 4; ++m) {
;                     const int r = ai * 128 + wr * 64 + m * 16 + fr, tok = tok0 + r;
;                     bool isfirst = false, islast = false;
;                     if (BND) { const int S1 = (tok < NPROMPT ? SEQP : SEQS) - 1, pos = tok & S1; isfirst = pos == 0; islast = pos == S1; }
;                     f32x4 cv[2];
; #pragma unroll
;                     for (int bj = 0; bj < 2; ++bj) {
;                         const f32x4 cur = acc[ai][bj][m][n];
;                         const f32x4 ups = m > 0 ? acc[ai][bj][m > 0 ? m - 1 : 0][n] : pe[bj];
;                         const f32x4 dns = m < 3 ? acc[ai][bj][m < 3 ? m + 1 : 3][n] : ne[bj];
;                         f32x4 prev, next;
; #pragma unroll
;                         for (int j = 0; j < 4; ++j) {
;                             const float t1 = fr == 15 ? ups[j] : cur[j]; float pv = dpp_ror1(t1);
;                             const float t2 = fr == 0 ? dns[j] : cur[j]; float nx = dpp_ror15(t2);
;                             if (BND) { prev[j] = isfirst ? 0.f : pv; next[j] = islast ? 0.f : nx; } else { prev[j] = pv; next[j] = nx; }
;                         }
;                         cv[bj] = w0[bj] * prev + w1[bj] * cur + w2[bj] * next + bb[bj];
;                     }
;                     f32x4 a;
; #pragma unroll
;                     for (int j = 0; j < 4; ++j) { const float g = cv[0][j]; const float sg = __builtin_amdgcn_rcpf(1.0f + __builtin_amdgcn_exp2f(-1.4426950408889634f * g)); a[j] = g * sg * cv[1][j]; }
;                     if (r >= 1 && r <= 254 && (!BND || tok < MTOK)) *(u32x2*)(act + (size_t)tok * DFF + fcol + 4 * n) = pack4(a);
;                     asm volatile("" ::: "memory");
.LBB0_644:
	s_or_b64 exec, exec, s[0:1]
	v_cndmask_b32_e64 v105, v48, v202, s[8:9]
	v_cndmask_b32_e64 v106, v49, v203, s[8:9]
	v_cndmask_b32_e64 v107, v50, v200, s[8:9]
	v_mov_b32_dpp v104, v105 row_ror:1 row_mask:0xf bank_mask:0xf
	v_cndmask_b32_e64 v105, v48, v96, s[6:7]
	v_cndmask_b32_e64 v108, v51, v201, s[8:9]
	v_cndmask_b32_e64 v109, v52, v206, s[8:9]
	v_mov_b32_dpp v96, v105 row_ror:15 row_mask:0xf bank_mask:0xf
	v_cndmask_b32_e64 v110, v53, v207, s[8:9]
	v_cndmask_b32_e64 v111, v54, v204, s[8:9]
	v_mov_b32_dpp v105, v106 row_ror:1 row_mask:0xf bank_mask:0xf
	v_cndmask_b32_e64 v106, v49, v97, s[6:7]
	v_cndmask_b32_e64 v112, v55, v205, s[8:9]
	v_add_u32_e32 v250, 47, v120
	v_mov_b32_dpp v97, v106 row_ror:15 row_mask:0xf bank_mask:0xf
	v_mov_b32_dpp v106, v107 row_ror:1 row_mask:0xf bank_mask:0xf
	v_cndmask_b32_e64 v107, v50, v98, s[6:7]
	s_nop 1
	v_mov_b32_dpp v98, v107 row_ror:15 row_mask:0xf bank_mask:0xf
	v_mov_b32_dpp v107, v108 row_ror:1 row_mask:0xf bank_mask:0xf
	v_cndmask_b32_e64 v108, v51, v99, s[6:7]
	s_nop 1
	v_mov_b32_dpp v99, v108 row_ror:15 row_mask:0xf bank_mask:0xf
	v_mov_b32_dpp v108, v109 row_ror:1 row_mask:0xf bank_mask:0xf
	v_cndmask_b32_e64 v109, v52, v100, s[6:7]
	s_nop 1
	v_mov_b32_dpp v100, v109 row_ror:15 row_mask:0xf bank_mask:0xf
	v_mov_b32_dpp v109, v110 row_ror:1 row_mask:0xf bank_mask:0xf
	v_cndmask_b32_e64 v110, v53, v101, s[6:7]
	s_nop 1
	v_mov_b32_dpp v101, v110 row_ror:15 row_mask:0xf bank_mask:0xf
	v_mov_b32_dpp v110, v111 row_ror:1 row_mask:0xf bank_mask:0xf
	v_cndmask_b32_e64 v111, v54, v102, s[6:7]
	s_nop 1
	v_mov_b32_dpp v102, v111 row_ror:15 row_mask:0xf bank_mask:0xf
	v_mov_b32_dpp v111, v112 row_ror:1 row_mask:0xf bank_mask:0xf
	v_cndmask_b32_e64 v112, v55, v103, s[6:7]
	s_nop 1
	v_mov_b32_dpp v103, v112 row_ror:15 row_mask:0xf bank_mask:0xf
	v_add_u32_e32 v112, 47, v245
	v_cmp_gt_u32_e64 s[24:25], s84, v112
	s_and_saveexec_b64 s[0:1], s[24:25]
	s_cbranch_execz .LBB0_646
	s_waitcnt vmcnt(0)
	v_pk_mul_f32 v[106:107], v[74:75], v[106:107]
	v_pk_mul_f32 v[104:105], v[72:73], v[104:105]
	v_pk_fma_f32 v[106:107], v[50:51], v[78:79], v[106:107]
	v_pk_fma_f32 v[104:105], v[48:49], v[76:77], v[104:105]
	v_pk_fma_f32 v[98:99], v[70:71], v[98:99], v[106:107]
	v_pk_fma_f32 v[96:97], v[68:69], v[96:97], v[104:105]
	v_pk_add_f32 v[98:99], v[66:67], v[98:99]
	v_pk_mul_f32 v[110:111], v[94:95], v[110:111]
	v_mul_f32_e32 v106, 0xbfb8aa3b, v99
	v_exp_f32_e32 v106, v106
	v_mul_f32_e32 v105, 0xbfb8aa3b, v98
	v_exp_f32_e32 v105, v105
	v_pk_fma_f32 v[110:111], v[54:55], v[90:91], v[110:111]
	v_add_f32_e32 v104, 1.0, v106
	v_rcp_f32_e32 v104, v104
	v_pk_fma_f32 v[102:103], v[86:87], v[102:103], v[110:111]
	v_pk_add_f32 v[96:97], v[64:65], v[96:97]
	v_pk_add_f32 v[102:103], v[82:83], v[102:103]
	v_mul_f32_e32 v99, v99, v104
	v_mul_f32_e32 v99, v99, v103
	v_add_f32_e32 v103, 1.0, v105
	v_mul_f32_e32 v104, 0xbfb8aa3b, v97
	v_mul_f32_e32 v105, 0xbfb8aa3b, v96
	v_rcp_f32_e32 v103, v103
	v_exp_f32_e32 v104, v104
	v_exp_f32_e32 v105, v105
	v_pk_mul_f32 v[108:109], v[92:93], v[108:109]
	v_mul_f32_e32 v98, v98, v103
	v_add_f32_e32 v103, 1.0, v104
	v_add_f32_e32 v104, 1.0, v105
	v_rcp_f32_e32 v103, v103
	v_rcp_f32_e32 v104, v104
	v_pk_fma_f32 v[108:109], v[52:53], v[88:89], v[108:109]
	v_mul_f32_e32 v98, v98, v102
	v_pk_fma_f32 v[100:101], v[84:85], v[100:101], v[108:109]
	v_mul_f32_e32 v97, v97, v103
	v_pk_add_f32 v[100:101], v[80:81], v[100:101]
	v_mul_f32_e32 v96, v96, v104
	v_mul_f32_e32 v97, v97, v101
	v_mul_f32_e32 v96, v96, v100
	v_cvt_pk_bf16_f32 v96, v96, v97
	v_cvt_pk_bf16_f32 v97, v98, v99
	v_mov_b64_e32 v[98:99], s[88:89]
	s_movk_i32 s4, 0x1600
	v_mad_i64_i32 v[98:99], s[4:5], v250, s4, v[98:99]
	v_lshl_add_u64 v[98:99], v[190:191], 1, v[98:99]
	global_store_dwordx2 v[98:99], v[96:97], off

; __device__ __forceinline__ u32x2 pack4(f32x4 a) { u32x2 w; w.x = cvt_pk_bf16(a[0], a[1]); w.y = cvt_pk_bf16(a[2], a[3]); return w; }
; __device__ __forceinline__ float dpp_ror1(float v) { return __builtin_bit_cast(float, __builtin_amdgcn_update_dpp(0, __builtin_bit_cast(int, v), 0x121, 0xf, 0xf, false)); }
; __device__ __forceinline__ float dpp_ror15(float v) { return __builtin_bit_cast(float, __builtin_amdgcn_update_dpp(0, __builtin_bit_cast(int, v), 0x12F, 0xf, 0xf, false)); }
;     template <bool BND> __device__ __forceinline__ void conv_gate(f32x4 (&acc)[2][2][4][2], const Unit& u, int wr, int wc, int fr, int fq, int tok0, int pcol) const {
;     ...
;                 for (int m = 0; m < 4; ++m) {
;                     const int r = ai * 128 + wr * 64 + m * 16 + fr, tok = tok0 + r;
;                     bool isfirst = false, islast = false;
;                     if (BND) { const int S1 = (tok < NPROMPT ? SEQP : SEQS) - 1, pos = tok & S1; isfirst = pos == 0; islast = pos == S1; }
;                     f32x4 cv[2];
; #pragma unroll
;                     for (int bj = 0; bj < 2; ++bj) {
;                         const f32x4 cur = acc[ai][bj][m][n];
;                         const f32x4 ups = m > 0 ? acc[ai][bj][m > 0 ? m - 1 : 0][n] : pe[bj];
;                         const f32x4 dns = m < 3 ? acc[ai][bj][m < 3 ? m + 1 : 3][n] : ne[bj];
;                         f32x4 prev, next;
; #pragma unroll
;                         for (int j = 0; j < 4; ++j) {
;                             const float t1 = fr == 15 ? ups[j] : cur[j]; float pv = dpp_ror1(t1);
;                             const float t2 = fr == 0 ? dns[j] : cur[j]; float nx = dpp_ror15(t2);
;                             if (BND) { prev[j] = isfirst ? 0.f : pv; next[j] = islast ? 0.f : nx; } else { prev[j] = pv; next[j] = nx; }
;                         }
;                         cv[bj] = w0[bj] * prev + w1[bj] * cur + w2[bj] * next + bb[bj];
;                     }
;                     f32x4 a;
; #pragma unroll
;                     for (int j = 0; j < 4; ++j) { const float g = cv[0][j]; const float sg = __builtin_amdgcn_rcpf(1.0f + __builtin_amdgcn_exp2f(-1.4426950408889634f * g)); a[j] = g * sg * cv[1][j]; }
;                     if (r >= 1 && r <= 254 && (!BND || tok < MTOK)) *(u32x2*)(act + (size_t)tok * DFF + fcol + 4 * n) = pack4(a);
;                     asm volatile("" ::: "memory");
.LBB0_654:
	s_waitcnt lgkmcnt(0)
	v_cndmask_b32_e64 v112, v40, v104, s[8:9]
	v_cndmask_b32_e64 v113, v40, v210, s[6:7]
	v_cndmask_b32_e64 v114, v41, v211, s[6:7]
	v_mov_b32_dpp v104, v112 row_ror:1 row_mask:0xf bank_mask:0xf
	v_cndmask_b32_e64 v106, v42, v106, s[8:9]
	v_cndmask_b32_e64 v115, v42, v208, s[6:7]
	v_mov_b32_dpp v112, v113 row_ror:15 row_mask:0xf bank_mask:0xf
	v_cndmask_b32_e64 v113, v41, v105, s[8:9]
	v_cndmask_b32_e64 v107, v43, v107, s[8:9]
	v_cndmask_b32_e64 v116, v43, v209, s[6:7]
	v_mov_b32_dpp v105, v113 row_ror:1 row_mask:0xf bank_mask:0xf
	v_cndmask_b32_e64 v108, v44, v108, s[8:9]
	v_cndmask_b32_e64 v117, v44, v214, s[6:7]
	v_mov_b32_dpp v113, v114 row_ror:15 row_mask:0xf bank_mask:0xf
	v_cndmask_b32_e64 v109, v45, v109, s[8:9]
	v_cndmask_b32_e64 v118, v45, v215, s[6:7]
	v_mov_b32_dpp v114, v106 row_ror:1 row_mask:0xf bank_mask:0xf
	v_cndmask_b32_e64 v110, v46, v110, s[8:9]
	v_cndmask_b32_e64 v119, v46, v212, s[6:7]
	v_mov_b32_dpp v106, v115 row_ror:15 row_mask:0xf bank_mask:0xf
	v_cndmask_b32_e64 v111, v47, v111, s[8:9]
	v_cndmask_b32_e64 v121, v47, v213, s[6:7]
	v_mov_b32_dpp v115, v107 row_ror:1 row_mask:0xf bank_mask:0xf
	v_add_u32_e32 v251, 0x7f, v120
	s_nop 0
	v_mov_b32_dpp v107, v116 row_ror:15 row_mask:0xf bank_mask:0xf
	v_mov_b32_dpp v116, v108 row_ror:1 row_mask:0xf bank_mask:0xf
	v_mov_b32_dpp v108, v117 row_ror:15 row_mask:0xf bank_mask:0xf
	v_mov_b32_dpp v117, v109 row_ror:1 row_mask:0xf bank_mask:0xf
	v_mov_b32_dpp v109, v118 row_ror:15 row_mask:0xf bank_mask:0xf
	v_mov_b32_dpp v118, v110 row_ror:1 row_mask:0xf bank_mask:0xf
	v_mov_b32_dpp v110, v119 row_ror:15 row_mask:0xf bank_mask:0xf
	v_mov_b32_dpp v119, v111 row_ror:1 row_mask:0xf bank_mask:0xf
	v_mov_b32_dpp v111, v121 row_ror:15 row_mask:0xf bank_mask:0xf
	v_add_u32_e32 v121, 0x7f, v245
	v_cmp_gt_u32_e64 s[26:27], s84, v121
	s_and_saveexec_b64 s[0:1], s[26:27]
	s_cbranch_execz .LBB0_656
	s_waitcnt vmcnt(0)
	v_pk_mul_f32 v[114:115], v[74:75], v[114:115]
	v_pk_mul_f32 v[104:105], v[72:73], v[104:105]
	v_pk_fma_f32 v[114:115], v[42:43], v[78:79], v[114:115]
	v_pk_fma_f32 v[104:105], v[40:41], v[76:77], v[104:105]
	v_pk_fma_f32 v[106:107], v[70:71], v[106:107], v[114:115]
	v_pk_fma_f32 v[104:105], v[68:69], v[112:113], v[104:105]
	v_pk_add_f32 v[106:107], v[66:67], v[106:107]
	v_pk_mul_f32 v[118:119], v[94:95], v[118:119]
	v_mul_f32_e32 v114, 0xbfb8aa3b, v107
	v_exp_f32_e32 v114, v114
	v_mul_f32_e32 v113, 0xbfb8aa3b, v106
	v_exp_f32_e32 v113, v113
	v_pk_fma_f32 v[118:119], v[46:47], v[90:91], v[118:119]
	v_add_f32_e32 v112, 1.0, v114
	v_rcp_f32_e32 v112, v112
	v_pk_fma_f32 v[110:111], v[86:87], v[110:111], v[118:119]
	v_pk_add_f32 v[104:105], v[64:65], v[104:105]
	v_pk_add_f32 v[110:111], v[82:83], v[110:111]
	v_mul_f32_e32 v107, v107, v112
	v_mul_f32_e32 v107, v107, v111
	v_add_f32_e32 v111, 1.0, v113
	v_mul_f32_e32 v112, 0xbfb8aa3b, v105
	v_mul_f32_e32 v113, 0xbfb8aa3b, v104
	v_rcp_f32_e32 v111, v111
	v_exp_f32_e32 v112, v112
	v_exp_f32_e32 v113, v113
	v_pk_mul_f32 v[116:117], v[92:93], v[116:117]
	v_mul_f32_e32 v106, v106, v111
	v_add_f32_e32 v111, 1.0, v112
	v_add_f32_e32 v112, 1.0, v113
	v_rcp_f32_e32 v111, v111
	v_rcp_f32_e32 v112, v112
	v_pk_fma_f32 v[116:117], v[44:45], v[88:89], v[116:117]
	v_mul_f32_e32 v106, v106, v110
	v_pk_fma_f32 v[108:109], v[84:85], v[108:109], v[116:117]
	v_mul_f32_e32 v105, v105, v111
	v_pk_add_f32 v[108:109], v[80:81], v[108:109]
	v_mul_f32_e32 v104, v104, v112
	v_mul_f32_e32 v105, v105, v109
	v_mul_f32_e32 v104, v104, v108
	v_cvt_pk_bf16_f32 v104, v104, v105
	v_cvt_pk_bf16_f32 v105, v106, v107
	v_mov_b64_e32 v[106:107], s[88:89]
	s_movk_i32 s4, 0x1600
	v_mad_i64_i32 v[106:107], s[4:5], v251, s4, v[106:107]
	v_lshl_add_u64 v[106:107], v[190:191], 1, v[106:107]
	global_store_dwordx2 v[106:107], v[104:105], off
.LBB0_656:
	s_or_b64 exec, exec, s[0:1]
	v_cndmask_b32_e64 v105, v210, v40, s[8:9]
	v_cndmask_b32_e64 v107, v211, v41, s[8:9]
	s_nop 0
	v_mov_b32_dpp v104, v105 row_ror:1 row_mask:0xf bank_mask:0xf
	v_cndmask_b32_e64 v105, v210, v218, s[6:7]
	v_cndmask_b32_e64 v108, v211, v219, s[6:7]
	s_nop 0
	v_mov_b32_dpp v106, v105 row_ror:15 row_mask:0xf bank_mask:0xf
	v_cndmask_b32_e64 v109, v208, v216, s[6:7]
	v_mov_b32_dpp v105, v107 row_ror:1 row_mask:0xf bank_mask:0xf
	v_cndmask_b32_e64 v112, v209, v217, s[6:7]
	v_mov_b32_dpp v107, v108 row_ror:15 row_mask:0xf bank_mask:0xf
	v_cndmask_b32_e64 v108, v208, v42, s[8:9]
	v_cndmask_b32_e64 v113, v214, v222, s[6:7]
	s_nop 0
	v_mov_b32_dpp v110, v108 row_ror:1 row_mask:0xf bank_mask:0xf
	v_cndmask_b32_e64 v116, v215, v223, s[6:7]
	v_mov_b32_dpp v108, v109 row_ror:15 row_mask:0xf bank_mask:0xf
	v_cndmask_b32_e64 v109, v209, v43, s[8:9]
	v_cndmask_b32_e64 v117, v212, v220, s[6:7]
	s_nop 0
	v_mov_b32_dpp v111, v109 row_ror:1 row_mask:0xf bank_mask:0xf
	v_cndmask_b32_e64 v121, v213, v221, s[6:7]
	v_add_u32_e32 v252, 0x8f, v120
	v_mov_b32_dpp v109, v112 row_ror:15 row_mask:0xf bank_mask:0xf
	v_cndmask_b32_e64 v112, v214, v44, s[8:9]
	s_nop 1
	v_mov_b32_dpp v114, v112 row_ror:1 row_mask:0xf bank_mask:0xf
	v_mov_b32_dpp v112, v113 row_ror:15 row_mask:0xf bank_mask:0xf
	v_cndmask_b32_e64 v113, v215, v45, s[8:9]
	s_nop 1
	v_mov_b32_dpp v115, v113 row_ror:1 row_mask:0xf bank_mask:0xf
	v_mov_b32_dpp v113, v116 row_ror:15 row_mask:0xf bank_mask:0xf
	v_cndmask_b32_e64 v116, v212, v46, s[8:9]
	s_nop 1
	v_mov_b32_dpp v118, v116 row_ror:1 row_mask:0xf bank_mask:0xf
	v_mov_b32_dpp v116, v117 row_ror:15 row_mask:0xf bank_mask:0xf
	v_cndmask_b32_e64 v117, v213, v47, s[8:9]
	s_nop 1
	v_mov_b32_dpp v119, v117 row_ror:1 row_mask:0xf bank_mask:0xf
	v_mov_b32_dpp v117, v121 row_ror:15 row_mask:0xf bank_mask:0xf
	v_add_u32_e32 v121, 0x8f, v245
	v_cmp_gt_u32_e64 s[28:29], s84, v121
	s_and_saveexec_b64 s[0:1], s[28:29]
	s_cbranch_execz .LBB0_658
; __device__ __forceinline__ u32x2 pack4(f32x4 a) { u32x2 w; w.x = cvt_pk_bf16(a[0], a[1]); w.y = cvt_pk_bf16(a[2], a[3]); return w; }
; __device__ __forceinline__ float dpp_ror1(float v) { return __builtin_bit_cast(float, __builtin_amdgcn_update_dpp(0, __builtin_bit_cast(int, v), 0x121, 0xf, 0xf, false)); }
; __device__ __forceinline__ float dpp_ror15(float v) { return __builtin_bit_cast(float, __builtin_amdgcn_update_dpp(0, __builtin_bit_cast(int, v), 0x12F, 0xf, 0xf, false)); }
;     template <bool BND> __device__ __forceinline__ void conv_gate(f32x4 (&acc)[2][2][4][2], const Unit& u, int wr, int wc, int fr, int fq, int tok0, int pcol) const {
;     ...
;                 for (int m = 0; m < 4; ++m) {
;                     const int r = ai * 128 + wr * 64 + m * 16 + fr, tok = tok0 + r;
;                     bool isfirst = false, islast = false;
;                     if (BND) { const int S1 = (tok < NPROMPT ? SEQP : SEQS) - 1, pos = tok & S1; isfirst = pos == 0; islast = pos == S1; }
;                     f32x4 cv[2];
; #pragma unroll
;                     for (int bj = 0; bj < 2; ++bj) {
;                         const f32x4 cur = acc[ai][bj][m][n];
;                         const f32x4 ups = m > 0 ? acc[ai][bj][m > 0 ? m - 1 : 0][n] : pe[bj];
;                         const f32x4 dns = m < 3 ? acc[ai][bj][m < 3 ? m + 1 : 3][n] : ne[bj];
;                         f32x4 prev, next;
; #pragma unroll
;                         for (int j = 0; j < 4; ++j) {
;                             const float t1 = fr == 15 ? ups[j] : cur[j]; float pv = dpp_ror1(t1);
;                             const float t2 = fr == 0 ? dns[j] : cur[j]; float nx = dpp_ror15(t2);
;                             if (BND) { prev[j] = isfirst ? 0.f : pv; next[j] = islast ? 0.f : nx; } else { prev[j] = pv; next[j] = nx; }
;                         }
;                         cv[bj] = w0[bj] * prev + w1[bj] * cur + w2[bj] * next + bb[bj];
;                     }
;                     f32x4 a;
; #pragma unroll
;                     for (int j = 0; j < 4; ++j) { const float g = cv[0][j]; const float sg = __builtin_amdgcn_rcpf(1.0f + __builtin_amdgcn_exp2f(-1.4426950408889634f * g)); a[j] = g * sg * cv[1][j]; }
;                     if (r >= 1 && r <= 254 && (!BND || tok < MTOK)) *(u32x2*)(act + (size_t)tok * DFF + fcol + 4 * n) = pack4(a);
;                     asm volatile("" ::: "memory");
	s_waitcnt vmcnt(0)
	v_pk_mul_f32 v[110:111], v[74:75], v[110:111]
	v_pk_mul_f32 v[104:105], v[72:73], v[104:105]
	v_pk_fma_f32 v[110:111], v[208:209], v[78:79], v[110:111]
	v_pk_fma_f32 v[104:105], v[210:211], v[76:77], v[104:105]
	v_pk_fma_f32 v[108:109], v[70:71], v[108:109], v[110:111]
	v_pk_fma_f32 v[104:105], v[68:69], v[106:107], v[104:105]
	v_pk_add_f32 v[108:109], v[66:67], v[108:109]
	v_pk_add_f32 v[104:105], v[64:65], v[104:105]
	v_mul_f32_e32 v110, 0xbfb8aa3b, v109
	v_exp_f32_e32 v110, v110
	v_mul_f32_e32 v107, 0xbfb8aa3b, v108
	v_exp_f32_e32 v107, v107
	v_pk_mul_f32 v[118:119], v[94:95], v[118:119]
	v_add_f32_e32 v106, 1.0, v110
	v_rcp_f32_e32 v106, v106
	v_add_f32_e32 v107, 1.0, v107
	v_mul_f32_e32 v110, 0xbfb8aa3b, v104
	v_rcp_f32_e32 v107, v107
	v_mul_f32_e32 v106, v109, v106
	v_mul_f32_e32 v109, 0xbfb8aa3b, v105
	v_exp_f32_e32 v109, v109
	v_exp_f32_e32 v110, v110
	v_mul_f32_e32 v107, v108, v107
	v_pk_mul_f32 v[114:115], v[92:93], v[114:115]
	v_add_f32_e32 v108, 1.0, v109
	v_add_f32_e32 v109, 1.0, v110
	v_rcp_f32_e32 v108, v108
	v_rcp_f32_e32 v109, v109
	v_pk_fma_f32 v[118:119], v[212:213], v[90:91], v[118:119]
	v_pk_fma_f32 v[114:115], v[214:215], v[88:89], v[114:115]
	v_pk_fma_f32 v[116:117], v[86:87], v[116:117], v[118:119]
	v_pk_fma_f32 v[112:113], v[84:85], v[112:113], v[114:115]
	v_pk_add_f32 v[114:115], v[82:83], v[116:117]
	v_pk_add_f32 v[112:113], v[80:81], v[112:113]
	v_mul_f32_e32 v105, v105, v108
	v_mul_f32_e32 v104, v104, v109
	v_mul_f32_e32 v106, v106, v115
	v_mul_f32_e32 v107, v107, v114
	v_mul_f32_e32 v105, v105, v113
	v_mul_f32_e32 v104, v104, v112
	v_cvt_pk_bf16_f32 v104, v104, v105
	v_cvt_pk_bf16_f32 v105, v107, v106
	v_mov_b64_e32 v[106:107], s[88:89]
	s_movk_i32 s4, 0x1600
	v_mad_i64_i32 v[106:107], s[4:5], v252, s4, v[106:107]
	v_lshl_add_u64 v[106:107], v[190:191], 1, v[106:107]
	global_store_dwordx2 v[106:107], v[104:105], off
.LBB0_658:
	s_or_b64 exec, exec, s[0:1]
	v_cndmask_b32_e64 v105, v218, v210, s[8:9]
	v_cndmask_b32_e64 v107, v219, v211, s[8:9]
	s_nop 0
	v_mov_b32_dpp v104, v105 row_ror:1 row_mask:0xf bank_mask:0xf
	v_cndmask_b32_e64 v105, v218, v56, s[6:7]
	v_cndmask_b32_e64 v108, v219, v57, s[6:7]
	s_nop 0
	v_mov_b32_dpp v106, v105 row_ror:15 row_mask:0xf bank_mask:0xf
	v_cndmask_b32_e64 v109, v216, v58, s[6:7]
	v_mov_b32_dpp v105, v107 row_ror:1 row_mask:0xf bank_mask:0xf
	v_cndmask_b32_e64 v112, v217, v59, s[6:7]
	v_mov_b32_dpp v107, v108 row_ror:15 row_mask:0xf bank_mask:0xf
	v_cndmask_b32_e64 v108, v216, v208, s[8:9]
	v_cndmask_b32_e64 v113, v222, v60, s[6:7]
	s_nop 0
	v_mov_b32_dpp v110, v108 row_ror:1 row_mask:0xf bank_mask:0xf
	v_cndmask_b32_e64 v116, v223, v61, s[6:7]
	v_mov_b32_dpp v108, v109 row_ror:15 row_mask:0xf bank_mask:0xf
	v_cndmask_b32_e64 v109, v217, v209, s[8:9]
	v_cndmask_b32_e64 v117, v220, v62, s[6:7]
	s_nop 0
	v_mov_b32_dpp v111, v109 row_ror:1 row_mask:0xf bank_mask:0xf
	v_cndmask_b32_e64 v121, v221, v63, s[6:7]
	v_add_u32_e32 v253, 0x9f, v120
	v_mov_b32_dpp v109, v112 row_ror:15 row_mask:0xf bank_mask:0xf
	v_cndmask_b32_e64 v112, v222, v214, s[8:9]
	s_nop 1
	v_mov_b32_dpp v114, v112 row_ror:1 row_mask:0xf bank_mask:0xf
	v_mov_b32_dpp v112, v113 row_ror:15 row_mask:0xf bank_mask:0xf
	v_cndmask_b32_e64 v113, v223, v215, s[8:9]
	s_nop 1
	v_mov_b32_dpp v115, v113 row_ror:1 row_mask:0xf bank_mask:0xf
	v_mov_b32_dpp v113, v116 row_ror:15 row_mask:0xf bank_mask:0xf
	v_cndmask_b32_e64 v116, v220, v212, s[8:9]
	s_nop 1
	v_mov_b32_dpp v118, v116 row_ror:1 row_mask:0xf bank_mask:0xf
	v_mov_b32_dpp v116, v117 row_ror:15 row_mask:0xf bank_mask:0xf
	v_cndmask_b32_e64 v117, v221, v213, s[8:9]
	s_nop 1
	v_mov_b32_dpp v119, v117 row_ror:1 row_mask:0xf bank_mask:0xf
	v_mov_b32_dpp v117, v121 row_ror:15 row_mask:0xf bank_mask:0xf
	v_add_u32_e32 v121, 0x9f, v245
	v_cmp_gt_u32_e64 s[30:31], s84, v121
	s_and_saveexec_b64 s[0:1], s[30:31]
	s_cbranch_execz .LBB0_660
	s_waitcnt vmcnt(0)
	v_pk_mul_f32 v[110:111], v[74:75], v[110:111]
	v_pk_mul_f32 v[104:105], v[72:73], v[104:105]
	v_pk_fma_f32 v[110:111], v[216:217], v[78:79], v[110:111]
	v_pk_fma_f32 v[104:105], v[218:219], v[76:77], v[104:105]
	v_pk_fma_f32 v[108:109], v[70:71], v[108:109], v[110:111]
	v_pk_fma_f32 v[104:105], v[68:69], v[106:107], v[104:105]
	v_pk_add_f32 v[108:109], v[66:67], v[108:109]
	v_pk_add_f32 v[104:105], v[64:65], v[104:105]
	v_mul_f32_e32 v110, 0xbfb8aa3b, v109
	v_exp_f32_e32 v110, v110
	v_mul_f32_e32 v107, 0xbfb8aa3b, v108
	v_exp_f32_e32 v107, v107
	v_pk_mul_f32 v[118:119], v[94:95], v[118:119]
	v_add_f32_e32 v106, 1.0, v110
	v_rcp_f32_e32 v106, v106
	v_add_f32_e32 v107, 1.0, v107
	v_mul_f32_e32 v110, 0xbfb8aa3b, v104
	v_rcp_f32_e32 v107, v107
	v_mul_f32_e32 v106, v109, v106
	v_mul_f32_e32 v109, 0xbfb8aa3b, v105
	v_exp_f32_e32 v109, v109
	v_exp_f32_e32 v110, v110
	v_mul_f32_e32 v107, v108, v107
	v_pk_mul_f32 v[114:115], v[92:93], v[114:115]
	v_add_f32_e32 v108, 1.0, v109
	v_add_f32_e32 v109, 1.0, v110
	v_rcp_f32_e32 v108, v108
	v_rcp_f32_e32 v109, v109
	v_pk_fma_f32 v[118:119], v[220:221], v[90:91], v[118:119]
	v_pk_fma_f32 v[114:115], v[222:223], v[88:89], v[114:115]
	v_pk_fma_f32 v[116:117], v[86:87], v[116:117], v[118:119]
	v_pk_fma_f32 v[112:113], v[84:85], v[112:113], v[114:115]
	v_pk_add_f32 v[114:115], v[82:83], v[116:117]
	v_pk_add_f32 v[112:113], v[80:81], v[112:113]
	v_mul_f32_e32 v105, v105, v108
	v_mul_f32_e32 v104, v104, v109
	v_mul_f32_e32 v106, v106, v115
	v_mul_f32_e32 v107, v107, v114
	v_mul_f32_e32 v105, v105, v113
	v_mul_f32_e32 v104, v104, v112
	v_cvt_pk_bf16_f32 v104, v104, v105
	v_cvt_pk_bf16_f32 v105, v107, v106
	v_mov_b64_e32 v[106:107], s[88:89]
	s_movk_i32 s4, 0x1600
	v_mad_i64_i32 v[106:107], s[4:5], v253, s4, v[106:107]
	v_lshl_add_u64 v[106:107], v[190:191], 1, v[106:107]
	global_store_dwordx2 v[106:107], v[104:105], off
; __device__ __forceinline__ u32x2 pack4(f32x4 a) { u32x2 w; w.x = cvt_pk_bf16(a[0], a[1]); w.y = cvt_pk_bf16(a[2], a[3]); return w; }
; __device__ __forceinline__ float dpp_ror1(float v) { return __builtin_bit_cast(float, __builtin_amdgcn_update_dpp(0, __builtin_bit_cast(int, v), 0x121, 0xf, 0xf, false)); }
; __device__ __forceinline__ float dpp_ror15(float v) { return __builtin_bit_cast(float, __builtin_amdgcn_update_dpp(0, __builtin_bit_cast(int, v), 0x12F, 0xf, 0xf, false)); }
;     template <bool BND> __device__ __forceinline__ void conv_gate(f32x4 (&acc)[2][2][4][2], const Unit& u, int wr, int wc, int fr, int fq, int tok0, int pcol) const {
;     ...
;                 for (int m = 0; m < 4; ++m) {
;                     const int r = ai * 128 + wr * 64 + m * 16 + fr, tok = tok0 + r;
;                     bool isfirst = false, islast = false;
;                     if (BND) { const int S1 = (tok < NPROMPT ? SEQP : SEQS) - 1, pos = tok & S1; isfirst = pos == 0; islast = pos == S1; }
;                     f32x4 cv[2];
; #pragma unroll
;                     for (int bj = 0; bj < 2; ++bj) {
;                         const f32x4 cur = acc[ai][bj][m][n];
;                         const f32x4 ups = m > 0 ? acc[ai][bj][m > 0 ? m - 1 : 0][n] : pe[bj];
;                         const f32x4 dns = m < 3 ? acc[ai][bj][m < 3 ? m + 1 : 3][n] : ne[bj];
;                         f32x4 prev, next;
; #pragma unroll
;                         for (int j = 0; j < 4; ++j) {
;                             const float t1 = fr == 15 ? ups[j] : cur[j]; float pv = dpp_ror1(t1);
;                             const float t2 = fr == 0 ? dns[j] : cur[j]; float nx = dpp_ror15(t2);
;                             if (BND) { prev[j] = isfirst ? 0.f : pv; next[j] = islast ? 0.f : nx; } else { prev[j] = pv; next[j] = nx; }
;                         }
;                         cv[bj] = w0[bj] * prev + w1[bj] * cur + w2[bj] * next + bb[bj];
;                     }
;                     f32x4 a;
; #pragma unroll
;                     for (int j = 0; j < 4; ++j) { const float g = cv[0][j]; const float sg = __builtin_amdgcn_rcpf(1.0f + __builtin_amdgcn_exp2f(-1.4426950408889634f * g)); a[j] = g * sg * cv[1][j]; }
;                     if (r >= 1 && r <= 254 && (!BND || tok < MTOK)) *(u32x2*)(act + (size_t)tok * DFF + fcol + 4 * n) = pack4(a);
;                     asm volatile("" ::: "memory");
.LBB0_660:
	s_or_b64 exec, exec, s[0:1]
	v_cndmask_b32_e64 v105, v56, v218, s[8:9]
	v_cndmask_b32_e64 v106, v57, v219, s[8:9]
	v_cndmask_b32_e64 v107, v58, v216, s[8:9]
	v_mov_b32_dpp v104, v105 row_ror:1 row_mask:0xf bank_mask:0xf
	v_cndmask_b32_e64 v105, v56, v96, s[6:7]
	v_cndmask_b32_e64 v108, v59, v217, s[8:9]
	v_cndmask_b32_e64 v109, v60, v222, s[8:9]
	v_mov_b32_dpp v96, v105 row_ror:15 row_mask:0xf bank_mask:0xf
	v_cndmask_b32_e64 v110, v61, v223, s[8:9]
	v_cndmask_b32_e64 v111, v62, v220, s[8:9]
	v_mov_b32_dpp v105, v106 row_ror:1 row_mask:0xf bank_mask:0xf
	v_cndmask_b32_e64 v106, v57, v97, s[6:7]
	v_cndmask_b32_e64 v112, v63, v221, s[8:9]
	v_add_u32_e32 v254, 0xaf, v120
	v_mov_b32_dpp v97, v106 row_ror:15 row_mask:0xf bank_mask:0xf
	v_mov_b32_dpp v106, v107 row_ror:1 row_mask:0xf bank_mask:0xf
	v_cndmask_b32_e64 v107, v58, v98, s[6:7]
	s_nop 1
	v_mov_b32_dpp v98, v107 row_ror:15 row_mask:0xf bank_mask:0xf
	v_mov_b32_dpp v107, v108 row_ror:1 row_mask:0xf bank_mask:0xf
	v_cndmask_b32_e64 v108, v59, v99, s[6:7]
	s_nop 1
	v_mov_b32_dpp v99, v108 row_ror:15 row_mask:0xf bank_mask:0xf
	v_mov_b32_dpp v108, v109 row_ror:1 row_mask:0xf bank_mask:0xf
	v_cndmask_b32_e64 v109, v60, v100, s[6:7]
	s_nop 1
	v_mov_b32_dpp v100, v109 row_ror:15 row_mask:0xf bank_mask:0xf
	v_mov_b32_dpp v109, v110 row_ror:1 row_mask:0xf bank_mask:0xf
	v_cndmask_b32_e64 v110, v61, v101, s[6:7]
	s_nop 1
	v_mov_b32_dpp v101, v110 row_ror:15 row_mask:0xf bank_mask:0xf
	v_mov_b32_dpp v110, v111 row_ror:1 row_mask:0xf bank_mask:0xf
	v_cndmask_b32_e64 v111, v62, v102, s[6:7]
	s_nop 1
	v_mov_b32_dpp v102, v111 row_ror:15 row_mask:0xf bank_mask:0xf
	v_mov_b32_dpp v111, v112 row_ror:1 row_mask:0xf bank_mask:0xf
	v_cndmask_b32_e64 v112, v63, v103, s[6:7]
	s_nop 1
	v_mov_b32_dpp v103, v112 row_ror:15 row_mask:0xf bank_mask:0xf
	v_add_u32_e32 v112, 0xaf, v245
	v_cmp_gt_u32_e64 s[34:35], s84, v112
	s_and_saveexec_b64 s[0:1], s[34:35]
	s_cbranch_execz .LBB0_662
	s_waitcnt vmcnt(0)
	v_pk_mul_f32 v[106:107], v[74:75], v[106:107]
	v_pk_mul_f32 v[104:105], v[72:73], v[104:105]
	v_pk_fma_f32 v[106:107], v[58:59], v[78:79], v[106:107]
	v_pk_fma_f32 v[104:105], v[56:57], v[76:77], v[104:105]
	v_pk_fma_f32 v[98:99], v[70:71], v[98:99], v[106:107]
	v_pk_fma_f32 v[96:97], v[68:69], v[96:97], v[104:105]
	v_pk_add_f32 v[98:99], v[66:67], v[98:99]
	v_pk_mul_f32 v[110:111], v[94:95], v[110:111]
	v_mul_f32_e32 v106, 0xbfb8aa3b, v99
	v_exp_f32_e32 v106, v106
	v_mul_f32_e32 v105, 0xbfb8aa3b, v98
	v_exp_f32_e32 v105, v105
	v_pk_fma_f32 v[110:111], v[62:63], v[90:91], v[110:111]
	v_add_f32_e32 v104, 1.0, v106
	v_rcp_f32_e32 v104, v104
	v_pk_fma_f32 v[102:103], v[86:87], v[102:103], v[110:111]
	v_pk_add_f32 v[96:97], v[64:65], v[96:97]
	v_pk_add_f32 v[102:103], v[82:83], v[102:103]
	v_mul_f32_e32 v99, v99, v104
	v_mul_f32_e32 v99, v99, v103
	v_add_f32_e32 v103, 1.0, v105
	v_mul_f32_e32 v104, 0xbfb8aa3b, v97
	v_mul_f32_e32 v105, 0xbfb8aa3b, v96
	v_rcp_f32_e32 v103, v103
	v_exp_f32_e32 v104, v104
	v_exp_f32_e32 v105, v105
	v_pk_mul_f32 v[108:109], v[92:93], v[108:109]
	v_mul_f32_e32 v98, v98, v103
	v_add_f32_e32 v103, 1.0, v104
	v_add_f32_e32 v104, 1.0, v105
	v_rcp_f32_e32 v103, v103
	v_rcp_f32_e32 v104, v104
	v_pk_fma_f32 v[108:109], v[60:61], v[88:89], v[108:109]
	v_mul_f32_e32 v98, v98, v102
	v_pk_fma_f32 v[100:101], v[84:85], v[100:101], v[108:109]
	v_mul_f32_e32 v97, v97, v103
	v_pk_add_f32 v[100:101], v[80:81], v[100:101]
	v_mul_f32_e32 v96, v96, v104
	v_mul_f32_e32 v97, v97, v101
	v_mul_f32_e32 v96, v96, v100
	v_cvt_pk_bf16_f32 v96, v96, v97
	v_cvt_pk_bf16_f32 v97, v98, v99
	v_mov_b64_e32 v[98:99], s[88:89]
	s_movk_i32 s4, 0x1600
	v_mad_i64_i32 v[98:99], s[4:5], v254, s4, v[98:99]
	v_lshl_add_u64 v[98:99], v[190:191], 1, v[98:99]
	global_store_dwordx2 v[98:99], v[96:97], off

; __device__ __forceinline__ u32x2 pack4(f32x4 a) { u32x2 w; w.x = cvt_pk_bf16(a[0], a[1]); w.y = cvt_pk_bf16(a[2], a[3]); return w; }
; __device__ __forceinline__ float dpp_ror1(float v) { return __builtin_bit_cast(float, __builtin_amdgcn_update_dpp(0, __builtin_bit_cast(int, v), 0x121, 0xf, 0xf, false)); }
; __device__ __forceinline__ float dpp_ror15(float v) { return __builtin_bit_cast(float, __builtin_amdgcn_update_dpp(0, __builtin_bit_cast(int, v), 0x12F, 0xf, 0xf, false)); }
;     template <bool BND> __device__ __forceinline__ void conv_gate(f32x4 (&acc)[2][2][4][2], const Unit& u, int wr, int wc, int fr, int fq, int tok0, int pcol) const {
;     ...
;                 for (int m = 0; m < 4; ++m) {
;                     const int r = ai * 128 + wr * 64 + m * 16 + fr, tok = tok0 + r;
;                     bool isfirst = false, islast = false;
;                     if (BND) { const int S1 = (tok < NPROMPT ? SEQP : SEQS) - 1, pos = tok & S1; isfirst = pos == 0; islast = pos == S1; }
;                     f32x4 cv[2];
; #pragma unroll
;                     for (int bj = 0; bj < 2; ++bj) {
;                         const f32x4 cur = acc[ai][bj][m][n];
;                         const f32x4 ups = m > 0 ? acc[ai][bj][m > 0 ? m - 1 : 0][n] : pe[bj];
;                         const f32x4 dns = m < 3 ? acc[ai][bj][m < 3 ? m + 1 : 3][n] : ne[bj];
;                         f32x4 prev, next;
; #pragma unroll
;                         for (int j = 0; j < 4; ++j) {
;                             const float t1 = fr == 15 ? ups[j] : cur[j]; float pv = dpp_ror1(t1);
;                             const float t2 = fr == 0 ? dns[j] : cur[j]; float nx = dpp_ror15(t2);
;                             if (BND) { prev[j] = isfirst ? 0.f : pv; next[j] = islast ? 0.f : nx; } else { prev[j] = pv; next[j] = nx; }
;                         }
;                         cv[bj] = w0[bj] * prev + w1[bj] * cur + w2[bj] * next + bb[bj];
;                     }
;                     f32x4 a;
; #pragma unroll
;                     for (int j = 0; j < 4; ++j) { const float g = cv[0][j]; const float sg = __builtin_amdgcn_rcpf(1.0f + __builtin_amdgcn_exp2f(-1.4426950408889634f * g)); a[j] = g * sg * cv[1][j]; }
;                     if (r >= 1 && r <= 254 && (!BND || tok < MTOK)) *(u32x2*)(act + (size_t)tok * DFF + fcol + 4 * n) = pack4(a);
;                     asm volatile("" ::: "memory");
.LBB0_670:
	s_waitcnt lgkmcnt(0)
	v_cndmask_b32_e64 v228, v0, v136, s[8:9]
	v_cndmask_b32_e64 v229, v0, v160, s[6:7]
	v_cndmask_b32_e64 v230, v1, v161, s[6:7]
	v_mov_b32_dpp v136, v228 row_ror:1 row_mask:0xf bank_mask:0xf
	v_cndmask_b32_e64 v138, v2, v138, s[8:9]
	v_cndmask_b32_e64 v231, v2, v158, s[6:7]
	v_mov_b32_dpp v228, v229 row_ror:15 row_mask:0xf bank_mask:0xf
	v_cndmask_b32_e64 v229, v1, v137, s[8:9]
	v_cndmask_b32_e64 v139, v3, v139, s[8:9]
	v_cndmask_b32_e64 v232, v3, v159, s[6:7]
	v_mov_b32_dpp v137, v229 row_ror:1 row_mask:0xf bank_mask:0xf
	v_cndmask_b32_e64 v140, v4, v140, s[8:9]
	v_cndmask_b32_e64 v233, v4, v164, s[6:7]
	v_mov_b32_dpp v229, v230 row_ror:15 row_mask:0xf bank_mask:0xf
	v_cndmask_b32_e64 v141, v5, v141, s[8:9]
	v_cndmask_b32_e64 v234, v5, v165, s[6:7]
	v_mov_b32_dpp v230, v138 row_ror:1 row_mask:0xf bank_mask:0xf
	v_cndmask_b32_e64 v142, v6, v142, s[8:9]
	v_cndmask_b32_e64 v235, v6, v162, s[6:7]
	v_mov_b32_dpp v138, v231 row_ror:15 row_mask:0xf bank_mask:0xf
	v_cndmask_b32_e64 v143, v7, v143, s[8:9]
	v_cndmask_b32_e64 v236, v7, v163, s[6:7]
	v_mov_b32_dpp v231, v139 row_ror:1 row_mask:0xf bank_mask:0xf
	v_mov_b32_dpp v139, v232 row_ror:15 row_mask:0xf bank_mask:0xf
	v_mov_b32_dpp v232, v140 row_ror:1 row_mask:0xf bank_mask:0xf
	v_mov_b32_dpp v140, v233 row_ror:15 row_mask:0xf bank_mask:0xf
	v_mov_b32_dpp v233, v141 row_ror:1 row_mask:0xf bank_mask:0xf
	v_mov_b32_dpp v141, v234 row_ror:15 row_mask:0xf bank_mask:0xf
	v_mov_b32_dpp v234, v142 row_ror:1 row_mask:0xf bank_mask:0xf
	v_mov_b32_dpp v142, v235 row_ror:15 row_mask:0xf bank_mask:0xf
	v_mov_b32_dpp v235, v143 row_ror:1 row_mask:0xf bank_mask:0xf
	v_mov_b32_dpp v143, v236 row_ror:15 row_mask:0xf bank_mask:0xf
	s_and_saveexec_b64 s[0:1], s[18:19]
	s_cbranch_execz .LBB0_672
	s_waitcnt vmcnt(0)
	v_pk_mul_f32 v[230:231], v[98:99], v[230:231]
	v_pk_mul_f32 v[136:137], v[96:97], v[136:137]
	v_pk_fma_f32 v[230:231], v[2:3], v[106:107], v[230:231]
	v_pk_fma_f32 v[136:137], v[0:1], v[104:105], v[136:137]
	v_pk_fma_f32 v[138:139], v[110:111], v[138:139], v[230:231]
	v_pk_fma_f32 v[136:137], v[108:109], v[228:229], v[136:137]
	v_pk_add_f32 v[138:139], v[102:103], v[138:139]
	v_pk_mul_f32 v[234:235], v[126:127], v[234:235]
	v_mul_f32_e32 v230, 0xbfb8aa3b, v139
	v_exp_f32_e32 v230, v230
	v_mul_f32_e32 v229, 0xbfb8aa3b, v138
	v_exp_f32_e32 v229, v229
	v_pk_fma_f32 v[234:235], v[6:7], v[122:123], v[234:235]
	v_add_f32_e32 v228, 1.0, v230
	v_rcp_f32_e32 v228, v228
	v_pk_fma_f32 v[142:143], v[118:119], v[142:143], v[234:235]
	v_pk_add_f32 v[136:137], v[100:101], v[136:137]
	v_pk_add_f32 v[142:143], v[114:115], v[142:143]
	v_mul_f32_e32 v139, v139, v228
	v_mul_f32_e32 v139, v139, v143
	v_add_f32_e32 v143, 1.0, v229
	v_mul_f32_e32 v228, 0xbfb8aa3b, v137
	v_mul_f32_e32 v229, 0xbfb8aa3b, v136
	v_rcp_f32_e32 v143, v143
	v_exp_f32_e32 v228, v228
	v_exp_f32_e32 v229, v229
	v_pk_mul_f32 v[232:233], v[124:125], v[232:233]
	v_mul_f32_e32 v138, v138, v143
	v_add_f32_e32 v143, 1.0, v228
	v_add_f32_e32 v228, 1.0, v229
	v_rcp_f32_e32 v143, v143
	v_rcp_f32_e32 v228, v228
	v_pk_fma_f32 v[232:233], v[4:5], v[120:121], v[232:233]
	v_mul_f32_e32 v138, v138, v142
	v_pk_fma_f32 v[140:141], v[116:117], v[140:141], v[232:233]
	v_mul_f32_e32 v137, v137, v143
	v_pk_add_f32 v[140:141], v[112:113], v[140:141]
	v_mul_f32_e32 v136, v136, v228
	v_mul_f32_e32 v137, v137, v141
	v_mul_f32_e32 v136, v136, v140
	v_cvt_pk_bf16_f32 v136, v136, v137
	v_cvt_pk_bf16_f32 v137, v138, v139
	v_mov_b64_e32 v[138:139], s[88:89]
	s_movk_i32 s4, 0x1600
	v_mad_i64_i32 v[138:139], s[4:5], v152, s4, v[138:139]
	v_lshl_add_u64 v[138:139], v[190:191], 1, v[138:139]
	global_store_dwordx2 v[138:139], v[136:137], off offset:8
.LBB0_672:
	s_or_b64 exec, exec, s[0:1]
	v_cndmask_b32_e64 v137, v160, v0, s[8:9]
	v_cndmask_b32_e64 v139, v161, v1, s[8:9]
	s_nop 0
	v_mov_b32_dpp v136, v137 row_ror:1 row_mask:0xf bank_mask:0xf
	v_cndmask_b32_e64 v137, v160, v168, s[6:7]
	v_cndmask_b32_e64 v140, v161, v169, s[6:7]
	s_nop 0
	v_mov_b32_dpp v138, v137 row_ror:15 row_mask:0xf bank_mask:0xf
	v_cndmask_b32_e64 v141, v158, v166, s[6:7]
	v_mov_b32_dpp v137, v139 row_ror:1 row_mask:0xf bank_mask:0xf
	v_cndmask_b32_e64 v228, v159, v167, s[6:7]
	v_mov_b32_dpp v139, v140 row_ror:15 row_mask:0xf bank_mask:0xf
	v_cndmask_b32_e64 v140, v158, v2, s[8:9]
	v_cndmask_b32_e64 v229, v164, v172, s[6:7]
	s_nop 0
	v_mov_b32_dpp v142, v140 row_ror:1 row_mask:0xf bank_mask:0xf
	v_cndmask_b32_e64 v232, v165, v173, s[6:7]
	v_mov_b32_dpp v140, v141 row_ror:15 row_mask:0xf bank_mask:0xf
	v_cndmask_b32_e64 v141, v159, v3, s[8:9]
	v_cndmask_b32_e64 v233, v162, v170, s[6:7]
	s_nop 0
	v_mov_b32_dpp v143, v141 row_ror:1 row_mask:0xf bank_mask:0xf
	v_cndmask_b32_e64 v236, v163, v171, s[6:7]
	s_nop 0
	v_mov_b32_dpp v141, v228 row_ror:15 row_mask:0xf bank_mask:0xf
	v_cndmask_b32_e64 v228, v164, v4, s[8:9]
	s_nop 1
	v_mov_b32_dpp v230, v228 row_ror:1 row_mask:0xf bank_mask:0xf
	v_mov_b32_dpp v228, v229 row_ror:15 row_mask:0xf bank_mask:0xf
	v_cndmask_b32_e64 v229, v165, v5, s[8:9]
	s_nop 1
	v_mov_b32_dpp v231, v229 row_ror:1 row_mask:0xf bank_mask:0xf
	v_mov_b32_dpp v229, v232 row_ror:15 row_mask:0xf bank_mask:0xf
	v_cndmask_b32_e64 v232, v162, v6, s[8:9]
	s_nop 1
	v_mov_b32_dpp v234, v232 row_ror:1 row_mask:0xf bank_mask:0xf
	v_mov_b32_dpp v232, v233 row_ror:15 row_mask:0xf bank_mask:0xf
	v_cndmask_b32_e64 v233, v163, v7, s[8:9]
	s_nop 1
	v_mov_b32_dpp v235, v233 row_ror:1 row_mask:0xf bank_mask:0xf
	v_mov_b32_dpp v233, v236 row_ror:15 row_mask:0xf bank_mask:0xf
	s_and_saveexec_b64 s[0:1], s[20:21]
	s_cbranch_execz .LBB0_674
; __device__ __forceinline__ u32x2 pack4(f32x4 a) { u32x2 w; w.x = cvt_pk_bf16(a[0], a[1]); w.y = cvt_pk_bf16(a[2], a[3]); return w; }
; __device__ __forceinline__ float dpp_ror1(float v) { return __builtin_bit_cast(float, __builtin_amdgcn_update_dpp(0, __builtin_bit_cast(int, v), 0x121, 0xf, 0xf, false)); }
; __device__ __forceinline__ float dpp_ror15(float v) { return __builtin_bit_cast(float, __builtin_amdgcn_update_dpp(0, __builtin_bit_cast(int, v), 0x12F, 0xf, 0xf, false)); }
;     template <bool BND> __device__ __forceinline__ void conv_gate(f32x4 (&acc)[2][2][4][2], const Unit& u, int wr, int wc, int fr, int fq, int tok0, int pcol) const {
;     ...
;                 for (int m = 0; m < 4; ++m) {
;                     const int r = ai * 128 + wr * 64 + m * 16 + fr, tok = tok0 + r;
;                     bool isfirst = false, islast = false;
;                     if (BND) { const int S1 = (tok < NPROMPT ? SEQP : SEQS) - 1, pos = tok & S1; isfirst = pos == 0; islast = pos == S1; }
;                     f32x4 cv[2];
; #pragma unroll
;                     for (int bj = 0; bj < 2; ++bj) {
;                         const f32x4 cur = acc[ai][bj][m][n];
;                         const f32x4 ups = m > 0 ? acc[ai][bj][m > 0 ? m - 1 : 0][n] : pe[bj];
;                         const f32x4 dns = m < 3 ? acc[ai][bj][m < 3 ? m + 1 : 3][n] : ne[bj];
;                         f32x4 prev, next;
; #pragma unroll
;                         for (int j = 0; j < 4; ++j) {
;                             const float t1 = fr == 15 ? ups[j] : cur[j]; float pv = dpp_ror1(t1);
;                             const float t2 = fr == 0 ? dns[j] : cur[j]; float nx = dpp_ror15(t2);
;                             if (BND) { prev[j] = isfirst ? 0.f : pv; next[j] = islast ? 0.f : nx; } else { prev[j] = pv; next[j] = nx; }
;                         }
;                         cv[bj] = w0[bj] * prev + w1[bj] * cur + w2[bj] * next + bb[bj];
;                     }
;                     f32x4 a;
; #pragma unroll
;                     for (int j = 0; j < 4; ++j) { const float g = cv[0][j]; const float sg = __builtin_amdgcn_rcpf(1.0f + __builtin_amdgcn_exp2f(-1.4426950408889634f * g)); a[j] = g * sg * cv[1][j]; }
;                     if (r >= 1 && r <= 254 && (!BND || tok < MTOK)) *(u32x2*)(act + (size_t)tok * DFF + fcol + 4 * n) = pack4(a);
;                     asm volatile("" ::: "memory");
	s_waitcnt vmcnt(0)
	v_pk_mul_f32 v[142:143], v[98:99], v[142:143]
	v_pk_mul_f32 v[136:137], v[96:97], v[136:137]
	v_pk_fma_f32 v[142:143], v[158:159], v[106:107], v[142:143]
	v_pk_fma_f32 v[136:137], v[160:161], v[104:105], v[136:137]
	v_pk_fma_f32 v[140:141], v[110:111], v[140:141], v[142:143]
	v_pk_fma_f32 v[136:137], v[108:109], v[138:139], v[136:137]
	v_pk_add_f32 v[140:141], v[102:103], v[140:141]
	v_pk_add_f32 v[136:137], v[100:101], v[136:137]
	v_mul_f32_e32 v142, 0xbfb8aa3b, v141
	v_exp_f32_e32 v142, v142
	v_mul_f32_e32 v139, 0xbfb8aa3b, v140
	v_exp_f32_e32 v139, v139
	v_pk_mul_f32 v[234:235], v[126:127], v[234:235]
	v_add_f32_e32 v138, 1.0, v142
	v_rcp_f32_e32 v138, v138
	v_add_f32_e32 v139, 1.0, v139
	v_mul_f32_e32 v142, 0xbfb8aa3b, v136
	v_rcp_f32_e32 v139, v139
	v_mul_f32_e32 v138, v141, v138
	v_mul_f32_e32 v141, 0xbfb8aa3b, v137
	v_exp_f32_e32 v141, v141
	v_exp_f32_e32 v142, v142
	v_mul_f32_e32 v139, v140, v139
	v_pk_mul_f32 v[230:231], v[124:125], v[230:231]
	v_add_f32_e32 v140, 1.0, v141
	v_add_f32_e32 v141, 1.0, v142
	v_rcp_f32_e32 v140, v140
	v_rcp_f32_e32 v141, v141
	v_pk_fma_f32 v[234:235], v[162:163], v[122:123], v[234:235]
	v_pk_fma_f32 v[230:231], v[164:165], v[120:121], v[230:231]
	v_pk_fma_f32 v[232:233], v[118:119], v[232:233], v[234:235]
	v_pk_fma_f32 v[228:229], v[116:117], v[228:229], v[230:231]
	v_pk_add_f32 v[230:231], v[114:115], v[232:233]
	v_pk_add_f32 v[228:229], v[112:113], v[228:229]
	v_mul_f32_e32 v137, v137, v140
	v_mul_f32_e32 v136, v136, v141
	v_mul_f32_e32 v138, v138, v231
	v_mul_f32_e32 v139, v139, v230
	v_mul_f32_e32 v137, v137, v229
	v_mul_f32_e32 v136, v136, v228
	v_cvt_pk_bf16_f32 v136, v136, v137
	v_cvt_pk_bf16_f32 v137, v139, v138
	v_mov_b64_e32 v[138:139], s[88:89]
	s_movk_i32 s4, 0x1600
	v_mad_i64_i32 v[138:139], s[4:5], v248, s4, v[138:139]
	v_lshl_add_u64 v[138:139], v[190:191], 1, v[138:139]
	global_store_dwordx2 v[138:139], v[136:137], off offset:8
.LBB0_674:
	s_or_b64 exec, exec, s[0:1]
	v_cndmask_b32_e64 v137, v168, v160, s[8:9]
	v_cndmask_b32_e64 v139, v169, v161, s[8:9]
	s_nop 0
	v_mov_b32_dpp v136, v137 row_ror:1 row_mask:0xf bank_mask:0xf
	v_cndmask_b32_e64 v137, v168, v16, s[6:7]
	v_cndmask_b32_e64 v140, v169, v17, s[6:7]
	s_nop 0
	v_mov_b32_dpp v138, v137 row_ror:15 row_mask:0xf bank_mask:0xf
	v_cndmask_b32_e64 v141, v166, v18, s[6:7]
	v_mov_b32_dpp v137, v139 row_ror:1 row_mask:0xf bank_mask:0xf
	v_cndmask_b32_e64 v228, v167, v19, s[6:7]
	v_mov_b32_dpp v139, v140 row_ror:15 row_mask:0xf bank_mask:0xf
	v_cndmask_b32_e64 v140, v166, v158, s[8:9]
	v_cndmask_b32_e64 v229, v172, v20, s[6:7]
	s_nop 0
	v_mov_b32_dpp v142, v140 row_ror:1 row_mask:0xf bank_mask:0xf
	v_cndmask_b32_e64 v232, v173, v21, s[6:7]
	v_mov_b32_dpp v140, v141 row_ror:15 row_mask:0xf bank_mask:0xf
	v_cndmask_b32_e64 v141, v167, v159, s[8:9]
	v_cndmask_b32_e64 v233, v170, v22, s[6:7]
	s_nop 0
	v_mov_b32_dpp v143, v141 row_ror:1 row_mask:0xf bank_mask:0xf
	v_cndmask_b32_e64 v236, v171, v23, s[6:7]
	s_nop 0
	v_mov_b32_dpp v141, v228 row_ror:15 row_mask:0xf bank_mask:0xf
	v_cndmask_b32_e64 v228, v172, v164, s[8:9]
	s_nop 1
	v_mov_b32_dpp v230, v228 row_ror:1 row_mask:0xf bank_mask:0xf
	v_mov_b32_dpp v228, v229 row_ror:15 row_mask:0xf bank_mask:0xf
	v_cndmask_b32_e64 v229, v173, v165, s[8:9]
	s_nop 1
	v_mov_b32_dpp v231, v229 row_ror:1 row_mask:0xf bank_mask:0xf
	v_mov_b32_dpp v229, v232 row_ror:15 row_mask:0xf bank_mask:0xf
	v_cndmask_b32_e64 v232, v170, v162, s[8:9]
	s_nop 1
	v_mov_b32_dpp v234, v232 row_ror:1 row_mask:0xf bank_mask:0xf
	v_mov_b32_dpp v232, v233 row_ror:15 row_mask:0xf bank_mask:0xf
	v_cndmask_b32_e64 v233, v171, v163, s[8:9]
	s_nop 1
	v_mov_b32_dpp v235, v233 row_ror:1 row_mask:0xf bank_mask:0xf
	v_mov_b32_dpp v233, v236 row_ror:15 row_mask:0xf bank_mask:0xf
	s_and_saveexec_b64 s[0:1], s[22:23]
	s_cbranch_execz .LBB0_676
	s_waitcnt vmcnt(0)
	v_pk_mul_f32 v[142:143], v[98:99], v[142:143]
	v_pk_mul_f32 v[136:137], v[96:97], v[136:137]
	v_pk_fma_f32 v[142:143], v[166:167], v[106:107], v[142:143]
	v_pk_fma_f32 v[136:137], v[168:169], v[104:105], v[136:137]
	v_pk_fma_f32 v[140:141], v[110:111], v[140:141], v[142:143]
	v_pk_fma_f32 v[136:137], v[108:109], v[138:139], v[136:137]
	v_pk_add_f32 v[140:141], v[102:103], v[140:141]
	v_pk_add_f32 v[136:137], v[100:101], v[136:137]
	v_mul_f32_e32 v142, 0xbfb8aa3b, v141
	v_exp_f32_e32 v142, v142
	v_mul_f32_e32 v139, 0xbfb8aa3b, v140
	v_exp_f32_e32 v139, v139
	v_pk_mul_f32 v[234:235], v[126:127], v[234:235]
	v_add_f32_e32 v138, 1.0, v142
	v_rcp_f32_e32 v138, v138
	v_add_f32_e32 v139, 1.0, v139
	v_mul_f32_e32 v142, 0xbfb8aa3b, v136
	v_rcp_f32_e32 v139, v139
	v_mul_f32_e32 v138, v141, v138
	v_mul_f32_e32 v141, 0xbfb8aa3b, v137
	v_exp_f32_e32 v141, v141
	v_exp_f32_e32 v142, v142
	v_mul_f32_e32 v139, v140, v139
	v_pk_mul_f32 v[230:231], v[124:125], v[230:231]
	v_add_f32_e32 v140, 1.0, v141
	v_add_f32_e32 v141, 1.0, v142
	v_rcp_f32_e32 v140, v140
	v_rcp_f32_e32 v141, v141
	v_pk_fma_f32 v[234:235], v[170:171], v[122:123], v[234:235]
	v_pk_fma_f32 v[230:231], v[172:173], v[120:121], v[230:231]
	v_pk_fma_f32 v[232:233], v[118:119], v[232:233], v[234:235]
	v_pk_fma_f32 v[228:229], v[116:117], v[228:229], v[230:231]
	v_pk_add_f32 v[230:231], v[114:115], v[232:233]
	v_pk_add_f32 v[228:229], v[112:113], v[228:229]
	v_mul_f32_e32 v137, v137, v140
	v_mul_f32_e32 v136, v136, v141
	v_mul_f32_e32 v138, v138, v231
	v_mul_f32_e32 v139, v139, v230
	v_mul_f32_e32 v137, v137, v229
	v_mul_f32_e32 v136, v136, v228
	v_cvt_pk_bf16_f32 v136, v136, v137
	v_cvt_pk_bf16_f32 v137, v139, v138
	v_mov_b64_e32 v[138:139], s[88:89]
	s_movk_i32 s4, 0x1600
	v_mad_i64_i32 v[138:139], s[4:5], v249, s4, v[138:139]
	v_lshl_add_u64 v[138:139], v[190:191], 1, v[138:139]
	global_store_dwordx2 v[138:139], v[136:137], off offset:8
; __device__ __forceinline__ u32x2 pack4(f32x4 a) { u32x2 w; w.x = cvt_pk_bf16(a[0], a[1]); w.y = cvt_pk_bf16(a[2], a[3]); return w; }
; __device__ __forceinline__ float dpp_ror1(float v) { return __builtin_bit_cast(float, __builtin_amdgcn_update_dpp(0, __builtin_bit_cast(int, v), 0x121, 0xf, 0xf, false)); }
; __device__ __forceinline__ float dpp_ror15(float v) { return __builtin_bit_cast(float, __builtin_amdgcn_update_dpp(0, __builtin_bit_cast(int, v), 0x12F, 0xf, 0xf, false)); }
;     template <bool BND> __device__ __forceinline__ void conv_gate(f32x4 (&acc)[2][2][4][2], const Unit& u, int wr, int wc, int fr, int fq, int tok0, int pcol) const {
;     ...
;                 for (int m = 0; m < 4; ++m) {
;                     const int r = ai * 128 + wr * 64 + m * 16 + fr, tok = tok0 + r;
;                     bool isfirst = false, islast = false;
;                     if (BND) { const int S1 = (tok < NPROMPT ? SEQP : SEQS) - 1, pos = tok & S1; isfirst = pos == 0; islast = pos == S1; }
;                     f32x4 cv[2];
; #pragma unroll
;                     for (int bj = 0; bj < 2; ++bj) {
;                         const f32x4 cur = acc[ai][bj][m][n];
;                         const f32x4 ups = m > 0 ? acc[ai][bj][m > 0 ? m - 1 : 0][n] : pe[bj];
;                         const f32x4 dns = m < 3 ? acc[ai][bj][m < 3 ? m + 1 : 3][n] : ne[bj];
;                         f32x4 prev, next;
; #pragma unroll
;                         for (int j = 0; j < 4; ++j) {
;                             const float t1 = fr == 15 ? ups[j] : cur[j]; float pv = dpp_ror1(t1);
;                             const float t2 = fr == 0 ? dns[j] : cur[j]; float nx = dpp_ror15(t2);
;                             if (BND) { prev[j] = isfirst ? 0.f : pv; next[j] = islast ? 0.f : nx; } else { prev[j] = pv; next[j] = nx; }
;                         }
;                         cv[bj] = w0[bj] * prev + w1[bj] * cur + w2[bj] * next + bb[bj];
;                     }
;                     f32x4 a;
; #pragma unroll
;                     for (int j = 0; j < 4; ++j) { const float g = cv[0][j]; const float sg = __builtin_amdgcn_rcpf(1.0f + __builtin_amdgcn_exp2f(-1.4426950408889634f * g)); a[j] = g * sg * cv[1][j]; }
;                     if (r >= 1 && r <= 254 && (!BND || tok < MTOK)) *(u32x2*)(act + (size_t)tok * DFF + fcol + 4 * n) = pack4(a);
;                     asm volatile("" ::: "memory");
.LBB0_676:
	s_or_b64 exec, exec, s[0:1]
	v_cndmask_b32_e64 v137, v16, v168, s[8:9]
	v_cndmask_b32_e64 v138, v17, v169, s[8:9]
	v_cndmask_b32_e64 v139, v18, v166, s[8:9]
	v_mov_b32_dpp v136, v137 row_ror:1 row_mask:0xf bank_mask:0xf
	v_cndmask_b32_e64 v137, v16, v128, s[6:7]
	v_cndmask_b32_e64 v140, v19, v167, s[8:9]
	v_cndmask_b32_e64 v141, v20, v172, s[8:9]
	v_mov_b32_dpp v128, v137 row_ror:15 row_mask:0xf bank_mask:0xf
	v_cndmask_b32_e64 v142, v21, v173, s[8:9]
	v_cndmask_b32_e64 v143, v22, v170, s[8:9]
	v_mov_b32_dpp v137, v138 row_ror:1 row_mask:0xf bank_mask:0xf
	v_cndmask_b32_e64 v138, v17, v129, s[6:7]
	v_cndmask_b32_e64 v228, v23, v171, s[8:9]
	s_nop 0
	v_mov_b32_dpp v129, v138 row_ror:15 row_mask:0xf bank_mask:0xf
	v_mov_b32_dpp v138, v139 row_ror:1 row_mask:0xf bank_mask:0xf
	v_cndmask_b32_e64 v139, v18, v130, s[6:7]
	s_nop 1
	v_mov_b32_dpp v130, v139 row_ror:15 row_mask:0xf bank_mask:0xf
	v_mov_b32_dpp v139, v140 row_ror:1 row_mask:0xf bank_mask:0xf
	v_cndmask_b32_e64 v140, v19, v131, s[6:7]
	s_nop 1
	v_mov_b32_dpp v131, v140 row_ror:15 row_mask:0xf bank_mask:0xf
	v_mov_b32_dpp v140, v141 row_ror:1 row_mask:0xf bank_mask:0xf
	v_cndmask_b32_e64 v141, v20, v132, s[6:7]
	s_nop 1
	v_mov_b32_dpp v132, v141 row_ror:15 row_mask:0xf bank_mask:0xf
	v_mov_b32_dpp v141, v142 row_ror:1 row_mask:0xf bank_mask:0xf
	v_cndmask_b32_e64 v142, v21, v133, s[6:7]
	s_nop 1
	v_mov_b32_dpp v133, v142 row_ror:15 row_mask:0xf bank_mask:0xf
	v_mov_b32_dpp v142, v143 row_ror:1 row_mask:0xf bank_mask:0xf
	v_cndmask_b32_e64 v143, v22, v134, s[6:7]
	s_nop 1
	v_mov_b32_dpp v134, v143 row_ror:15 row_mask:0xf bank_mask:0xf
	v_mov_b32_dpp v143, v228 row_ror:1 row_mask:0xf bank_mask:0xf
	v_cndmask_b32_e64 v228, v23, v135, s[6:7]
	s_nop 1
	v_mov_b32_dpp v135, v228 row_ror:15 row_mask:0xf bank_mask:0xf
	s_and_saveexec_b64 s[0:1], s[24:25]
	s_cbranch_execz .LBB0_678
	s_waitcnt vmcnt(0)
	v_pk_mul_f32 v[138:139], v[98:99], v[138:139]
	v_pk_mul_f32 v[136:137], v[96:97], v[136:137]
	v_pk_fma_f32 v[138:139], v[18:19], v[106:107], v[138:139]
	v_pk_fma_f32 v[136:137], v[16:17], v[104:105], v[136:137]
	v_pk_fma_f32 v[130:131], v[110:111], v[130:131], v[138:139]
	v_pk_fma_f32 v[128:129], v[108:109], v[128:129], v[136:137]
	v_pk_add_f32 v[130:131], v[102:103], v[130:131]
	v_pk_mul_f32 v[142:143], v[126:127], v[142:143]
	v_mul_f32_e32 v138, 0xbfb8aa3b, v131
	v_exp_f32_e32 v138, v138
	v_mul_f32_e32 v137, 0xbfb8aa3b, v130
	v_exp_f32_e32 v137, v137
	v_pk_fma_f32 v[142:143], v[22:23], v[122:123], v[142:143]
	v_add_f32_e32 v136, 1.0, v138
	v_rcp_f32_e32 v136, v136
	v_pk_fma_f32 v[134:135], v[118:119], v[134:135], v[142:143]
	v_pk_add_f32 v[128:129], v[100:101], v[128:129]
	v_pk_add_f32 v[134:135], v[114:115], v[134:135]
	v_mul_f32_e32 v131, v131, v136
	v_mul_f32_e32 v131, v131, v135
	v_add_f32_e32 v135, 1.0, v137
	v_mul_f32_e32 v136, 0xbfb8aa3b, v129
	v_mul_f32_e32 v137, 0xbfb8aa3b, v128
	v_rcp_f32_e32 v135, v135
	v_exp_f32_e32 v136, v136
	v_exp_f32_e32 v137, v137
	v_pk_mul_f32 v[140:141], v[124:125], v[140:141]
	v_mul_f32_e32 v130, v130, v135
	v_add_f32_e32 v135, 1.0, v136
	v_add_f32_e32 v136, 1.0, v137
	v_rcp_f32_e32 v135, v135
	v_rcp_f32_e32 v136, v136
	v_pk_fma_f32 v[140:141], v[20:21], v[120:121], v[140:141]
	v_mul_f32_e32 v130, v130, v134
	v_pk_fma_f32 v[132:133], v[116:117], v[132:133], v[140:141]
	v_mul_f32_e32 v129, v129, v135
	v_pk_add_f32 v[132:133], v[112:113], v[132:133]
	v_mul_f32_e32 v128, v128, v136
	v_mul_f32_e32 v129, v129, v133
	v_mul_f32_e32 v128, v128, v132
	v_cvt_pk_bf16_f32 v128, v128, v129
	v_cvt_pk_bf16_f32 v129, v130, v131
	v_mov_b64_e32 v[130:131], s[88:89]
	s_movk_i32 s4, 0x1600
	v_mad_i64_i32 v[130:131], s[4:5], v250, s4, v[130:131]
	v_lshl_add_u64 v[130:131], v[190:191], 1, v[130:131]
	global_store_dwordx2 v[130:131], v[128:129], off offset:8

; __device__ __forceinline__ u32x2 pack4(f32x4 a) { u32x2 w; w.x = cvt_pk_bf16(a[0], a[1]); w.y = cvt_pk_bf16(a[2], a[3]); return w; }
; __device__ __forceinline__ float dpp_ror1(float v) { return __builtin_bit_cast(float, __builtin_amdgcn_update_dpp(0, __builtin_bit_cast(int, v), 0x121, 0xf, 0xf, false)); }
; __device__ __forceinline__ float dpp_ror15(float v) { return __builtin_bit_cast(float, __builtin_amdgcn_update_dpp(0, __builtin_bit_cast(int, v), 0x12F, 0xf, 0xf, false)); }
;     template <bool BND> __device__ __forceinline__ void conv_gate(f32x4 (&acc)[2][2][4][2], const Unit& u, int wr, int wc, int fr, int fq, int tok0, int pcol) const {
;     ...
;                 for (int m = 0; m < 4; ++m) {
;                     const int r = ai * 128 + wr * 64 + m * 16 + fr, tok = tok0 + r;
;                     bool isfirst = false, islast = false;
;                     if (BND) { const int S1 = (tok < NPROMPT ? SEQP : SEQS) - 1, pos = tok & S1; isfirst = pos == 0; islast = pos == S1; }
;                     f32x4 cv[2];
; #pragma unroll
;                     for (int bj = 0; bj < 2; ++bj) {
;                         const f32x4 cur = acc[ai][bj][m][n];
;                         const f32x4 ups = m > 0 ? acc[ai][bj][m > 0 ? m - 1 : 0][n] : pe[bj];
;                         const f32x4 dns = m < 3 ? acc[ai][bj][m < 3 ? m + 1 : 3][n] : ne[bj];
;                         f32x4 prev, next;
; #pragma unroll
;                         for (int j = 0; j < 4; ++j) {
;                             const float t1 = fr == 15 ? ups[j] : cur[j]; float pv = dpp_ror1(t1);
;                             const float t2 = fr == 0 ? dns[j] : cur[j]; float nx = dpp_ror15(t2);
;                             if (BND) { prev[j] = isfirst ? 0.f : pv; next[j] = islast ? 0.f : nx; } else { prev[j] = pv; next[j] = nx; }
;                         }
;                         cv[bj] = w0[bj] * prev + w1[bj] * cur + w2[bj] * next + bb[bj];
;                     }
;                     f32x4 a;
; #pragma unroll
;                     for (int j = 0; j < 4; ++j) { const float g = cv[0][j]; const float sg = __builtin_amdgcn_rcpf(1.0f + __builtin_amdgcn_exp2f(-1.4426950408889634f * g)); a[j] = g * sg * cv[1][j]; }
;                     if (r >= 1 && r <= 254 && (!BND || tok < MTOK)) *(u32x2*)(act + (size_t)tok * DFF + fcol + 4 * n) = pack4(a);
;                     asm volatile("" ::: "memory");
.LBB0_686:
	s_waitcnt lgkmcnt(0)
	v_cndmask_b32_e64 v228, v8, v136, s[8:9]
	v_cndmask_b32_e64 v229, v8, v176, s[6:7]
	v_cndmask_b32_e64 v230, v9, v177, s[6:7]
	v_mov_b32_dpp v136, v228 row_ror:1 row_mask:0xf bank_mask:0xf
	v_cndmask_b32_e64 v138, v10, v138, s[8:9]
	v_cndmask_b32_e64 v231, v10, v174, s[6:7]
	v_mov_b32_dpp v228, v229 row_ror:15 row_mask:0xf bank_mask:0xf
	v_cndmask_b32_e64 v229, v9, v137, s[8:9]
	v_cndmask_b32_e64 v139, v11, v139, s[8:9]
	v_cndmask_b32_e64 v232, v11, v175, s[6:7]
	v_mov_b32_dpp v137, v229 row_ror:1 row_mask:0xf bank_mask:0xf
	v_cndmask_b32_e64 v140, v12, v140, s[8:9]
	v_cndmask_b32_e64 v233, v12, v180, s[6:7]
	v_mov_b32_dpp v229, v230 row_ror:15 row_mask:0xf bank_mask:0xf
	v_cndmask_b32_e64 v141, v13, v141, s[8:9]
	v_cndmask_b32_e64 v234, v13, v181, s[6:7]
	v_mov_b32_dpp v230, v138 row_ror:1 row_mask:0xf bank_mask:0xf
	v_cndmask_b32_e64 v142, v14, v142, s[8:9]
	v_cndmask_b32_e64 v235, v14, v178, s[6:7]
	v_mov_b32_dpp v138, v231 row_ror:15 row_mask:0xf bank_mask:0xf
	v_cndmask_b32_e64 v143, v15, v143, s[8:9]
	v_cndmask_b32_e64 v236, v15, v179, s[6:7]
	v_mov_b32_dpp v231, v139 row_ror:1 row_mask:0xf bank_mask:0xf
	v_mov_b32_dpp v139, v232 row_ror:15 row_mask:0xf bank_mask:0xf
	v_mov_b32_dpp v232, v140 row_ror:1 row_mask:0xf bank_mask:0xf
	v_mov_b32_dpp v140, v233 row_ror:15 row_mask:0xf bank_mask:0xf
	v_mov_b32_dpp v233, v141 row_ror:1 row_mask:0xf bank_mask:0xf
	v_mov_b32_dpp v141, v234 row_ror:15 row_mask:0xf bank_mask:0xf
	v_mov_b32_dpp v234, v142 row_ror:1 row_mask:0xf bank_mask:0xf
	v_mov_b32_dpp v142, v235 row_ror:15 row_mask:0xf bank_mask:0xf
	v_mov_b32_dpp v235, v143 row_ror:1 row_mask:0xf bank_mask:0xf
	v_mov_b32_dpp v143, v236 row_ror:15 row_mask:0xf bank_mask:0xf
	s_and_saveexec_b64 s[0:1], s[26:27]
	s_cbranch_execz .LBB0_688
	s_waitcnt vmcnt(0)
	v_pk_mul_f32 v[230:231], v[98:99], v[230:231]
	v_pk_mul_f32 v[136:137], v[96:97], v[136:137]
	v_pk_fma_f32 v[230:231], v[10:11], v[106:107], v[230:231]
	v_pk_fma_f32 v[136:137], v[8:9], v[104:105], v[136:137]
	v_pk_fma_f32 v[138:139], v[110:111], v[138:139], v[230:231]
	v_pk_fma_f32 v[136:137], v[108:109], v[228:229], v[136:137]
	v_pk_add_f32 v[138:139], v[102:103], v[138:139]
	v_pk_mul_f32 v[234:235], v[126:127], v[234:235]
	v_mul_f32_e32 v230, 0xbfb8aa3b, v139
	v_exp_f32_e32 v230, v230
	v_mul_f32_e32 v229, 0xbfb8aa3b, v138
	v_exp_f32_e32 v229, v229
	v_pk_fma_f32 v[234:235], v[14:15], v[122:123], v[234:235]
	v_add_f32_e32 v228, 1.0, v230
	v_rcp_f32_e32 v228, v228
	v_pk_fma_f32 v[142:143], v[118:119], v[142:143], v[234:235]
	v_pk_add_f32 v[136:137], v[100:101], v[136:137]
	v_pk_add_f32 v[142:143], v[114:115], v[142:143]
	v_mul_f32_e32 v139, v139, v228
	v_mul_f32_e32 v139, v139, v143
	v_add_f32_e32 v143, 1.0, v229
	v_mul_f32_e32 v228, 0xbfb8aa3b, v137
	v_mul_f32_e32 v229, 0xbfb8aa3b, v136
	v_rcp_f32_e32 v143, v143
	v_exp_f32_e32 v228, v228
	v_exp_f32_e32 v229, v229
	v_pk_mul_f32 v[232:233], v[124:125], v[232:233]
	v_mul_f32_e32 v138, v138, v143
	v_add_f32_e32 v143, 1.0, v228
	v_add_f32_e32 v228, 1.0, v229
	v_rcp_f32_e32 v143, v143
	v_rcp_f32_e32 v228, v228
	v_pk_fma_f32 v[232:233], v[12:13], v[120:121], v[232:233]
	v_mul_f32_e32 v138, v138, v142
	v_pk_fma_f32 v[140:141], v[116:117], v[140:141], v[232:233]
	v_mul_f32_e32 v137, v137, v143
	v_pk_add_f32 v[140:141], v[112:113], v[140:141]
	v_mul_f32_e32 v136, v136, v228
	v_mul_f32_e32 v137, v137, v141
	v_mul_f32_e32 v136, v136, v140
	v_cvt_pk_bf16_f32 v136, v136, v137
	v_cvt_pk_bf16_f32 v137, v138, v139
	v_mov_b64_e32 v[138:139], s[88:89]
	s_movk_i32 s4, 0x1600
	v_mad_i64_i32 v[138:139], s[4:5], v251, s4, v[138:139]
	v_lshl_add_u64 v[138:139], v[190:191], 1, v[138:139]
	global_store_dwordx2 v[138:139], v[136:137], off offset:8
.LBB0_688:
	s_or_b64 exec, exec, s[0:1]
	v_cndmask_b32_e64 v137, v176, v8, s[8:9]
	v_cndmask_b32_e64 v139, v177, v9, s[8:9]
	s_nop 0
	v_mov_b32_dpp v136, v137 row_ror:1 row_mask:0xf bank_mask:0xf
	v_cndmask_b32_e64 v137, v176, v184, s[6:7]
	v_cndmask_b32_e64 v140, v177, v185, s[6:7]
	s_nop 0
	v_mov_b32_dpp v138, v137 row_ror:15 row_mask:0xf bank_mask:0xf
	v_cndmask_b32_e64 v141, v174, v182, s[6:7]
	v_mov_b32_dpp v137, v139 row_ror:1 row_mask:0xf bank_mask:0xf
	v_cndmask_b32_e64 v228, v175, v183, s[6:7]
	v_mov_b32_dpp v139, v140 row_ror:15 row_mask:0xf bank_mask:0xf
	v_cndmask_b32_e64 v140, v174, v10, s[8:9]
	v_cndmask_b32_e64 v229, v180, v188, s[6:7]
	s_nop 0
	v_mov_b32_dpp v142, v140 row_ror:1 row_mask:0xf bank_mask:0xf
	v_cndmask_b32_e64 v232, v181, v189, s[6:7]
	v_mov_b32_dpp v140, v141 row_ror:15 row_mask:0xf bank_mask:0xf
	v_cndmask_b32_e64 v141, v175, v11, s[8:9]
	v_cndmask_b32_e64 v233, v178, v186, s[6:7]
	s_nop 0
	v_mov_b32_dpp v143, v141 row_ror:1 row_mask:0xf bank_mask:0xf
	v_cndmask_b32_e64 v236, v179, v187, s[6:7]
	s_nop 0
	v_mov_b32_dpp v141, v228 row_ror:15 row_mask:0xf bank_mask:0xf
	v_cndmask_b32_e64 v228, v180, v12, s[8:9]
	s_nop 1
	v_mov_b32_dpp v230, v228 row_ror:1 row_mask:0xf bank_mask:0xf
	v_mov_b32_dpp v228, v229 row_ror:15 row_mask:0xf bank_mask:0xf
	v_cndmask_b32_e64 v229, v181, v13, s[8:9]
	s_nop 1
	v_mov_b32_dpp v231, v229 row_ror:1 row_mask:0xf bank_mask:0xf
	v_mov_b32_dpp v229, v232 row_ror:15 row_mask:0xf bank_mask:0xf
	v_cndmask_b32_e64 v232, v178, v14, s[8:9]
	s_nop 1
	v_mov_b32_dpp v234, v232 row_ror:1 row_mask:0xf bank_mask:0xf
	v_mov_b32_dpp v232, v233 row_ror:15 row_mask:0xf bank_mask:0xf
	v_cndmask_b32_e64 v233, v179, v15, s[8:9]
	s_nop 1
	v_mov_b32_dpp v235, v233 row_ror:1 row_mask:0xf bank_mask:0xf
	v_mov_b32_dpp v233, v236 row_ror:15 row_mask:0xf bank_mask:0xf
	s_and_saveexec_b64 s[0:1], s[28:29]
	s_cbranch_execz .LBB0_690
; __device__ __forceinline__ u32x2 pack4(f32x4 a) { u32x2 w; w.x = cvt_pk_bf16(a[0], a[1]); w.y = cvt_pk_bf16(a[2], a[3]); return w; }
; __device__ __forceinline__ float dpp_ror1(float v) { return __builtin_bit_cast(float, __builtin_amdgcn_update_dpp(0, __builtin_bit_cast(int, v), 0x121, 0xf, 0xf, false)); }
; __device__ __forceinline__ float dpp_ror15(float v) { return __builtin_bit_cast(float, __builtin_amdgcn_update_dpp(0, __builtin_bit_cast(int, v), 0x12F, 0xf, 0xf, false)); }
;     template <bool BND> __device__ __forceinline__ void conv_gate(f32x4 (&acc)[2][2][4][2], const Unit& u, int wr, int wc, int fr, int fq, int tok0, int pcol) const {
;     ...
;                 for (int m = 0; m < 4; ++m) {
;                     const int r = ai * 128 + wr * 64 + m * 16 + fr, tok = tok0 + r;
;                     bool isfirst = false, islast = false;
;                     if (BND) { const int S1 = (tok < NPROMPT ? SEQP : SEQS) - 1, pos = tok & S1; isfirst = pos == 0; islast = pos == S1; }
;                     f32x4 cv[2];
; #pragma unroll
;                     for (int bj = 0; bj < 2; ++bj) {
;                         const f32x4 cur = acc[ai][bj][m][n];
;                         const f32x4 ups = m > 0 ? acc[ai][bj][m > 0 ? m - 1 : 0][n] : pe[bj];
;                         const f32x4 dns = m < 3 ? acc[ai][bj][m < 3 ? m + 1 : 3][n] : ne[bj];
;                         f32x4 prev, next;
; #pragma unroll
;                         for (int j = 0; j < 4; ++j) {
;                             const float t1 = fr == 15 ? ups[j] : cur[j]; float pv = dpp_ror1(t1);
;                             const float t2 = fr == 0 ? dns[j] : cur[j]; float nx = dpp_ror15(t2);
;                             if (BND) { prev[j] = isfirst ? 0.f : pv; next[j] = islast ? 0.f : nx; } else { prev[j] = pv; next[j] = nx; }
;                         }
;                         cv[bj] = w0[bj] * prev + w1[bj] * cur + w2[bj] * next + bb[bj];
;                     }
;                     f32x4 a;
; #pragma unroll
;                     for (int j = 0; j < 4; ++j) { const float g = cv[0][j]; const float sg = __builtin_amdgcn_rcpf(1.0f + __builtin_amdgcn_exp2f(-1.4426950408889634f * g)); a[j] = g * sg * cv[1][j]; }
;                     if (r >= 1 && r <= 254 && (!BND || tok < MTOK)) *(u32x2*)(act + (size_t)tok * DFF + fcol + 4 * n) = pack4(a);
;                     asm volatile("" ::: "memory");
	s_waitcnt vmcnt(0)
	v_pk_mul_f32 v[142:143], v[98:99], v[142:143]
	v_pk_mul_f32 v[136:137], v[96:97], v[136:137]
	v_pk_fma_f32 v[142:143], v[174:175], v[106:107], v[142:143]
	v_pk_fma_f32 v[136:137], v[176:177], v[104:105], v[136:137]
	v_pk_fma_f32 v[140:141], v[110:111], v[140:141], v[142:143]
	v_pk_fma_f32 v[136:137], v[108:109], v[138:139], v[136:137]
	v_pk_add_f32 v[140:141], v[102:103], v[140:141]
	v_pk_add_f32 v[136:137], v[100:101], v[136:137]
	v_mul_f32_e32 v142, 0xbfb8aa3b, v141
	v_exp_f32_e32 v142, v142
	v_mul_f32_e32 v139, 0xbfb8aa3b, v140
	v_exp_f32_e32 v139, v139
	v_pk_mul_f32 v[234:235], v[126:127], v[234:235]
	v_add_f32_e32 v138, 1.0, v142
	v_rcp_f32_e32 v138, v138
	v_add_f32_e32 v139, 1.0, v139
	v_mul_f32_e32 v142, 0xbfb8aa3b, v136
	v_rcp_f32_e32 v139, v139
	v_mul_f32_e32 v138, v141, v138
	v_mul_f32_e32 v141, 0xbfb8aa3b, v137
	v_exp_f32_e32 v141, v141
	v_exp_f32_e32 v142, v142
	v_mul_f32_e32 v139, v140, v139
	v_pk_mul_f32 v[230:231], v[124:125], v[230:231]
	v_add_f32_e32 v140, 1.0, v141
	v_add_f32_e32 v141, 1.0, v142
	v_rcp_f32_e32 v140, v140
	v_rcp_f32_e32 v141, v141
	v_pk_fma_f32 v[234:235], v[178:179], v[122:123], v[234:235]
	v_pk_fma_f32 v[230:231], v[180:181], v[120:121], v[230:231]
	v_pk_fma_f32 v[232:233], v[118:119], v[232:233], v[234:235]
	v_pk_fma_f32 v[228:229], v[116:117], v[228:229], v[230:231]
	v_pk_add_f32 v[230:231], v[114:115], v[232:233]
	v_pk_add_f32 v[228:229], v[112:113], v[228:229]
	v_mul_f32_e32 v137, v137, v140
	v_mul_f32_e32 v136, v136, v141
	v_mul_f32_e32 v138, v138, v231
	v_mul_f32_e32 v139, v139, v230
	v_mul_f32_e32 v137, v137, v229
	v_mul_f32_e32 v136, v136, v228
	v_cvt_pk_bf16_f32 v136, v136, v137
	v_cvt_pk_bf16_f32 v137, v139, v138
	v_mov_b64_e32 v[138:139], s[88:89]
	s_movk_i32 s4, 0x1600
	v_mad_i64_i32 v[138:139], s[4:5], v252, s4, v[138:139]
	v_lshl_add_u64 v[138:139], v[190:191], 1, v[138:139]
	global_store_dwordx2 v[138:139], v[136:137], off offset:8
.LBB0_690:
	s_or_b64 exec, exec, s[0:1]
	v_cndmask_b32_e64 v137, v184, v176, s[8:9]
	v_cndmask_b32_e64 v139, v185, v177, s[8:9]
	s_nop 0
	v_mov_b32_dpp v136, v137 row_ror:1 row_mask:0xf bank_mask:0xf
	v_cndmask_b32_e64 v137, v184, v24, s[6:7]
	v_cndmask_b32_e64 v140, v185, v25, s[6:7]
	s_nop 0
	v_mov_b32_dpp v138, v137 row_ror:15 row_mask:0xf bank_mask:0xf
	v_cndmask_b32_e64 v141, v182, v26, s[6:7]
	v_mov_b32_dpp v137, v139 row_ror:1 row_mask:0xf bank_mask:0xf
	v_cndmask_b32_e64 v228, v183, v27, s[6:7]
	v_mov_b32_dpp v139, v140 row_ror:15 row_mask:0xf bank_mask:0xf
	v_cndmask_b32_e64 v140, v182, v174, s[8:9]
	v_cndmask_b32_e64 v229, v188, v28, s[6:7]
	s_nop 0
	v_mov_b32_dpp v142, v140 row_ror:1 row_mask:0xf bank_mask:0xf
	v_cndmask_b32_e64 v232, v189, v29, s[6:7]
	v_mov_b32_dpp v140, v141 row_ror:15 row_mask:0xf bank_mask:0xf
	v_cndmask_b32_e64 v141, v183, v175, s[8:9]
	v_cndmask_b32_e64 v233, v186, v30, s[6:7]
	s_nop 0
	v_mov_b32_dpp v143, v141 row_ror:1 row_mask:0xf bank_mask:0xf
	v_cndmask_b32_e64 v236, v187, v31, s[6:7]
	s_nop 0
	v_mov_b32_dpp v141, v228 row_ror:15 row_mask:0xf bank_mask:0xf
	v_cndmask_b32_e64 v228, v188, v180, s[8:9]
	s_nop 1
	v_mov_b32_dpp v230, v228 row_ror:1 row_mask:0xf bank_mask:0xf
	v_mov_b32_dpp v228, v229 row_ror:15 row_mask:0xf bank_mask:0xf
	v_cndmask_b32_e64 v229, v189, v181, s[8:9]
	s_nop 1
	v_mov_b32_dpp v231, v229 row_ror:1 row_mask:0xf bank_mask:0xf
	v_mov_b32_dpp v229, v232 row_ror:15 row_mask:0xf bank_mask:0xf
	v_cndmask_b32_e64 v232, v186, v178, s[8:9]
	s_nop 1
	v_mov_b32_dpp v234, v232 row_ror:1 row_mask:0xf bank_mask:0xf
	v_mov_b32_dpp v232, v233 row_ror:15 row_mask:0xf bank_mask:0xf
	v_cndmask_b32_e64 v233, v187, v179, s[8:9]
	s_nop 1
	v_mov_b32_dpp v235, v233 row_ror:1 row_mask:0xf bank_mask:0xf
	v_mov_b32_dpp v233, v236 row_ror:15 row_mask:0xf bank_mask:0xf
	s_mov_b64 s[0:1], exec
	s_and_b64 s[4:5], s[0:1], s[30:31]
	v_mov_b32_e32 v236, v237
	v_mov_b32_e32 v237, v243
	v_mov_b32_e32 v243, v244
	v_mov_b32_e32 v244, 0xfff
	s_mov_b64 exec, s[4:5]
	s_cbranch_execz .LBB0_692
	s_waitcnt vmcnt(0)
	v_pk_mul_f32 v[142:143], v[98:99], v[142:143]
	v_pk_mul_f32 v[136:137], v[96:97], v[136:137]
	v_pk_fma_f32 v[142:143], v[182:183], v[106:107], v[142:143]
	v_pk_fma_f32 v[136:137], v[184:185], v[104:105], v[136:137]
	v_pk_fma_f32 v[140:141], v[110:111], v[140:141], v[142:143]
	v_pk_fma_f32 v[136:137], v[108:109], v[138:139], v[136:137]
	v_pk_add_f32 v[140:141], v[102:103], v[140:141]
	v_pk_add_f32 v[136:137], v[100:101], v[136:137]
	v_mul_f32_e32 v142, 0xbfb8aa3b, v141
	v_exp_f32_e32 v142, v142
	v_mul_f32_e32 v139, 0xbfb8aa3b, v140
	v_exp_f32_e32 v139, v139
	v_pk_mul_f32 v[234:235], v[126:127], v[234:235]
	v_add_f32_e32 v138, 1.0, v142
	v_rcp_f32_e32 v138, v138
	v_add_f32_e32 v139, 1.0, v139
	v_mul_f32_e32 v142, 0xbfb8aa3b, v136
	v_rcp_f32_e32 v139, v139
	v_mul_f32_e32 v138, v141, v138
	v_mul_f32_e32 v141, 0xbfb8aa3b, v137
	v_exp_f32_e32 v141, v141
	v_exp_f32_e32 v142, v142
	v_mul_f32_e32 v139, v140, v139
	v_pk_mul_f32 v[230:231], v[124:125], v[230:231]
	v_add_f32_e32 v140, 1.0, v141
	v_add_f32_e32 v141, 1.0, v142
	v_rcp_f32_e32 v140, v140
	v_rcp_f32_e32 v141, v141
	v_pk_fma_f32 v[234:235], v[186:187], v[122:123], v[234:235]
	v_pk_fma_f32 v[230:231], v[188:189], v[120:121], v[230:231]
	v_pk_fma_f32 v[232:233], v[118:119], v[232:233], v[234:235]
	v_pk_fma_f32 v[228:229], v[116:117], v[228:229], v[230:231]
	v_pk_add_f32 v[230:231], v[114:115], v[232:233]
	v_pk_add_f32 v[228:229], v[112:113], v[228:229]
	v_mul_f32_e32 v137, v137, v140
	v_mul_f32_e32 v136, v136, v141
	v_mul_f32_e32 v138, v138, v231
	v_mul_f32_e32 v139, v139, v230
	v_mul_f32_e32 v137, v137, v229
	v_mul_f32_e32 v136, v136, v228
	v_cvt_pk_bf16_f32 v136, v136, v137
	v_cvt_pk_bf16_f32 v137, v139, v138
	v_mov_b64_e32 v[138:139], s[88:89]
	s_movk_i32 s4, 0x1600
	v_mad_i64_i32 v[138:139], s[4:5], v253, s4, v[138:139]
	v_lshl_add_u64 v[138:139], v[190:191], 1, v[138:139]
	global_store_dwordx2 v[138:139], v[136:137], off offset:8
; __device__ __forceinline__ u32x2 pack4(f32x4 a) { u32x2 w; w.x = cvt_pk_bf16(a[0], a[1]); w.y = cvt_pk_bf16(a[2], a[3]); return w; }
; __device__ __forceinline__ float dpp_ror1(float v) { return __builtin_bit_cast(float, __builtin_amdgcn_update_dpp(0, __builtin_bit_cast(int, v), 0x121, 0xf, 0xf, false)); }
; __device__ __forceinline__ float dpp_ror15(float v) { return __builtin_bit_cast(float, __builtin_amdgcn_update_dpp(0, __builtin_bit_cast(int, v), 0x12F, 0xf, 0xf, false)); }
;     template <bool BND> __device__ __forceinline__ void conv_gate(f32x4 (&acc)[2][2][4][2], const Unit& u, int wr, int wc, int fr, int fq, int tok0, int pcol) const {
;     ...
;                 for (int m = 0; m < 4; ++m) {
;                     const int r = ai * 128 + wr * 64 + m * 16 + fr, tok = tok0 + r;
;                     bool isfirst = false, islast = false;
;                     if (BND) { const int S1 = (tok < NPROMPT ? SEQP : SEQS) - 1, pos = tok & S1; isfirst = pos == 0; islast = pos == S1; }
;                     f32x4 cv[2];
; #pragma unroll
;                     for (int bj = 0; bj < 2; ++bj) {
;                         const f32x4 cur = acc[ai][bj][m][n];
;                         const f32x4 ups = m > 0 ? acc[ai][bj][m > 0 ? m - 1 : 0][n] : pe[bj];
;                         const f32x4 dns = m < 3 ? acc[ai][bj][m < 3 ? m + 1 : 3][n] : ne[bj];
;                         f32x4 prev, next;
; #pragma unroll
;                         for (int j = 0; j < 4; ++j) {
;                             const float t1 = fr == 15 ? ups[j] : cur[j]; float pv = dpp_ror1(t1);
;                             const float t2 = fr == 0 ? dns[j] : cur[j]; float nx = dpp_ror15(t2);
;                             if (BND) { prev[j] = isfirst ? 0.f : pv; next[j] = islast ? 0.f : nx; } else { prev[j] = pv; next[j] = nx; }
;                         }
;                         cv[bj] = w0[bj] * prev + w1[bj] * cur + w2[bj] * next + bb[bj];
;                     }
;                     f32x4 a;
; #pragma unroll
;                     for (int j = 0; j < 4; ++j) { const float g = cv[0][j]; const float sg = __builtin_amdgcn_rcpf(1.0f + __builtin_amdgcn_exp2f(-1.4426950408889634f * g)); a[j] = g * sg * cv[1][j]; }
;                     if (r >= 1 && r <= 254 && (!BND || tok < MTOK)) *(u32x2*)(act + (size_t)tok * DFF + fcol + 4 * n) = pack4(a);
;                     asm volatile("" ::: "memory");
.LBB0_692:
	s_or_b64 exec, exec, s[0:1]
	v_cndmask_b32_e64 v137, v24, v184, s[8:9]
	v_cndmask_b32_e64 v138, v25, v185, s[8:9]
	v_cndmask_b32_e64 v139, v26, v182, s[8:9]
	v_mov_b32_dpp v136, v137 row_ror:1 row_mask:0xf bank_mask:0xf
	v_cndmask_b32_e64 v137, v24, v128, s[6:7]
	v_cndmask_b32_e64 v140, v27, v183, s[8:9]
	v_cndmask_b32_e64 v141, v28, v188, s[8:9]
	v_mov_b32_dpp v128, v137 row_ror:15 row_mask:0xf bank_mask:0xf
	v_cndmask_b32_e64 v142, v29, v189, s[8:9]
	v_cndmask_b32_e64 v143, v30, v186, s[8:9]
	v_mov_b32_dpp v137, v138 row_ror:1 row_mask:0xf bank_mask:0xf
	v_cndmask_b32_e64 v138, v25, v129, s[6:7]
	v_cndmask_b32_e64 v228, v31, v187, s[8:9]
	s_nop 0
	v_mov_b32_dpp v129, v138 row_ror:15 row_mask:0xf bank_mask:0xf
	v_mov_b32_dpp v138, v139 row_ror:1 row_mask:0xf bank_mask:0xf
	v_cndmask_b32_e64 v139, v26, v130, s[6:7]
	s_nop 1
	v_mov_b32_dpp v130, v139 row_ror:15 row_mask:0xf bank_mask:0xf
	v_mov_b32_dpp v139, v140 row_ror:1 row_mask:0xf bank_mask:0xf
	v_cndmask_b32_e64 v140, v27, v131, s[6:7]
	s_nop 1
	v_mov_b32_dpp v131, v140 row_ror:15 row_mask:0xf bank_mask:0xf
	v_mov_b32_dpp v140, v141 row_ror:1 row_mask:0xf bank_mask:0xf
	v_cndmask_b32_e64 v141, v28, v132, s[6:7]
	s_nop 1
	v_mov_b32_dpp v132, v141 row_ror:15 row_mask:0xf bank_mask:0xf
	v_mov_b32_dpp v141, v142 row_ror:1 row_mask:0xf bank_mask:0xf
	v_cndmask_b32_e64 v142, v29, v133, s[6:7]
	s_nop 1
	v_mov_b32_dpp v133, v142 row_ror:15 row_mask:0xf bank_mask:0xf
	v_mov_b32_dpp v142, v143 row_ror:1 row_mask:0xf bank_mask:0xf
	v_cndmask_b32_e64 v143, v30, v134, s[6:7]
	s_nop 1
	v_mov_b32_dpp v134, v143 row_ror:15 row_mask:0xf bank_mask:0xf
	v_mov_b32_dpp v143, v228 row_ror:1 row_mask:0xf bank_mask:0xf
	v_cndmask_b32_e64 v228, v31, v135, s[6:7]
	s_nop 1
	v_mov_b32_dpp v135, v228 row_ror:15 row_mask:0xf bank_mask:0xf
	s_and_saveexec_b64 s[0:1], s[34:35]
	s_cbranch_execz .LBB0_694
	s_waitcnt vmcnt(0)
	v_pk_mul_f32 v[98:99], v[98:99], v[138:139]
	v_pk_mul_f32 v[96:97], v[96:97], v[136:137]
	v_pk_fma_f32 v[98:99], v[26:27], v[106:107], v[98:99]
	v_pk_fma_f32 v[96:97], v[24:25], v[104:105], v[96:97]
	v_pk_fma_f32 v[98:99], v[110:111], v[130:131], v[98:99]
	v_pk_fma_f32 v[96:97], v[108:109], v[128:129], v[96:97]
	v_pk_add_f32 v[98:99], v[102:103], v[98:99]
	v_pk_add_f32 v[96:97], v[100:101], v[96:97]
	v_mul_f32_e32 v102, 0xbfb8aa3b, v99
	v_exp_f32_e32 v102, v102
	v_mul_f32_e32 v103, 0xbfb8aa3b, v98
	v_exp_f32_e32 v103, v103
	v_mul_f32_e32 v101, 0xbfb8aa3b, v97
	v_add_f32_e32 v102, 1.0, v102
	v_rcp_f32_e32 v102, v102
	v_add_f32_e32 v100, 1.0, v103
	v_rcp_f32_e32 v100, v100
	v_exp_f32_e32 v101, v101
	v_mul_f32_e32 v99, v99, v102
	v_mul_f32_e32 v102, 0xbfb8aa3b, v96
	v_exp_f32_e32 v102, v102
	v_mul_f32_e32 v98, v98, v100
	v_add_f32_e32 v100, 1.0, v101
	v_rcp_f32_e32 v100, v100
	v_add_f32_e32 v101, 1.0, v102
	v_rcp_f32_e32 v101, v101
	v_pk_mul_f32 v[126:127], v[126:127], v[142:143]
	v_pk_mul_f32 v[124:125], v[124:125], v[140:141]
	v_pk_fma_f32 v[122:123], v[30:31], v[122:123], v[126:127]
	v_pk_fma_f32 v[120:121], v[28:29], v[120:121], v[124:125]
	v_pk_fma_f32 v[118:119], v[118:119], v[134:135], v[122:123]
	v_pk_fma_f32 v[116:117], v[116:117], v[132:133], v[120:121]
	v_pk_add_f32 v[114:115], v[114:115], v[118:119]
	v_pk_add_f32 v[112:113], v[112:113], v[116:117]
	v_mul_f32_e32 v97, v97, v100
	v_mul_f32_e32 v96, v96, v101
	v_mul_f32_e32 v99, v99, v115
	v_mul_f32_e32 v98, v98, v114
	v_mul_f32_e32 v97, v97, v113
	v_mul_f32_e32 v96, v96, v112
	v_cvt_pk_bf16_f32 v96, v96, v97
	v_cvt_pk_bf16_f32 v97, v98, v99
	v_mov_b64_e32 v[98:99], s[88:89]
	s_movk_i32 s4, 0x1600
	v_mad_i64_i32 v[98:99], s[4:5], v254, s4, v[98:99]
	v_lshl_add_u64 v[98:99], v[190:191], 1, v[98:99]
	global_store_dwordx2 v[98:99], v[96:97], off offset:8

; __device__ __forceinline__ u32x2 pack4(f32x4 a) { u32x2 w; w.x = cvt_pk_bf16(a[0], a[1]); w.y = cvt_pk_bf16(a[2], a[3]); return w; }
; __device__ __forceinline__ float dpp_ror1(float v) { return __builtin_bit_cast(float, __builtin_amdgcn_update_dpp(0, __builtin_bit_cast(int, v), 0x121, 0xf, 0xf, false)); }
; __device__ __forceinline__ float dpp_ror15(float v) { return __builtin_bit_cast(float, __builtin_amdgcn_update_dpp(0, __builtin_bit_cast(int, v), 0x12F, 0xf, 0xf, false)); }
;     template <bool BND> __device__ __forceinline__ void conv_gate(f32x4 (&acc)[2][2][4][2], const Unit& u, int wr, int wc, int fr, int fq, int tok0, int pcol) const {
;     ...
;                     const int r = ai * 128 + wr * 64 + m * 16 + fr, tok = tok0 + r;
;                     bool isfirst = false, islast = false;
;                     if (BND) { const int S1 = (tok < NPROMPT ? SEQP : SEQS) - 1, pos = tok & S1; isfirst = pos == 0; islast = pos == S1; }
;                     f32x4 cv[2];
; #pragma unroll
;                     for (int bj = 0; bj < 2; ++bj) {
;                         const f32x4 cur = acc[ai][bj][m][n];
;                         const f32x4 ups = m > 0 ? acc[ai][bj][m > 0 ? m - 1 : 0][n] : pe[bj];
;                         const f32x4 dns = m < 3 ? acc[ai][bj][m < 3 ? m + 1 : 3][n] : ne[bj];
;                         f32x4 prev, next;
; #pragma unroll
;                         for (int j = 0; j < 4; ++j) {
;                             const float t1 = fr == 15 ? ups[j] : cur[j]; float pv = dpp_ror1(t1);
;                             const float t2 = fr == 0 ? dns[j] : cur[j]; float nx = dpp_ror15(t2);
;                             if (BND) { prev[j] = isfirst ? 0.f : pv; next[j] = islast ? 0.f : nx; } else { prev[j] = pv; next[j] = nx; }
;                         }
;                         cv[bj] = w0[bj] * prev + w1[bj] * cur + w2[bj] * next + bb[bj];
;                     }
;                     f32x4 a;
; #pragma unroll
;                     for (int j = 0; j < 4; ++j) { const float g = cv[0][j]; const float sg = __builtin_amdgcn_rcpf(1.0f + __builtin_amdgcn_exp2f(-1.4426950408889634f * g)); a[j] = g * sg * cv[1][j]; }
;                     if (r >= 1 && r <= 254 && (!BND || tok < MTOK)) *(u32x2*)(act + (size_t)tok * DFF + fcol + 4 * n) = pack4(a);
.LBB0_704:
	v_cmp_gt_i32_e32 vcc, s56, v152
	s_waitcnt lgkmcnt(0)
	v_cndmask_b32_e64 v104, v32, v104, s[8:9]
	v_cndmask_b32_e64 v105, v33, v105, s[8:9]
	v_cndmask_b32_e32 v112, v243, v244, vcc
	v_and_b32_e32 v113, v112, v152
	v_cmp_eq_u32_e64 s[12:13], v113, v112
	v_cmp_eq_u32_e64 s[20:21], 0, v113
	v_cndmask_b32_e64 v113, v32, v194, s[6:7]
	v_mov_b32_dpp v112, v104 row_ror:1 row_mask:0xf bank_mask:0xf
	v_cndmask_b32_e64 v114, v33, v195, s[6:7]
	v_cndmask_b32_e64 v106, v34, v106, s[8:9]
	v_mov_b32_dpp v104, v113 row_ror:15 row_mask:0xf bank_mask:0xf
	v_cndmask_b32_e64 v115, v34, v192, s[6:7]
	v_cndmask_b32_e64 v107, v35, v107, s[8:9]
	v_mov_b32_dpp v113, v105 row_ror:1 row_mask:0xf bank_mask:0xf
	v_cndmask_b32_e64 v116, v35, v193, s[6:7]
	v_cndmask_b32_e64 v117, v36, v198, s[6:7]
	v_mov_b32_dpp v105, v114 row_ror:15 row_mask:0xf bank_mask:0xf
	v_cndmask_b32_e64 v118, v37, v199, s[6:7]
	v_cndmask_b32_e64 v119, v38, v196, s[6:7]
	v_mov_b32_dpp v114, v106 row_ror:1 row_mask:0xf bank_mask:0xf
	v_cndmask_b32_e64 v120, v39, v197, s[6:7]
	v_cmp_gt_i32_e64 s[14:15], s69, v152
	v_mov_b32_dpp v106, v115 row_ror:15 row_mask:0xf bank_mask:0xf
	v_mov_b32_dpp v115, v107 row_ror:1 row_mask:0xf bank_mask:0xf
	v_mov_b32_dpp v107, v116 row_ror:15 row_mask:0xf bank_mask:0xf
	v_cndmask_b32_e64 v116, v36, v108, s[8:9]
	s_nop 1
	v_mov_b32_dpp v108, v116 row_ror:1 row_mask:0xf bank_mask:0xf
	v_mov_b32_dpp v116, v117 row_ror:15 row_mask:0xf bank_mask:0xf
	v_cndmask_b32_e64 v117, v37, v109, s[8:9]
	s_nop 1
	v_mov_b32_dpp v109, v117 row_ror:1 row_mask:0xf bank_mask:0xf
	v_mov_b32_dpp v117, v118 row_ror:15 row_mask:0xf bank_mask:0xf
	v_cndmask_b32_e64 v118, v38, v110, s[8:9]
	s_nop 1
	v_mov_b32_dpp v110, v118 row_ror:1 row_mask:0xf bank_mask:0xf
	v_mov_b32_dpp v118, v119 row_ror:15 row_mask:0xf bank_mask:0xf
	v_cndmask_b32_e64 v119, v39, v111, s[8:9]
	s_nop 1
	v_mov_b32_dpp v111, v119 row_ror:1 row_mask:0xf bank_mask:0xf
	v_mov_b32_dpp v119, v120 row_ror:15 row_mask:0xf bank_mask:0xf
	v_add_u32_e32 v120, -1, v245
	v_cmp_gt_u32_e32 vcc, s84, v120
	s_and_b64 s[0:1], vcc, s[14:15]
	s_and_saveexec_b64 s[14:15], s[0:1]
	s_cbranch_execz .LBB0_706
	v_cndmask_b32_e64 v114, v114, 0, s[20:21]
	v_cndmask_b32_e64 v115, v115, 0, s[20:21]
	v_pk_mul_f32 v[114:115], v[74:75], v[114:115]
	v_cndmask_b32_e64 v106, v106, 0, s[12:13]
	v_pk_fma_f32 v[114:115], v[34:35], v[78:79], v[114:115]
	v_cndmask_b32_e64 v107, v107, 0, s[12:13]
	v_pk_fma_f32 v[106:107], v[70:71], v[106:107], v[114:115]
	v_cndmask_b32_e64 v112, v112, 0, s[20:21]
	v_pk_add_f32 v[106:107], v[66:67], v[106:107]
	v_cndmask_b32_e64 v113, v113, 0, s[20:21]
	v_mul_f32_e32 v114, 0xbfb8aa3b, v107
	v_exp_f32_e32 v114, v114
	v_pk_mul_f32 v[112:113], v[72:73], v[112:113]
	v_cndmask_b32_e64 v104, v104, 0, s[12:13]
	v_pk_fma_f32 v[112:113], v[32:33], v[76:77], v[112:113]
	v_cndmask_b32_e64 v105, v105, 0, s[12:13]
	v_pk_fma_f32 v[104:105], v[68:69], v[104:105], v[112:113]
	v_add_f32_e32 v112, 1.0, v114
	v_cndmask_b32_e64 v110, v110, 0, s[20:21]
	v_cndmask_b32_e64 v111, v111, 0, s[20:21]
	v_rcp_f32_e32 v112, v112
	v_mul_f32_e32 v113, 0xbfb8aa3b, v106
	v_pk_mul_f32 v[110:111], v[94:95], v[110:111]
	v_exp_f32_e32 v113, v113
	v_cndmask_b32_e64 v118, v118, 0, s[12:13]
	v_cndmask_b32_e64 v119, v119, 0, s[12:13]
	v_pk_fma_f32 v[110:111], v[38:39], v[90:91], v[110:111]
	v_pk_add_f32 v[104:105], v[64:65], v[104:105]
	v_pk_fma_f32 v[110:111], v[86:87], v[118:119], v[110:111]
	v_mul_f32_e32 v107, v107, v112
	v_pk_add_f32 v[110:111], v[82:83], v[110:111]
	v_mul_f32_e32 v112, 0xbfb8aa3b, v105
	v_mul_f32_e32 v107, v107, v111
	v_add_f32_e32 v111, 1.0, v113
	v_mul_f32_e32 v113, 0xbfb8aa3b, v104
	v_rcp_f32_e32 v111, v111
	v_exp_f32_e32 v112, v112
	v_exp_f32_e32 v113, v113
	v_cndmask_b32_e64 v108, v108, 0, s[20:21]
	v_mul_f32_e32 v106, v106, v111
	v_add_f32_e32 v111, 1.0, v112
	v_add_f32_e32 v112, 1.0, v113
	v_cndmask_b32_e64 v109, v109, 0, s[20:21]
	v_rcp_f32_e32 v111, v111
	v_rcp_f32_e32 v112, v112
	v_pk_mul_f32 v[108:109], v[92:93], v[108:109]
	v_cndmask_b32_e64 v116, v116, 0, s[12:13]
	v_cndmask_b32_e64 v117, v117, 0, s[12:13]
	v_pk_fma_f32 v[108:109], v[36:37], v[88:89], v[108:109]
	v_mul_f32_e32 v105, v105, v111
	v_pk_fma_f32 v[108:109], v[84:85], v[116:117], v[108:109]
	v_mul_f32_e32 v104, v104, v112
	v_pk_add_f32 v[108:109], v[80:81], v[108:109]
	v_mul_f32_e32 v106, v106, v110
	v_mul_f32_e32 v105, v105, v109
	v_mul_f32_e32 v104, v104, v108
	v_cvt_pk_bf16_f32 v104, v104, v105
	v_cvt_pk_bf16_f32 v105, v106, v107
	v_mov_b64_e32 v[106:107], s[88:89]
	s_movk_i32 s4, 0x1600
	v_mad_i64_i32 v[106:107], s[16:17], v152, s4, v[106:107]
	v_lshl_add_u64 v[106:107], v[190:191], 1, v[106:107]
	global_store_dwordx2 v[106:107], v[104:105], off
; __device__ __forceinline__ u32x2 pack4(f32x4 a) { u32x2 w; w.x = cvt_pk_bf16(a[0], a[1]); w.y = cvt_pk_bf16(a[2], a[3]); return w; }
; __device__ __forceinline__ float dpp_ror1(float v) { return __builtin_bit_cast(float, __builtin_amdgcn_update_dpp(0, __builtin_bit_cast(int, v), 0x121, 0xf, 0xf, false)); }
; __device__ __forceinline__ float dpp_ror15(float v) { return __builtin_bit_cast(float, __builtin_amdgcn_update_dpp(0, __builtin_bit_cast(int, v), 0x12F, 0xf, 0xf, false)); }
;     template <bool BND> __device__ __forceinline__ void conv_gate(f32x4 (&acc)[2][2][4][2], const Unit& u, int wr, int wc, int fr, int fq, int tok0, int pcol) const {
;     ...
;                 for (int m = 0; m < 4; ++m) {
;                     const int r = ai * 128 + wr * 64 + m * 16 + fr, tok = tok0 + r;
;                     bool isfirst = false, islast = false;
;                     if (BND) { const int S1 = (tok < NPROMPT ? SEQP : SEQS) - 1, pos = tok & S1; isfirst = pos == 0; islast = pos == S1; }
;                     f32x4 cv[2];
; #pragma unroll
;                     for (int bj = 0; bj < 2; ++bj) {
;                         const f32x4 cur = acc[ai][bj][m][n];
;                         const f32x4 ups = m > 0 ? acc[ai][bj][m > 0 ? m - 1 : 0][n] : pe[bj];
;                         const f32x4 dns = m < 3 ? acc[ai][bj][m < 3 ? m + 1 : 3][n] : ne[bj];
;                         f32x4 prev, next;
; #pragma unroll
;                         for (int j = 0; j < 4; ++j) {
;                             const float t1 = fr == 15 ? ups[j] : cur[j]; float pv = dpp_ror1(t1);
;                             const float t2 = fr == 0 ? dns[j] : cur[j]; float nx = dpp_ror15(t2);
;                             if (BND) { prev[j] = isfirst ? 0.f : pv; next[j] = islast ? 0.f : nx; } else { prev[j] = pv; next[j] = nx; }
;                         }
;                         cv[bj] = w0[bj] * prev + w1[bj] * cur + w2[bj] * next + bb[bj];
;                     }
;                     f32x4 a;
; #pragma unroll
;                     for (int j = 0; j < 4; ++j) { const float g = cv[0][j]; const float sg = __builtin_amdgcn_rcpf(1.0f + __builtin_amdgcn_exp2f(-1.4426950408889634f * g)); a[j] = g * sg * cv[1][j]; }
;                     if (r >= 1 && r <= 254 && (!BND || tok < MTOK)) *(u32x2*)(act + (size_t)tok * DFF + fcol + 4 * n) = pack4(a);
;                     asm volatile("" ::: "memory");
.LBB0_706:
	s_or_b64 exec, exec, s[14:15]
	v_add_u32_e32 v107, s36, v245
	v_add_u32_e32 v104, 15, v107
	v_cmp_gt_i32_e32 vcc, s56, v104
	v_cndmask_b32_e64 v32, v194, v32, s[8:9]
	v_cndmask_b32_e64 v33, v195, v33, s[8:9]
	v_cndmask_b32_e32 v105, v243, v244, vcc
	v_and_b32_e32 v106, v105, v104
	v_cmp_eq_u32_e64 s[14:15], v106, v105
	v_cmp_eq_u32_e64 s[22:23], 0, v106
	v_cndmask_b32_e64 v106, v194, v202, s[6:7]
	v_mov_b32_dpp v105, v32 row_ror:1 row_mask:0xf bank_mask:0xf
	v_cndmask_b32_e64 v108, v195, v203, s[6:7]
	v_cndmask_b32_e64 v34, v192, v34, s[8:9]
	v_mov_b32_dpp v32, v106 row_ror:15 row_mask:0xf bank_mask:0xf
	v_cndmask_b32_e64 v109, v192, v200, s[6:7]
	v_cndmask_b32_e64 v35, v193, v35, s[8:9]
	v_mov_b32_dpp v106, v33 row_ror:1 row_mask:0xf bank_mask:0xf
	v_cndmask_b32_e64 v110, v193, v201, s[6:7]
	v_cndmask_b32_e64 v111, v198, v206, s[6:7]
	v_mov_b32_dpp v33, v108 row_ror:15 row_mask:0xf bank_mask:0xf
	v_cndmask_b32_e64 v112, v199, v207, s[6:7]
	v_cndmask_b32_e64 v113, v196, v204, s[6:7]
	v_mov_b32_dpp v108, v34 row_ror:1 row_mask:0xf bank_mask:0xf
	v_cndmask_b32_e64 v114, v197, v205, s[6:7]
	v_cmp_gt_i32_e64 s[16:17], s69, v104
	v_mov_b32_dpp v34, v109 row_ror:15 row_mask:0xf bank_mask:0xf
	v_mov_b32_dpp v109, v35 row_ror:1 row_mask:0xf bank_mask:0xf
	v_mov_b32_dpp v35, v110 row_ror:15 row_mask:0xf bank_mask:0xf
	v_cndmask_b32_e64 v110, v198, v36, s[8:9]
	s_nop 1
	v_mov_b32_dpp v36, v110 row_ror:1 row_mask:0xf bank_mask:0xf
	v_mov_b32_dpp v110, v111 row_ror:15 row_mask:0xf bank_mask:0xf
	v_cndmask_b32_e64 v111, v199, v37, s[8:9]
	s_nop 1
	v_mov_b32_dpp v37, v111 row_ror:1 row_mask:0xf bank_mask:0xf
	v_mov_b32_dpp v111, v112 row_ror:15 row_mask:0xf bank_mask:0xf
	v_cndmask_b32_e64 v112, v196, v38, s[8:9]
	s_nop 1
	v_mov_b32_dpp v38, v112 row_ror:1 row_mask:0xf bank_mask:0xf
	v_mov_b32_dpp v112, v113 row_ror:15 row_mask:0xf bank_mask:0xf
	v_cndmask_b32_e64 v113, v197, v39, s[8:9]
	s_nop 1
	v_mov_b32_dpp v39, v113 row_ror:1 row_mask:0xf bank_mask:0xf
	v_mov_b32_dpp v113, v114 row_ror:15 row_mask:0xf bank_mask:0xf
	v_add_u32_e32 v114, 15, v245
	v_cmp_gt_u32_e32 vcc, s84, v114
	s_and_b64 s[52:53], vcc, s[16:17]
	s_and_saveexec_b64 s[16:17], s[52:53]
	s_cbranch_execz .LBB0_708
	v_cndmask_b32_e64 v108, v108, 0, s[22:23]
	v_cndmask_b32_e64 v109, v109, 0, s[22:23]
	v_pk_mul_f32 v[108:109], v[74:75], v[108:109]
	v_cndmask_b32_e64 v36, v36, 0, s[22:23]
	v_cndmask_b32_e64 v37, v37, 0, s[22:23]
	v_pk_fma_f32 v[108:109], v[192:193], v[78:79], v[108:109]
	v_cndmask_b32_e64 v34, v34, 0, s[14:15]
	v_cndmask_b32_e64 v35, v35, 0, s[14:15]
	v_pk_mul_f32 v[36:37], v[92:93], v[36:37]
	v_pk_fma_f32 v[34:35], v[70:71], v[34:35], v[108:109]
	v_cndmask_b32_e64 v110, v110, 0, s[14:15]
	v_cndmask_b32_e64 v111, v111, 0, s[14:15]
	v_pk_fma_f32 v[36:37], v[198:199], v[88:89], v[36:37]
	v_pk_add_f32 v[34:35], v[66:67], v[34:35]
	v_pk_fma_f32 v[36:37], v[84:85], v[110:111], v[36:37]
	v_cndmask_b32_e64 v110, v105, 0, s[22:23]
	v_mul_f32_e32 v105, 0xbfb8aa3b, v35
	v_exp_f32_e32 v105, v105
	v_cndmask_b32_e64 v38, v38, 0, s[22:23]
	v_cndmask_b32_e64 v39, v39, 0, s[22:23]
	v_cndmask_b32_e64 v111, v106, 0, s[22:23]
	v_add_f32_e32 v105, 1.0, v105
	v_rcp_f32_e32 v105, v105
	v_mul_f32_e32 v106, 0xbfb8aa3b, v34
	v_pk_mul_f32 v[38:39], v[94:95], v[38:39]
	v_pk_mul_f32 v[110:111], v[72:73], v[110:111]
	v_exp_f32_e32 v106, v106
	v_cndmask_b32_e64 v112, v112, 0, s[14:15]
	v_cndmask_b32_e64 v113, v113, 0, s[14:15]
	v_pk_fma_f32 v[38:39], v[196:197], v[90:91], v[38:39]
	v_pk_fma_f32 v[110:111], v[194:195], v[76:77], v[110:111]
	v_cndmask_b32_e64 v32, v32, 0, s[14:15]
	v_cndmask_b32_e64 v33, v33, 0, s[14:15]
	v_pk_fma_f32 v[38:39], v[86:87], v[112:113], v[38:39]
	v_pk_fma_f32 v[32:33], v[68:69], v[32:33], v[110:111]
	v_pk_add_f32 v[38:39], v[82:83], v[38:39]
	v_pk_add_f32 v[32:33], v[64:65], v[32:33]
	v_mul_f32_e32 v35, v35, v105
	v_mul_f32_e32 v35, v35, v39
	v_add_f32_e32 v39, 1.0, v106
	v_mul_f32_e32 v105, 0xbfb8aa3b, v33
	v_mul_f32_e32 v106, 0xbfb8aa3b, v32
	v_rcp_f32_e32 v39, v39
	v_exp_f32_e32 v105, v105
	v_exp_f32_e32 v106, v106
	v_pk_add_f32 v[36:37], v[80:81], v[36:37]
	v_mul_f32_e32 v34, v34, v39
	v_add_f32_e32 v39, 1.0, v105
	v_add_f32_e32 v105, 1.0, v106
	v_rcp_f32_e32 v39, v39
	v_rcp_f32_e32 v105, v105
	v_mul_f32_e32 v34, v34, v38
	s_movk_i32 s4, 0x1600
	v_mul_f32_e32 v33, v33, v39
	v_mul_f32_e32 v32, v32, v105
	v_mul_f32_e32 v33, v33, v37
	v_mul_f32_e32 v32, v32, v36
	v_cvt_pk_bf16_f32 v32, v32, v33
	v_cvt_pk_bf16_f32 v33, v34, v35
	v_mov_b64_e32 v[34:35], s[88:89]
	v_mad_i64_i32 v[34:35], s[18:19], v104, s4, v[34:35]
	v_lshl_add_u64 v[34:35], v[190:191], 1, v[34:35]
	global_store_dwordx2 v[34:35], v[32:33], off
; __device__ __forceinline__ u32x2 pack4(f32x4 a) { u32x2 w; w.x = cvt_pk_bf16(a[0], a[1]); w.y = cvt_pk_bf16(a[2], a[3]); return w; }
; __device__ __forceinline__ float dpp_ror1(float v) { return __builtin_bit_cast(float, __builtin_amdgcn_update_dpp(0, __builtin_bit_cast(int, v), 0x121, 0xf, 0xf, false)); }
; __device__ __forceinline__ float dpp_ror15(float v) { return __builtin_bit_cast(float, __builtin_amdgcn_update_dpp(0, __builtin_bit_cast(int, v), 0x12F, 0xf, 0xf, false)); }
;     template <bool BND> __device__ __forceinline__ void conv_gate(f32x4 (&acc)[2][2][4][2], const Unit& u, int wr, int wc, int fr, int fq, int tok0, int pcol) const {
;     ...
;                 for (int m = 0; m < 4; ++m) {
;                     const int r = ai * 128 + wr * 64 + m * 16 + fr, tok = tok0 + r;
;                     bool isfirst = false, islast = false;
;                     if (BND) { const int S1 = (tok < NPROMPT ? SEQP : SEQS) - 1, pos = tok & S1; isfirst = pos == 0; islast = pos == S1; }
;                     f32x4 cv[2];
; #pragma unroll
;                     for (int bj = 0; bj < 2; ++bj) {
;                         const f32x4 cur = acc[ai][bj][m][n];
;                         const f32x4 ups = m > 0 ? acc[ai][bj][m > 0 ? m - 1 : 0][n] : pe[bj];
;                         const f32x4 dns = m < 3 ? acc[ai][bj][m < 3 ? m + 1 : 3][n] : ne[bj];
;                         f32x4 prev, next;
; #pragma unroll
;                         for (int j = 0; j < 4; ++j) {
;                             const float t1 = fr == 15 ? ups[j] : cur[j]; float pv = dpp_ror1(t1);
;                             const float t2 = fr == 0 ? dns[j] : cur[j]; float nx = dpp_ror15(t2);
;                             if (BND) { prev[j] = isfirst ? 0.f : pv; next[j] = islast ? 0.f : nx; } else { prev[j] = pv; next[j] = nx; }
;                         }
;                         cv[bj] = w0[bj] * prev + w1[bj] * cur + w2[bj] * next + bb[bj];
;                     }
;                     f32x4 a;
; #pragma unroll
;                     for (int j = 0; j < 4; ++j) { const float g = cv[0][j]; const float sg = __builtin_amdgcn_rcpf(1.0f + __builtin_amdgcn_exp2f(-1.4426950408889634f * g)); a[j] = g * sg * cv[1][j]; }
;                     if (r >= 1 && r <= 254 && (!BND || tok < MTOK)) *(u32x2*)(act + (size_t)tok * DFF + fcol + 4 * n) = pack4(a);
;                     asm volatile("" ::: "memory");
.LBB0_708:
	s_or_b64 exec, exec, s[16:17]
	v_add_u32_e32 v105, 31, v107
	v_cmp_gt_i32_e32 vcc, s56, v105
	s_nop 1
	v_cndmask_b32_e32 v32, v243, v244, vcc
	v_and_b32_e32 v33, v32, v105
	v_cmp_eq_u32_e64 s[16:17], v33, v32
	v_cndmask_b32_e64 v32, v202, v194, s[8:9]
	v_cmp_eq_u32_e64 s[26:27], 0, v33
	v_cndmask_b32_e64 v33, v202, v48, s[6:7]
	v_mov_b32_dpp v35, v32 row_ror:1 row_mask:0xf bank_mask:0xf
	v_cndmask_b32_e64 v34, v203, v49, s[6:7]
	v_mov_b32_dpp v32, v33 row_ror:15 row_mask:0xf bank_mask:0xf
	v_cndmask_b32_e64 v33, v203, v195, s[8:9]
	v_cndmask_b32_e64 v36, v200, v50, s[6:7]
	s_nop 0
	v_mov_b32_dpp v37, v33 row_ror:1 row_mask:0xf bank_mask:0xf
	v_cndmask_b32_e64 v106, v201, v51, s[6:7]
	v_cndmask_b32_e64 v108, v206, v198, s[8:9]
	v_mov_b32_dpp v33, v34 row_ror:15 row_mask:0xf bank_mask:0xf
	v_cndmask_b32_e64 v34, v200, v192, s[8:9]
	v_cndmask_b32_e64 v110, v207, v199, s[8:9]
	s_nop 0
	v_mov_b32_dpp v38, v34 row_ror:1 row_mask:0xf bank_mask:0xf
	v_cndmask_b32_e64 v112, v204, v196, s[8:9]
	v_mov_b32_dpp v34, v36 row_ror:15 row_mask:0xf bank_mask:0xf
	v_cndmask_b32_e64 v36, v201, v193, s[8:9]
	v_cndmask_b32_e64 v114, v205, v197, s[8:9]
	s_nop 0
	v_mov_b32_dpp v39, v36 row_ror:1 row_mask:0xf bank_mask:0xf
	v_cndmask_b32_e64 v115, v205, v55, s[6:7]
	v_cmp_gt_i32_e64 s[18:19], s69, v105
	v_mov_b32_dpp v36, v106 row_ror:15 row_mask:0xf bank_mask:0xf
	s_movk_i32 s55, 0xfe
	s_nop 0
	v_mov_b32_dpp v106, v108 row_ror:1 row_mask:0xf bank_mask:0xf
	v_cndmask_b32_e64 v108, v206, v52, s[6:7]
	s_nop 1
	v_mov_b32_dpp v109, v108 row_ror:15 row_mask:0xf bank_mask:0xf
	v_mov_b32_dpp v108, v110 row_ror:1 row_mask:0xf bank_mask:0xf
	v_cndmask_b32_e64 v110, v207, v53, s[6:7]
	s_nop 1
	v_mov_b32_dpp v111, v110 row_ror:15 row_mask:0xf bank_mask:0xf
	v_mov_b32_dpp v110, v112 row_ror:1 row_mask:0xf bank_mask:0xf
	v_cndmask_b32_e64 v112, v204, v54, s[6:7]
	s_nop 1
	v_mov_b32_dpp v113, v112 row_ror:15 row_mask:0xf bank_mask:0xf
	v_mov_b32_dpp v112, v114 row_ror:1 row_mask:0xf bank_mask:0xf
	v_mov_b32_dpp v114, v115 row_ror:15 row_mask:0xf bank_mask:0xf
	v_add_u32_e32 v115, 31, v245
	v_cmp_gt_u32_e32 vcc, s84, v115
	s_and_b64 s[84:85], vcc, s[18:19]
	s_and_saveexec_b64 s[18:19], s[84:85]
	s_cbranch_execz .LBB0_710
	v_cndmask_b32_e64 v38, v38, 0, s[26:27]
	v_cndmask_b32_e64 v39, v39, 0, s[26:27]
	v_pk_mul_f32 v[38:39], v[74:75], v[38:39]
	v_cndmask_b32_e64 v116, v109, 0, s[16:17]
	v_cndmask_b32_e64 v109, v112, 0, s[26:27]
	v_cndmask_b32_e64 v112, v35, 0, s[26:27]
	v_pk_fma_f32 v[38:39], v[200:201], v[78:79], v[38:39]
	v_cndmask_b32_e64 v34, v34, 0, s[16:17]
	v_cndmask_b32_e64 v35, v36, 0, s[16:17]
	v_pk_fma_f32 v[34:35], v[70:71], v[34:35], v[38:39]
	v_cndmask_b32_e64 v118, v113, 0, s[16:17]
	v_pk_add_f32 v[34:35], v[66:67], v[34:35]
	v_cndmask_b32_e64 v113, v37, 0, s[26:27]
	v_mul_f32_e32 v36, 0xbfb8aa3b, v35
	v_exp_f32_e32 v36, v36
	v_mul_f32_e32 v37, 0xbfb8aa3b, v34
	v_pk_mul_f32 v[112:113], v[72:73], v[112:113]
	v_exp_f32_e32 v37, v37
	v_add_f32_e32 v36, 1.0, v36
	v_rcp_f32_e32 v36, v36
	v_pk_fma_f32 v[112:113], v[202:203], v[76:77], v[112:113]
	v_cndmask_b32_e64 v32, v32, 0, s[16:17]
	v_cndmask_b32_e64 v33, v33, 0, s[16:17]
	v_pk_fma_f32 v[32:33], v[68:69], v[32:33], v[112:113]
	v_mul_f32_e32 v35, v35, v36
	v_pk_add_f32 v[32:33], v[64:65], v[32:33]
	v_add_f32_e32 v36, 1.0, v37
	v_mul_f32_e32 v37, 0xbfb8aa3b, v33
	v_mul_f32_e32 v38, 0xbfb8aa3b, v32
	v_rcp_f32_e32 v36, v36
	v_exp_f32_e32 v37, v37
	v_exp_f32_e32 v38, v38
	v_cndmask_b32_e64 v119, v114, 0, s[16:17]
	v_mul_f32_e32 v34, v34, v36
	v_add_f32_e32 v36, 1.0, v37
	v_add_f32_e32 v37, 1.0, v38
	v_cndmask_b32_e64 v114, v106, 0, s[26:27]
	v_cndmask_b32_e64 v115, v108, 0, s[26:27]
	v_cndmask_b32_e64 v108, v110, 0, s[26:27]
	v_rcp_f32_e32 v36, v36
	v_rcp_f32_e32 v37, v37
	v_cndmask_b32_e64 v117, v111, 0, s[16:17]
	v_pk_mul_f32 v[108:109], v[94:95], v[108:109]
	v_pk_mul_f32 v[110:111], v[92:93], v[114:115]
	v_pk_fma_f32 v[108:109], v[204:205], v[90:91], v[108:109]
	v_pk_fma_f32 v[110:111], v[206:207], v[88:89], v[110:111]
	v_pk_fma_f32 v[108:109], v[86:87], v[118:119], v[108:109]
	v_pk_fma_f32 v[110:111], v[84:85], v[116:117], v[110:111]
	v_pk_add_f32 v[108:109], v[82:83], v[108:109]
	v_pk_add_f32 v[110:111], v[80:81], v[110:111]
	v_mul_f32_e32 v33, v33, v36
	v_mul_f32_e32 v32, v32, v37
	v_mul_f32_e32 v35, v35, v109
	v_mul_f32_e32 v34, v34, v108
	v_mul_f32_e32 v33, v33, v111
	v_mul_f32_e32 v32, v32, v110
	v_cvt_pk_bf16_f32 v32, v32, v33
	v_cvt_pk_bf16_f32 v33, v34, v35
	v_mov_b64_e32 v[34:35], s[88:89]
	s_movk_i32 s4, 0x1600
	v_mad_i64_i32 v[34:35], s[24:25], v105, s4, v[34:35]
	v_lshl_add_u64 v[34:35], v[190:191], 1, v[34:35]
	global_store_dwordx2 v[34:35], v[32:33], off
; __device__ __forceinline__ u32x2 pack4(f32x4 a) { u32x2 w; w.x = cvt_pk_bf16(a[0], a[1]); w.y = cvt_pk_bf16(a[2], a[3]); return w; }
; __device__ __forceinline__ float dpp_ror1(float v) { return __builtin_bit_cast(float, __builtin_amdgcn_update_dpp(0, __builtin_bit_cast(int, v), 0x121, 0xf, 0xf, false)); }
; __device__ __forceinline__ float dpp_ror15(float v) { return __builtin_bit_cast(float, __builtin_amdgcn_update_dpp(0, __builtin_bit_cast(int, v), 0x12F, 0xf, 0xf, false)); }
;     template <bool BND> __device__ __forceinline__ void conv_gate(f32x4 (&acc)[2][2][4][2], const Unit& u, int wr, int wc, int fr, int fq, int tok0, int pcol) const {
;     ...
;                 for (int m = 0; m < 4; ++m) {
;                     const int r = ai * 128 + wr * 64 + m * 16 + fr, tok = tok0 + r;
;                     bool isfirst = false, islast = false;
;                     if (BND) { const int S1 = (tok < NPROMPT ? SEQP : SEQS) - 1, pos = tok & S1; isfirst = pos == 0; islast = pos == S1; }
;                     f32x4 cv[2];
; #pragma unroll
;                     for (int bj = 0; bj < 2; ++bj) {
;                         const f32x4 cur = acc[ai][bj][m][n];
;                         const f32x4 ups = m > 0 ? acc[ai][bj][m > 0 ? m - 1 : 0][n] : pe[bj];
;                         const f32x4 dns = m < 3 ? acc[ai][bj][m < 3 ? m + 1 : 3][n] : ne[bj];
;                         f32x4 prev, next;
; #pragma unroll
;                         for (int j = 0; j < 4; ++j) {
;                             const float t1 = fr == 15 ? ups[j] : cur[j]; float pv = dpp_ror1(t1);
;                             const float t2 = fr == 0 ? dns[j] : cur[j]; float nx = dpp_ror15(t2);
;                             if (BND) { prev[j] = isfirst ? 0.f : pv; next[j] = islast ? 0.f : nx; } else { prev[j] = pv; next[j] = nx; }
;                         }
;                         cv[bj] = w0[bj] * prev + w1[bj] * cur + w2[bj] * next + bb[bj];
;                     }
;                     f32x4 a;
; #pragma unroll
;                     for (int j = 0; j < 4; ++j) { const float g = cv[0][j]; const float sg = __builtin_amdgcn_rcpf(1.0f + __builtin_amdgcn_exp2f(-1.4426950408889634f * g)); a[j] = g * sg * cv[1][j]; }
;                     if (r >= 1 && r <= 254 && (!BND || tok < MTOK)) *(u32x2*)(act + (size_t)tok * DFF + fcol + 4 * n) = pack4(a);
;                     asm volatile("" ::: "memory");
.LBB0_710:
	s_or_b64 exec, exec, s[18:19]
	v_add_u32_e32 v106, 47, v107
	v_cmp_gt_i32_e32 vcc, s56, v106
	s_nop 1
	v_cndmask_b32_e32 v32, v243, v244, vcc
	v_and_b32_e32 v33, v32, v106
	v_cmp_eq_u32_e64 s[18:19], v33, v32
	v_cndmask_b32_e64 v32, v48, v202, s[8:9]
	v_cmp_eq_u32_e64 s[30:31], 0, v33
	v_cndmask_b32_e64 v33, v48, v96, s[6:7]
	v_mov_b32_dpp v35, v32 row_ror:1 row_mask:0xf bank_mask:0xf
	v_cndmask_b32_e64 v34, v49, v97, s[6:7]
	v_mov_b32_dpp v32, v33 row_ror:15 row_mask:0xf bank_mask:0xf
	v_cndmask_b32_e64 v33, v49, v203, s[8:9]
	v_cndmask_b32_e64 v36, v50, v98, s[6:7]
	s_nop 0
	v_mov_b32_dpp v37, v33 row_ror:1 row_mask:0xf bank_mask:0xf
	v_cndmask_b32_e64 v96, v51, v99, s[6:7]
	v_cndmask_b32_e64 v97, v52, v206, s[8:9]
	v_mov_b32_dpp v33, v34 row_ror:15 row_mask:0xf bank_mask:0xf
	v_cndmask_b32_e64 v34, v50, v200, s[8:9]
	v_cndmask_b32_e64 v99, v53, v207, s[8:9]
	s_nop 0
	v_mov_b32_dpp v38, v34 row_ror:1 row_mask:0xf bank_mask:0xf
	v_cndmask_b32_e64 v108, v55, v205, s[8:9]
	v_cmp_gt_i32_e64 s[24:25], s69, v106
	v_mov_b32_dpp v34, v36 row_ror:15 row_mask:0xf bank_mask:0xf
	v_cndmask_b32_e64 v36, v51, v201, s[8:9]
	s_mov_b32 s54, 0x20000
	s_nop 0
	v_mov_b32_dpp v39, v36 row_ror:1 row_mask:0xf bank_mask:0xf
	v_mov_b32_dpp v36, v96 row_ror:15 row_mask:0xf bank_mask:0xf
	v_mov_b32_dpp v96, v97 row_ror:1 row_mask:0xf bank_mask:0xf
	v_cndmask_b32_e64 v97, v52, v100, s[6:7]
	s_nop 0
	s_nop 0
	v_mov_b32_dpp v98, v97 row_ror:15 row_mask:0xf bank_mask:0xf
	v_mov_b32_dpp v97, v99 row_ror:1 row_mask:0xf bank_mask:0xf
	v_cndmask_b32_e64 v99, v53, v101, s[6:7]
	v_cndmask_b32_e64 v101, v54, v204, s[8:9]
	s_nop 0
	v_mov_b32_dpp v100, v99 row_ror:15 row_mask:0xf bank_mask:0xf
	v_mov_b32_dpp v99, v101 row_ror:1 row_mask:0xf bank_mask:0xf
	v_cndmask_b32_e64 v101, v54, v102, s[6:7]
	s_nop 1
	v_mov_b32_dpp v102, v101 row_ror:15 row_mask:0xf bank_mask:0xf
	v_mov_b32_dpp v101, v108 row_ror:1 row_mask:0xf bank_mask:0xf
	v_cndmask_b32_e64 v108, v55, v103, s[6:7]
	s_nop 1
	v_mov_b32_dpp v103, v108 row_ror:15 row_mask:0xf bank_mask:0xf
	v_add_u32_e32 v108, 47, v245
	v_cmp_gt_u32_e32 vcc, s55, v108
	s_and_b64 s[90:91], vcc, s[24:25]
	s_and_saveexec_b64 s[24:25], s[90:91]
	s_cbranch_execz .LBB0_712
	v_cndmask_b32_e64 v96, v96, 0, s[30:31]
	v_cndmask_b32_e64 v97, v97, 0, s[30:31]
	v_cndmask_b32_e64 v38, v38, 0, s[30:31]
	v_cndmask_b32_e64 v39, v39, 0, s[30:31]
	v_pk_mul_f32 v[96:97], v[92:93], v[96:97]
	v_pk_mul_f32 v[38:39], v[74:75], v[38:39]
	v_pk_fma_f32 v[52:53], v[52:53], v[88:89], v[96:97]
	v_cndmask_b32_e64 v96, v35, 0, s[30:31]
	v_pk_fma_f32 v[38:39], v[50:51], v[78:79], v[38:39]
	v_cndmask_b32_e64 v34, v34, 0, s[18:19]
	v_cndmask_b32_e64 v35, v36, 0, s[18:19]
	v_pk_fma_f32 v[34:35], v[70:71], v[34:35], v[38:39]
	v_cndmask_b32_e64 v97, v37, 0, s[30:31]
	v_pk_add_f32 v[34:35], v[66:67], v[34:35]
	v_pk_mul_f32 v[96:97], v[72:73], v[96:97]
	v_mul_f32_e32 v36, 0xbfb8aa3b, v35
	v_exp_f32_e32 v36, v36
	v_mul_f32_e32 v37, 0xbfb8aa3b, v34
	v_exp_f32_e32 v37, v37
	v_pk_fma_f32 v[48:49], v[48:49], v[76:77], v[96:97]
	v_add_f32_e32 v36, 1.0, v36
	v_rcp_f32_e32 v36, v36
	v_cndmask_b32_e64 v32, v32, 0, s[18:19]
	v_cndmask_b32_e64 v33, v33, 0, s[18:19]
	v_pk_fma_f32 v[32:33], v[68:69], v[32:33], v[48:49]
	v_mul_f32_e32 v35, v35, v36
	v_pk_add_f32 v[32:33], v[64:65], v[32:33]
	v_add_f32_e32 v36, 1.0, v37
	v_mul_f32_e32 v37, 0xbfb8aa3b, v33
	v_mul_f32_e32 v38, 0xbfb8aa3b, v32
	v_rcp_f32_e32 v36, v36
	v_exp_f32_e32 v37, v37
	v_exp_f32_e32 v38, v38
	v_cndmask_b32_e64 v108, v98, 0, s[18:19]
	v_mul_f32_e32 v34, v34, v36
	v_add_f32_e32 v36, 1.0, v37
	v_add_f32_e32 v37, 1.0, v38
	v_cndmask_b32_e64 v98, v99, 0, s[30:31]
	v_cndmask_b32_e64 v99, v101, 0, s[30:31]
	v_rcp_f32_e32 v36, v36
	v_rcp_f32_e32 v37, v37
	v_pk_mul_f32 v[98:99], v[94:95], v[98:99]
	v_cndmask_b32_e64 v109, v100, 0, s[18:19]
	v_cndmask_b32_e64 v102, v102, 0, s[18:19]
	v_cndmask_b32_e64 v103, v103, 0, s[18:19]
	v_pk_fma_f32 v[54:55], v[54:55], v[90:91], v[98:99]
	v_pk_fma_f32 v[52:53], v[84:85], v[108:109], v[52:53]
	v_pk_fma_f32 v[54:55], v[86:87], v[102:103], v[54:55]
	v_pk_add_f32 v[52:53], v[80:81], v[52:53]
	v_pk_add_f32 v[54:55], v[82:83], v[54:55]
	v_mul_f32_e32 v33, v33, v36
	v_mul_f32_e32 v32, v32, v37
	v_mul_f32_e32 v35, v35, v55
	v_mul_f32_e32 v34, v34, v54
	v_mul_f32_e32 v33, v33, v53
	v_mul_f32_e32 v32, v32, v52
	v_cvt_pk_bf16_f32 v32, v32, v33
	v_cvt_pk_bf16_f32 v33, v34, v35
	v_mov_b64_e32 v[34:35], s[88:89]
	s_movk_i32 s4, 0x1600
	v_mad_i64_i32 v[34:35], s[28:29], v106, s4, v[34:35]
	v_lshl_add_u64 v[34:35], v[190:191], 1, v[34:35]
	global_store_dwordx2 v[34:35], v[32:33], off

; __device__ __forceinline__ u32x2 pack4(f32x4 a) { u32x2 w; w.x = cvt_pk_bf16(a[0], a[1]); w.y = cvt_pk_bf16(a[2], a[3]); return w; }
; __device__ __forceinline__ float dpp_ror1(float v) { return __builtin_bit_cast(float, __builtin_amdgcn_update_dpp(0, __builtin_bit_cast(int, v), 0x121, 0xf, 0xf, false)); }
; __device__ __forceinline__ float dpp_ror15(float v) { return __builtin_bit_cast(float, __builtin_amdgcn_update_dpp(0, __builtin_bit_cast(int, v), 0x12F, 0xf, 0xf, false)); }
;     template <bool BND> __device__ __forceinline__ void conv_gate(f32x4 (&acc)[2][2][4][2], const Unit& u, int wr, int wc, int fr, int fq, int tok0, int pcol) const {
;     ...
;                 for (int m = 0; m < 4; ++m) {
;                     const int r = ai * 128 + wr * 64 + m * 16 + fr, tok = tok0 + r;
;                     bool isfirst = false, islast = false;
;                     if (BND) { const int S1 = (tok < NPROMPT ? SEQP : SEQS) - 1, pos = tok & S1; isfirst = pos == 0; islast = pos == S1; }
;                     f32x4 cv[2];
; #pragma unroll
;                     for (int bj = 0; bj < 2; ++bj) {
;                         const f32x4 cur = acc[ai][bj][m][n];
;                         const f32x4 ups = m > 0 ? acc[ai][bj][m > 0 ? m - 1 : 0][n] : pe[bj];
;                         const f32x4 dns = m < 3 ? acc[ai][bj][m < 3 ? m + 1 : 3][n] : ne[bj];
;                         f32x4 prev, next;
; #pragma unroll
;                         for (int j = 0; j < 4; ++j) {
;                             const float t1 = fr == 15 ? ups[j] : cur[j]; float pv = dpp_ror1(t1);
;                             const float t2 = fr == 0 ? dns[j] : cur[j]; float nx = dpp_ror15(t2);
;                             if (BND) { prev[j] = isfirst ? 0.f : pv; next[j] = islast ? 0.f : nx; } else { prev[j] = pv; next[j] = nx; }
;                         }
;                         cv[bj] = w0[bj] * prev + w1[bj] * cur + w2[bj] * next + bb[bj];
;                     }
;                     f32x4 a;
; #pragma unroll
;                     for (int j = 0; j < 4; ++j) { const float g = cv[0][j]; const float sg = __builtin_amdgcn_rcpf(1.0f + __builtin_amdgcn_exp2f(-1.4426950408889634f * g)); a[j] = g * sg * cv[1][j]; }
;                     if (r >= 1 && r <= 254 && (!BND || tok < MTOK)) *(u32x2*)(act + (size_t)tok * DFF + fcol + 4 * n) = pack4(a);
;                     asm volatile("" ::: "memory");
.LBB0_720:
	v_add_u32_e32 v96, 0x7f, v107
	v_cmp_gt_i32_e32 vcc, s56, v96
	s_waitcnt lgkmcnt(0)
	v_cndmask_b32_e64 v48, v40, v48, s[8:9]
	v_cndmask_b32_e64 v49, v41, v49, s[8:9]
	v_cndmask_b32_e32 v97, v243, v244, vcc
	v_and_b32_e32 v98, v97, v96
	v_cmp_eq_u32_e64 s[24:25], v98, v97
	v_cmp_eq_u32_e64 s[40:41], 0, v98
	v_cndmask_b32_e64 v98, v40, v210, s[6:7]
	v_mov_b32_dpp v97, v48 row_ror:1 row_mask:0xf bank_mask:0xf
	v_cndmask_b32_e64 v99, v41, v211, s[6:7]
	v_cndmask_b32_e64 v50, v42, v50, s[8:9]
	v_mov_b32_dpp v48, v98 row_ror:15 row_mask:0xf bank_mask:0xf
	v_cndmask_b32_e64 v100, v42, v208, s[6:7]
	v_cndmask_b32_e64 v51, v43, v51, s[8:9]
	v_mov_b32_dpp v98, v49 row_ror:1 row_mask:0xf bank_mask:0xf
	v_cndmask_b32_e64 v101, v43, v209, s[6:7]
	v_cndmask_b32_e64 v102, v44, v214, s[6:7]
	v_mov_b32_dpp v49, v99 row_ror:15 row_mask:0xf bank_mask:0xf
	v_cndmask_b32_e64 v103, v45, v215, s[6:7]
	v_cndmask_b32_e64 v108, v46, v212, s[6:7]
	v_mov_b32_dpp v99, v50 row_ror:1 row_mask:0xf bank_mask:0xf
	v_cndmask_b32_e64 v109, v47, v213, s[6:7]
	v_cmp_gt_i32_e64 s[28:29], s54, v96
	v_mov_b32_dpp v50, v100 row_ror:15 row_mask:0xf bank_mask:0xf
	s_mov_b32 s4, 0x10000
	s_nop 0
	v_mov_b32_dpp v100, v51 row_ror:1 row_mask:0xf bank_mask:0xf
	v_mov_b32_dpp v51, v101 row_ror:15 row_mask:0xf bank_mask:0xf
	v_cndmask_b32_e64 v101, v44, v52, s[8:9]
	s_nop 1
	v_mov_b32_dpp v52, v101 row_ror:1 row_mask:0xf bank_mask:0xf
	v_mov_b32_dpp v101, v102 row_ror:15 row_mask:0xf bank_mask:0xf
	v_cndmask_b32_e64 v102, v45, v53, s[8:9]
	s_nop 1
	v_mov_b32_dpp v53, v102 row_ror:1 row_mask:0xf bank_mask:0xf
	v_mov_b32_dpp v102, v103 row_ror:15 row_mask:0xf bank_mask:0xf
	v_cndmask_b32_e64 v103, v46, v54, s[8:9]
	s_nop 1
	v_mov_b32_dpp v54, v103 row_ror:1 row_mask:0xf bank_mask:0xf
	v_mov_b32_dpp v103, v108 row_ror:15 row_mask:0xf bank_mask:0xf
	v_cndmask_b32_e64 v108, v47, v55, s[8:9]
	s_nop 1
	v_mov_b32_dpp v55, v108 row_ror:1 row_mask:0xf bank_mask:0xf
	v_mov_b32_dpp v108, v109 row_ror:15 row_mask:0xf bank_mask:0xf
	v_add_u32_e32 v109, 0x7f, v245
	v_cmp_gt_u32_e32 vcc, s55, v109
	s_and_b64 s[66:67], vcc, s[28:29]
	s_and_saveexec_b64 s[28:29], s[66:67]
	s_cbranch_execz .LBB0_722
	v_cndmask_b32_e64 v54, v54, 0, s[40:41]
	v_cndmask_b32_e64 v55, v55, 0, s[40:41]
	v_pk_mul_f32 v[54:55], v[94:95], v[54:55]
	v_cndmask_b32_e64 v111, v102, 0, s[24:25]
	v_cndmask_b32_e64 v102, v103, 0, s[24:25]
	v_cndmask_b32_e64 v103, v108, 0, s[24:25]
	v_pk_fma_f32 v[54:55], v[46:47], v[90:91], v[54:55]
	v_cndmask_b32_e64 v50, v50, 0, s[24:25]
	v_pk_fma_f32 v[54:55], v[86:87], v[102:103], v[54:55]
	v_cndmask_b32_e64 v103, v98, 0, s[40:41]
	v_cndmask_b32_e64 v98, v99, 0, s[40:41]
	v_cndmask_b32_e64 v99, v100, 0, s[40:41]
	v_pk_mul_f32 v[98:99], v[74:75], v[98:99]
	v_cndmask_b32_e64 v51, v51, 0, s[24:25]
	v_pk_fma_f32 v[98:99], v[42:43], v[78:79], v[98:99]
	v_cndmask_b32_e64 v102, v97, 0, s[40:41]
	v_pk_fma_f32 v[50:51], v[70:71], v[50:51], v[98:99]
	v_cndmask_b32_e64 v110, v101, 0, s[24:25]
	v_pk_add_f32 v[50:51], v[66:67], v[50:51]
	v_pk_mul_f32 v[100:101], v[72:73], v[102:103]
	v_mul_f32_e32 v97, 0xbfb8aa3b, v51
	v_exp_f32_e32 v97, v97
	v_mul_f32_e32 v98, 0xbfb8aa3b, v50
	v_exp_f32_e32 v98, v98
	v_pk_fma_f32 v[100:101], v[40:41], v[76:77], v[100:101]
	v_add_f32_e32 v97, 1.0, v97
	v_rcp_f32_e32 v97, v97
	v_cndmask_b32_e64 v48, v48, 0, s[24:25]
	v_cndmask_b32_e64 v49, v49, 0, s[24:25]
	v_pk_fma_f32 v[48:49], v[68:69], v[48:49], v[100:101]
	v_pk_add_f32 v[54:55], v[82:83], v[54:55]
	v_pk_add_f32 v[48:49], v[64:65], v[48:49]
	v_mul_f32_e32 v51, v51, v97
	v_mul_f32_e32 v51, v51, v55
	v_add_f32_e32 v55, 1.0, v98
	v_mul_f32_e32 v97, 0xbfb8aa3b, v49
	v_mul_f32_e32 v98, 0xbfb8aa3b, v48
	v_rcp_f32_e32 v55, v55
	v_exp_f32_e32 v97, v97
	v_exp_f32_e32 v98, v98
	v_cndmask_b32_e64 v52, v52, 0, s[40:41]
	v_mul_f32_e32 v50, v50, v55
	v_add_f32_e32 v55, 1.0, v97
	v_add_f32_e32 v97, 1.0, v98
	v_cndmask_b32_e64 v53, v53, 0, s[40:41]
	v_rcp_f32_e32 v55, v55
	v_rcp_f32_e32 v97, v97
	v_pk_mul_f32 v[52:53], v[92:93], v[52:53]
	v_mul_f32_e32 v50, v50, v54
	v_pk_fma_f32 v[52:53], v[44:45], v[88:89], v[52:53]
	v_mul_f32_e32 v49, v49, v55
	v_pk_fma_f32 v[52:53], v[84:85], v[110:111], v[52:53]
	v_mul_f32_e32 v48, v48, v97
	v_pk_add_f32 v[52:53], v[80:81], v[52:53]
	s_movk_i32 s5, 0x1600
	v_mul_f32_e32 v49, v49, v53
	v_mul_f32_e32 v48, v48, v52
	v_cvt_pk_bf16_f32 v48, v48, v49
	v_cvt_pk_bf16_f32 v49, v50, v51
	v_mov_b64_e32 v[50:51], s[88:89]
	v_mad_i64_i32 v[50:51], s[34:35], v96, s5, v[50:51]
	v_lshl_add_u64 v[50:51], v[190:191], 1, v[50:51]
	global_store_dwordx2 v[50:51], v[48:49], off
; __device__ __forceinline__ u32x2 pack4(f32x4 a) { u32x2 w; w.x = cvt_pk_bf16(a[0], a[1]); w.y = cvt_pk_bf16(a[2], a[3]); return w; }
; __device__ __forceinline__ float dpp_ror1(float v) { return __builtin_bit_cast(float, __builtin_amdgcn_update_dpp(0, __builtin_bit_cast(int, v), 0x121, 0xf, 0xf, false)); }
; __device__ __forceinline__ float dpp_ror15(float v) { return __builtin_bit_cast(float, __builtin_amdgcn_update_dpp(0, __builtin_bit_cast(int, v), 0x12F, 0xf, 0xf, false)); }
;     template <bool BND> __device__ __forceinline__ void conv_gate(f32x4 (&acc)[2][2][4][2], const Unit& u, int wr, int wc, int fr, int fq, int tok0, int pcol) const {
;     ...
;                 for (int m = 0; m < 4; ++m) {
;                     const int r = ai * 128 + wr * 64 + m * 16 + fr, tok = tok0 + r;
;                     bool isfirst = false, islast = false;
;                     if (BND) { const int S1 = (tok < NPROMPT ? SEQP : SEQS) - 1, pos = tok & S1; isfirst = pos == 0; islast = pos == S1; }
;                     f32x4 cv[2];
; #pragma unroll
;                     for (int bj = 0; bj < 2; ++bj) {
;                         const f32x4 cur = acc[ai][bj][m][n];
;                         const f32x4 ups = m > 0 ? acc[ai][bj][m > 0 ? m - 1 : 0][n] : pe[bj];
;                         const f32x4 dns = m < 3 ? acc[ai][bj][m < 3 ? m + 1 : 3][n] : ne[bj];
;                         f32x4 prev, next;
; #pragma unroll
;                         for (int j = 0; j < 4; ++j) {
;                             const float t1 = fr == 15 ? ups[j] : cur[j]; float pv = dpp_ror1(t1);
;                             const float t2 = fr == 0 ? dns[j] : cur[j]; float nx = dpp_ror15(t2);
;                             if (BND) { prev[j] = isfirst ? 0.f : pv; next[j] = islast ? 0.f : nx; } else { prev[j] = pv; next[j] = nx; }
;                         }
;                         cv[bj] = w0[bj] * prev + w1[bj] * cur + w2[bj] * next + bb[bj];
;                     }
;                     f32x4 a;
; #pragma unroll
;                     for (int j = 0; j < 4; ++j) { const float g = cv[0][j]; const float sg = __builtin_amdgcn_rcpf(1.0f + __builtin_amdgcn_exp2f(-1.4426950408889634f * g)); a[j] = g * sg * cv[1][j]; }
;                     if (r >= 1 && r <= 254 && (!BND || tok < MTOK)) *(u32x2*)(act + (size_t)tok * DFF + fcol + 4 * n) = pack4(a);
;                     asm volatile("" ::: "memory");
.LBB0_722:
	s_or_b64 exec, exec, s[28:29]
	v_add_u32_e32 v97, 0x8f, v107
	v_cmp_gt_i32_e32 vcc, s4, v97
	v_cndmask_b32_e64 v40, v210, v40, s[8:9]
	v_cndmask_b32_e64 v41, v211, v41, s[8:9]
	v_cndmask_b32_e32 v48, v243, v244, vcc
	v_and_b32_e32 v49, v48, v97
	v_cmp_eq_u32_e64 s[28:29], v49, v48
	v_cmp_eq_u32_e64 s[42:43], 0, v49
	v_cndmask_b32_e64 v49, v210, v218, s[6:7]
	v_mov_b32_dpp v48, v40 row_ror:1 row_mask:0xf bank_mask:0xf
	v_cndmask_b32_e64 v50, v211, v219, s[6:7]
	v_cndmask_b32_e64 v42, v208, v42, s[8:9]
	v_mov_b32_dpp v40, v49 row_ror:15 row_mask:0xf bank_mask:0xf
	v_cndmask_b32_e64 v51, v208, v216, s[6:7]
	v_cndmask_b32_e64 v43, v209, v43, s[8:9]
	v_mov_b32_dpp v49, v41 row_ror:1 row_mask:0xf bank_mask:0xf
	v_cndmask_b32_e64 v52, v209, v217, s[6:7]
	v_cndmask_b32_e64 v53, v214, v222, s[6:7]
	v_mov_b32_dpp v41, v50 row_ror:15 row_mask:0xf bank_mask:0xf
	v_cndmask_b32_e64 v54, v215, v223, s[6:7]
	v_cndmask_b32_e64 v55, v212, v220, s[6:7]
	v_mov_b32_dpp v50, v42 row_ror:1 row_mask:0xf bank_mask:0xf
	v_cndmask_b32_e64 v98, v213, v221, s[6:7]
	v_cmp_gt_i32_e64 s[34:35], s54, v97
	v_mov_b32_dpp v42, v51 row_ror:15 row_mask:0xf bank_mask:0xf
	v_mov_b32_dpp v51, v43 row_ror:1 row_mask:0xf bank_mask:0xf
	v_mov_b32_dpp v43, v52 row_ror:15 row_mask:0xf bank_mask:0xf
	v_cndmask_b32_e64 v52, v214, v44, s[8:9]
	s_nop 1
	v_mov_b32_dpp v44, v52 row_ror:1 row_mask:0xf bank_mask:0xf
	v_mov_b32_dpp v52, v53 row_ror:15 row_mask:0xf bank_mask:0xf
	v_cndmask_b32_e64 v53, v215, v45, s[8:9]
	s_nop 1
	v_mov_b32_dpp v45, v53 row_ror:1 row_mask:0xf bank_mask:0xf
	v_mov_b32_dpp v53, v54 row_ror:15 row_mask:0xf bank_mask:0xf
	v_cndmask_b32_e64 v54, v212, v46, s[8:9]
	s_nop 1
	v_mov_b32_dpp v46, v54 row_ror:1 row_mask:0xf bank_mask:0xf
	v_mov_b32_dpp v54, v55 row_ror:15 row_mask:0xf bank_mask:0xf
	v_cndmask_b32_e64 v55, v213, v47, s[8:9]
	s_nop 1
	v_mov_b32_dpp v47, v55 row_ror:1 row_mask:0xf bank_mask:0xf
	v_mov_b32_dpp v55, v98 row_ror:15 row_mask:0xf bank_mask:0xf
	v_add_u32_e32 v98, 0x8f, v245
	v_cmp_gt_u32_e32 vcc, s55, v98
	s_and_b64 s[68:69], vcc, s[34:35]
	s_and_saveexec_b64 s[34:35], s[68:69]
	s_cbranch_execz .LBB0_724
	v_cndmask_b32_e64 v50, v50, 0, s[42:43]
	v_cndmask_b32_e64 v51, v51, 0, s[42:43]
	v_pk_mul_f32 v[50:51], v[74:75], v[50:51]
	v_cndmask_b32_e64 v42, v42, 0, s[28:29]
	v_pk_fma_f32 v[50:51], v[208:209], v[78:79], v[50:51]
	v_cndmask_b32_e64 v43, v43, 0, s[28:29]
	v_pk_fma_f32 v[42:43], v[70:71], v[42:43], v[50:51]
	v_cndmask_b32_e64 v48, v48, 0, s[42:43]
	v_pk_add_f32 v[42:43], v[66:67], v[42:43]
	v_cndmask_b32_e64 v49, v49, 0, s[42:43]
	v_mul_f32_e32 v50, 0xbfb8aa3b, v43
	v_exp_f32_e32 v50, v50
	v_pk_mul_f32 v[48:49], v[72:73], v[48:49]
	v_cndmask_b32_e64 v40, v40, 0, s[28:29]
	v_pk_fma_f32 v[48:49], v[210:211], v[76:77], v[48:49]
	v_cndmask_b32_e64 v41, v41, 0, s[28:29]
	v_pk_fma_f32 v[40:41], v[68:69], v[40:41], v[48:49]
	v_add_f32_e32 v48, 1.0, v50
	v_cndmask_b32_e64 v46, v46, 0, s[42:43]
	v_cndmask_b32_e64 v47, v47, 0, s[42:43]
	v_rcp_f32_e32 v48, v48
	v_mul_f32_e32 v49, 0xbfb8aa3b, v42
	v_pk_mul_f32 v[46:47], v[94:95], v[46:47]
	v_exp_f32_e32 v49, v49
	v_cndmask_b32_e64 v54, v54, 0, s[28:29]
	v_cndmask_b32_e64 v55, v55, 0, s[28:29]
	v_pk_fma_f32 v[46:47], v[212:213], v[90:91], v[46:47]
	v_pk_add_f32 v[40:41], v[64:65], v[40:41]
	v_pk_fma_f32 v[46:47], v[86:87], v[54:55], v[46:47]
	v_mul_f32_e32 v43, v43, v48
	v_pk_add_f32 v[46:47], v[82:83], v[46:47]
	v_mul_f32_e32 v48, 0xbfb8aa3b, v41
	v_mul_f32_e32 v43, v43, v47
	v_add_f32_e32 v47, 1.0, v49
	v_mul_f32_e32 v49, 0xbfb8aa3b, v40
	v_rcp_f32_e32 v47, v47
	v_exp_f32_e32 v48, v48
	v_exp_f32_e32 v49, v49
	v_cndmask_b32_e64 v44, v44, 0, s[42:43]
	v_mul_f32_e32 v42, v42, v47
	v_add_f32_e32 v47, 1.0, v48
	v_add_f32_e32 v48, 1.0, v49
	v_cndmask_b32_e64 v45, v45, 0, s[42:43]
	v_rcp_f32_e32 v47, v47
	v_rcp_f32_e32 v48, v48
	v_pk_mul_f32 v[44:45], v[92:93], v[44:45]
	v_cndmask_b32_e64 v52, v52, 0, s[28:29]
	v_cndmask_b32_e64 v53, v53, 0, s[28:29]
	v_pk_fma_f32 v[44:45], v[214:215], v[88:89], v[44:45]
	v_mul_f32_e32 v41, v41, v47
	v_pk_fma_f32 v[44:45], v[84:85], v[52:53], v[44:45]
	v_mul_f32_e32 v40, v40, v48
	v_pk_add_f32 v[44:45], v[80:81], v[44:45]
	v_mul_f32_e32 v42, v42, v46
	v_mul_f32_e32 v41, v41, v45
	v_mul_f32_e32 v40, v40, v44
	v_cvt_pk_bf16_f32 v40, v40, v41
	v_cvt_pk_bf16_f32 v41, v42, v43
	v_mov_b64_e32 v[42:43], s[88:89]
	s_movk_i32 s5, 0x1600
	v_mad_i64_i32 v[42:43], s[36:37], v97, s5, v[42:43]
	v_lshl_add_u64 v[42:43], v[190:191], 1, v[42:43]
	global_store_dwordx2 v[42:43], v[40:41], off
; __device__ __forceinline__ u32x2 pack4(f32x4 a) { u32x2 w; w.x = cvt_pk_bf16(a[0], a[1]); w.y = cvt_pk_bf16(a[2], a[3]); return w; }
; __device__ __forceinline__ float dpp_ror1(float v) { return __builtin_bit_cast(float, __builtin_amdgcn_update_dpp(0, __builtin_bit_cast(int, v), 0x121, 0xf, 0xf, false)); }
; __device__ __forceinline__ float dpp_ror15(float v) { return __builtin_bit_cast(float, __builtin_amdgcn_update_dpp(0, __builtin_bit_cast(int, v), 0x12F, 0xf, 0xf, false)); }
;     template <bool BND> __device__ __forceinline__ void conv_gate(f32x4 (&acc)[2][2][4][2], const Unit& u, int wr, int wc, int fr, int fq, int tok0, int pcol) const {
;     ...
;                 for (int m = 0; m < 4; ++m) {
;                     const int r = ai * 128 + wr * 64 + m * 16 + fr, tok = tok0 + r;
;                     bool isfirst = false, islast = false;
;                     if (BND) { const int S1 = (tok < NPROMPT ? SEQP : SEQS) - 1, pos = tok & S1; isfirst = pos == 0; islast = pos == S1; }
;                     f32x4 cv[2];
; #pragma unroll
;                     for (int bj = 0; bj < 2; ++bj) {
;                         const f32x4 cur = acc[ai][bj][m][n];
;                         const f32x4 ups = m > 0 ? acc[ai][bj][m > 0 ? m - 1 : 0][n] : pe[bj];
;                         const f32x4 dns = m < 3 ? acc[ai][bj][m < 3 ? m + 1 : 3][n] : ne[bj];
;                         f32x4 prev, next;
; #pragma unroll
;                         for (int j = 0; j < 4; ++j) {
;                             const float t1 = fr == 15 ? ups[j] : cur[j]; float pv = dpp_ror1(t1);
;                             const float t2 = fr == 0 ? dns[j] : cur[j]; float nx = dpp_ror15(t2);
;                             if (BND) { prev[j] = isfirst ? 0.f : pv; next[j] = islast ? 0.f : nx; } else { prev[j] = pv; next[j] = nx; }
;                         }
;                         cv[bj] = w0[bj] * prev + w1[bj] * cur + w2[bj] * next + bb[bj];
;                     }
;                     f32x4 a;
; #pragma unroll
;                     for (int j = 0; j < 4; ++j) { const float g = cv[0][j]; const float sg = __builtin_amdgcn_rcpf(1.0f + __builtin_amdgcn_exp2f(-1.4426950408889634f * g)); a[j] = g * sg * cv[1][j]; }
;                     if (r >= 1 && r <= 254 && (!BND || tok < MTOK)) *(u32x2*)(act + (size_t)tok * DFF + fcol + 4 * n) = pack4(a);
;                     asm volatile("" ::: "memory");
.LBB0_724:
	s_or_b64 exec, exec, s[34:35]
	v_add_u32_e32 v98, 0x9f, v107
	v_cmp_gt_i32_e32 vcc, s4, v98
	s_nop 1
	v_cndmask_b32_e32 v40, v243, v244, vcc
	v_and_b32_e32 v41, v40, v98
	v_cmp_eq_u32_e64 s[34:35], v41, v40
	v_cndmask_b32_e64 v40, v218, v210, s[8:9]
	v_cmp_eq_u32_e64 s[44:45], 0, v41
	v_cndmask_b32_e64 v41, v218, v56, s[6:7]
	v_mov_b32_dpp v43, v40 row_ror:1 row_mask:0xf bank_mask:0xf
	v_cndmask_b32_e64 v42, v219, v57, s[6:7]
	v_mov_b32_dpp v40, v41 row_ror:15 row_mask:0xf bank_mask:0xf
	v_cndmask_b32_e64 v41, v219, v211, s[8:9]
	v_cndmask_b32_e64 v44, v216, v58, s[6:7]
	s_nop 0
	v_mov_b32_dpp v45, v41 row_ror:1 row_mask:0xf bank_mask:0xf
	v_cndmask_b32_e64 v48, v217, v59, s[6:7]
	v_cndmask_b32_e64 v49, v222, v214, s[8:9]
	v_mov_b32_dpp v41, v42 row_ror:15 row_mask:0xf bank_mask:0xf
	v_cndmask_b32_e64 v42, v216, v208, s[8:9]
	v_cndmask_b32_e64 v51, v223, v215, s[8:9]
	s_nop 0
	v_mov_b32_dpp v46, v42 row_ror:1 row_mask:0xf bank_mask:0xf
	v_cndmask_b32_e64 v53, v220, v212, s[8:9]
	v_mov_b32_dpp v42, v44 row_ror:15 row_mask:0xf bank_mask:0xf
	v_cndmask_b32_e64 v44, v217, v209, s[8:9]
	v_cndmask_b32_e64 v55, v221, v213, s[8:9]
	s_nop 0
	v_mov_b32_dpp v47, v44 row_ror:1 row_mask:0xf bank_mask:0xf
	v_cndmask_b32_e64 v99, v221, v63, s[6:7]
	v_cmp_gt_i32_e64 s[36:37], s54, v98
	v_mov_b32_dpp v44, v48 row_ror:15 row_mask:0xf bank_mask:0xf
	v_mov_b32_dpp v48, v49 row_ror:1 row_mask:0xf bank_mask:0xf
	v_cndmask_b32_e64 v49, v222, v60, s[6:7]
	s_nop 1
	v_mov_b32_dpp v50, v49 row_ror:15 row_mask:0xf bank_mask:0xf
	v_mov_b32_dpp v49, v51 row_ror:1 row_mask:0xf bank_mask:0xf
	v_cndmask_b32_e64 v51, v223, v61, s[6:7]
	s_nop 1
	v_mov_b32_dpp v52, v51 row_ror:15 row_mask:0xf bank_mask:0xf
	v_mov_b32_dpp v51, v53 row_ror:1 row_mask:0xf bank_mask:0xf
	v_cndmask_b32_e64 v53, v220, v62, s[6:7]
	s_nop 1
	v_mov_b32_dpp v54, v53 row_ror:15 row_mask:0xf bank_mask:0xf
	v_mov_b32_dpp v53, v55 row_ror:1 row_mask:0xf bank_mask:0xf
	v_mov_b32_dpp v55, v99 row_ror:15 row_mask:0xf bank_mask:0xf
	v_add_u32_e32 v99, 0x9f, v245
	v_cmp_gt_u32_e32 vcc, s55, v99
	s_and_b64 s[70:71], vcc, s[36:37]
	s_and_saveexec_b64 s[36:37], s[70:71]
	s_cbranch_execz .LBB0_726
	v_cndmask_b32_e64 v46, v46, 0, s[44:45]
	v_cndmask_b32_e64 v47, v47, 0, s[44:45]
	v_pk_mul_f32 v[46:47], v[74:75], v[46:47]
	v_cndmask_b32_e64 v101, v52, 0, s[34:35]
	v_cndmask_b32_e64 v52, v43, 0, s[44:45]
	v_pk_fma_f32 v[46:47], v[216:217], v[78:79], v[46:47]
	v_cndmask_b32_e64 v42, v42, 0, s[34:35]
	v_cndmask_b32_e64 v43, v44, 0, s[34:35]
	v_pk_fma_f32 v[42:43], v[70:71], v[42:43], v[46:47]
	v_cndmask_b32_e64 v100, v50, 0, s[34:35]
	v_pk_add_f32 v[42:43], v[66:67], v[42:43]
	v_cndmask_b32_e64 v50, v51, 0, s[44:45]
	v_mul_f32_e32 v44, 0xbfb8aa3b, v43
	v_exp_f32_e32 v44, v44
	v_cndmask_b32_e64 v51, v53, 0, s[44:45]
	v_cndmask_b32_e64 v53, v45, 0, s[44:45]
	v_mul_f32_e32 v45, 0xbfb8aa3b, v42
	v_add_f32_e32 v44, 1.0, v44
	v_pk_mul_f32 v[52:53], v[72:73], v[52:53]
	v_rcp_f32_e32 v44, v44
	v_exp_f32_e32 v45, v45
	v_pk_fma_f32 v[52:53], v[218:219], v[76:77], v[52:53]
	v_cndmask_b32_e64 v40, v40, 0, s[34:35]
	v_cndmask_b32_e64 v41, v41, 0, s[34:35]
	v_pk_fma_f32 v[40:41], v[68:69], v[40:41], v[52:53]
	v_mul_f32_e32 v43, v43, v44
	v_pk_add_f32 v[40:41], v[64:65], v[40:41]
	v_add_f32_e32 v44, 1.0, v45
	v_mul_f32_e32 v45, 0xbfb8aa3b, v41
	v_mul_f32_e32 v46, 0xbfb8aa3b, v40
	v_rcp_f32_e32 v44, v44
	v_exp_f32_e32 v45, v45
	v_exp_f32_e32 v46, v46
	v_cndmask_b32_e64 v48, v48, 0, s[44:45]
	v_mul_f32_e32 v42, v42, v44
	v_add_f32_e32 v44, 1.0, v45
	v_add_f32_e32 v45, 1.0, v46
	v_cndmask_b32_e64 v49, v49, 0, s[44:45]
	v_rcp_f32_e32 v44, v44
	v_rcp_f32_e32 v45, v45
	v_pk_mul_f32 v[50:51], v[94:95], v[50:51]
	v_pk_mul_f32 v[48:49], v[92:93], v[48:49]
	v_cndmask_b32_e64 v54, v54, 0, s[34:35]
	v_cndmask_b32_e64 v55, v55, 0, s[34:35]
	v_pk_fma_f32 v[48:49], v[222:223], v[88:89], v[48:49]
	v_pk_fma_f32 v[50:51], v[220:221], v[90:91], v[50:51]
	v_pk_fma_f32 v[48:49], v[84:85], v[100:101], v[48:49]
	v_pk_fma_f32 v[50:51], v[86:87], v[54:55], v[50:51]
	v_pk_add_f32 v[48:49], v[80:81], v[48:49]
	v_pk_add_f32 v[50:51], v[82:83], v[50:51]
	v_mul_f32_e32 v41, v41, v44
	v_mul_f32_e32 v40, v40, v45
	v_mul_f32_e32 v43, v43, v51
	v_mul_f32_e32 v42, v42, v50
	v_mul_f32_e32 v41, v41, v49
	v_mul_f32_e32 v40, v40, v48
	v_cvt_pk_bf16_f32 v40, v40, v41
	v_cvt_pk_bf16_f32 v41, v42, v43
	v_mov_b64_e32 v[42:43], s[88:89]
	s_movk_i32 s5, 0x1600
	v_mad_i64_i32 v[42:43], s[46:47], v98, s5, v[42:43]
	v_lshl_add_u64 v[42:43], v[190:191], 1, v[42:43]
	global_store_dwordx2 v[42:43], v[40:41], off
; __device__ __forceinline__ u32x2 pack4(f32x4 a) { u32x2 w; w.x = cvt_pk_bf16(a[0], a[1]); w.y = cvt_pk_bf16(a[2], a[3]); return w; }
; __device__ __forceinline__ float dpp_ror1(float v) { return __builtin_bit_cast(float, __builtin_amdgcn_update_dpp(0, __builtin_bit_cast(int, v), 0x121, 0xf, 0xf, false)); }
; __device__ __forceinline__ float dpp_ror15(float v) { return __builtin_bit_cast(float, __builtin_amdgcn_update_dpp(0, __builtin_bit_cast(int, v), 0x12F, 0xf, 0xf, false)); }
;     template <bool BND> __device__ __forceinline__ void conv_gate(f32x4 (&acc)[2][2][4][2], const Unit& u, int wr, int wc, int fr, int fq, int tok0, int pcol) const {
;     ...
;                 for (int m = 0; m < 4; ++m) {
;                     const int r = ai * 128 + wr * 64 + m * 16 + fr, tok = tok0 + r;
;                     bool isfirst = false, islast = false;
;                     if (BND) { const int S1 = (tok < NPROMPT ? SEQP : SEQS) - 1, pos = tok & S1; isfirst = pos == 0; islast = pos == S1; }
;                     f32x4 cv[2];
; #pragma unroll
;                     for (int bj = 0; bj < 2; ++bj) {
;                         const f32x4 cur = acc[ai][bj][m][n];
;                         const f32x4 ups = m > 0 ? acc[ai][bj][m > 0 ? m - 1 : 0][n] : pe[bj];
;                         const f32x4 dns = m < 3 ? acc[ai][bj][m < 3 ? m + 1 : 3][n] : ne[bj];
;                         f32x4 prev, next;
; #pragma unroll
;                         for (int j = 0; j < 4; ++j) {
;                             const float t1 = fr == 15 ? ups[j] : cur[j]; float pv = dpp_ror1(t1);
;                             const float t2 = fr == 0 ? dns[j] : cur[j]; float nx = dpp_ror15(t2);
;                             if (BND) { prev[j] = isfirst ? 0.f : pv; next[j] = islast ? 0.f : nx; } else { prev[j] = pv; next[j] = nx; }
;                         }
;                         cv[bj] = w0[bj] * prev + w1[bj] * cur + w2[bj] * next + bb[bj];
;                     }
;                     f32x4 a;
; #pragma unroll
;                     for (int j = 0; j < 4; ++j) { const float g = cv[0][j]; const float sg = __builtin_amdgcn_rcpf(1.0f + __builtin_amdgcn_exp2f(-1.4426950408889634f * g)); a[j] = g * sg * cv[1][j]; }
;                     if (r >= 1 && r <= 254 && (!BND || tok < MTOK)) *(u32x2*)(act + (size_t)tok * DFF + fcol + 4 * n) = pack4(a);
;                     asm volatile("" ::: "memory");
.LBB0_726:
	s_or_b64 exec, exec, s[36:37]
	v_add_u32_e32 v99, 0xaf, v107
	v_cmp_gt_i32_e32 vcc, s4, v99
	v_cndmask_b32_e64 v42, v57, v219, s[8:9]
	v_cndmask_b32_e64 v43, v58, v216, s[8:9]
	v_cndmask_b32_e32 v40, v243, v244, vcc
	v_and_b32_e32 v41, v40, v99
	v_cmp_eq_u32_e64 s[46:47], 0, v41
	v_cmp_eq_u32_e64 s[36:37], v41, v40
	v_cndmask_b32_e64 v41, v56, v218, s[8:9]
	v_cndmask_b32_e64 v44, v59, v217, s[8:9]
	v_cndmask_b32_e64 v45, v60, v222, s[8:9]
	v_mov_b32_dpp v40, v41 row_ror:1 row_mask:0xf bank_mask:0xf
	v_cndmask_b32_e64 v41, v56, v32, s[6:7]
	v_cndmask_b32_e64 v36, v60, v36, s[6:7]
	v_cndmask_b32_e64 v46, v61, v223, s[8:9]
	v_mov_b32_dpp v32, v41 row_ror:15 row_mask:0xf bank_mask:0xf
	v_cndmask_b32_e64 v37, v61, v37, s[6:7]
	v_cndmask_b32_e64 v47, v62, v220, s[8:9]
	v_mov_b32_dpp v41, v42 row_ror:1 row_mask:0xf bank_mask:0xf
	v_cndmask_b32_e64 v42, v57, v33, s[6:7]
	v_cndmask_b32_e64 v38, v62, v38, s[6:7]
	v_cndmask_b32_e64 v48, v63, v221, s[8:9]
	v_mov_b32_dpp v33, v42 row_ror:15 row_mask:0xf bank_mask:0xf
	s_nop 1
	v_mov_b32_dpp v42, v43 row_ror:1 row_mask:0xf bank_mask:0xf
	v_cndmask_b32_e64 v43, v58, v34, s[6:7]
	s_nop 1
	v_mov_b32_dpp v34, v43 row_ror:15 row_mask:0xf bank_mask:0xf
	v_mov_b32_dpp v43, v44 row_ror:1 row_mask:0xf bank_mask:0xf
	v_cndmask_b32_e64 v44, v59, v35, s[6:7]
	s_nop 1
	v_mov_b32_dpp v35, v44 row_ror:15 row_mask:0xf bank_mask:0xf
	v_mov_b32_dpp v44, v45 row_ror:1 row_mask:0xf bank_mask:0xf
	v_mov_b32_dpp v45, v36 row_ror:15 row_mask:0xf bank_mask:0xf
	v_mov_b32_dpp v36, v46 row_ror:1 row_mask:0xf bank_mask:0xf
	v_mov_b32_dpp v46, v37 row_ror:15 row_mask:0xf bank_mask:0xf
	v_mov_b32_dpp v37, v47 row_ror:1 row_mask:0xf bank_mask:0xf
	v_mov_b32_dpp v47, v38 row_ror:15 row_mask:0xf bank_mask:0xf
	v_mov_b32_dpp v38, v48 row_ror:1 row_mask:0xf bank_mask:0xf
	v_cndmask_b32_e64 v48, v63, v39, s[6:7]
	s_nop 1
	v_mov_b32_dpp v39, v48 row_ror:15 row_mask:0xf bank_mask:0xf
	v_add_u32_e32 v48, 0xaf, v245
	v_cmp_gt_u32_e32 vcc, s55, v48
	v_cmp_gt_i32_e64 s[54:55], s54, v99
	s_and_b64 s[54:55], vcc, s[54:55]
	s_and_saveexec_b64 vcc, s[54:55]
	s_cbranch_execz .LBB0_728
	v_cndmask_b32_e64 v42, v42, 0, s[46:47]
	v_cndmask_b32_e64 v43, v43, 0, s[46:47]
	v_pk_mul_f32 v[42:43], v[74:75], v[42:43]
	v_cndmask_b32_e64 v34, v34, 0, s[36:37]
	v_pk_fma_f32 v[42:43], v[58:59], v[78:79], v[42:43]
	v_cndmask_b32_e64 v35, v35, 0, s[36:37]
	v_pk_fma_f32 v[34:35], v[70:71], v[34:35], v[42:43]
	v_cndmask_b32_e64 v40, v40, 0, s[46:47]
	v_pk_add_f32 v[34:35], v[66:67], v[34:35]
	v_cndmask_b32_e64 v41, v41, 0, s[46:47]
	v_mul_f32_e32 v42, 0xbfb8aa3b, v35
	v_exp_f32_e32 v42, v42
	v_pk_mul_f32 v[40:41], v[72:73], v[40:41]
	v_cndmask_b32_e64 v32, v32, 0, s[36:37]
	v_pk_fma_f32 v[40:41], v[56:57], v[76:77], v[40:41]
	v_cndmask_b32_e64 v33, v33, 0, s[36:37]
	v_pk_fma_f32 v[32:33], v[68:69], v[32:33], v[40:41]
	v_add_f32_e32 v40, 1.0, v42
	v_cndmask_b32_e64 v48, v45, 0, s[36:37]
	v_cndmask_b32_e64 v45, v36, 0, s[46:47]
	v_cndmask_b32_e64 v36, v37, 0, s[46:47]
	v_cndmask_b32_e64 v37, v38, 0, s[46:47]
	v_rcp_f32_e32 v40, v40
	v_mul_f32_e32 v41, 0xbfb8aa3b, v34
	v_pk_mul_f32 v[36:37], v[94:95], v[36:37]
	v_exp_f32_e32 v41, v41
	v_cndmask_b32_e64 v49, v46, 0, s[36:37]
	v_cndmask_b32_e64 v46, v47, 0, s[36:37]
	v_cndmask_b32_e64 v47, v39, 0, s[36:37]
	v_pk_fma_f32 v[36:37], v[62:63], v[90:91], v[36:37]
	v_pk_add_f32 v[32:33], v[64:65], v[32:33]
	v_pk_fma_f32 v[36:37], v[86:87], v[46:47], v[36:37]
	v_mul_f32_e32 v35, v35, v40
	v_pk_add_f32 v[36:37], v[82:83], v[36:37]
	v_mul_f32_e32 v40, 0xbfb8aa3b, v33
	v_mul_f32_e32 v35, v35, v37
	v_add_f32_e32 v37, 1.0, v41
	v_mul_f32_e32 v41, 0xbfb8aa3b, v32
	v_rcp_f32_e32 v37, v37
	v_exp_f32_e32 v40, v40
	v_exp_f32_e32 v41, v41
	v_cndmask_b32_e64 v44, v44, 0, s[46:47]
	v_mul_f32_e32 v34, v34, v37
	v_add_f32_e32 v37, 1.0, v40
	v_add_f32_e32 v40, 1.0, v41
	v_rcp_f32_e32 v37, v37
	v_rcp_f32_e32 v40, v40
	v_pk_mul_f32 v[38:39], v[92:93], v[44:45]
	v_mul_f32_e32 v34, v34, v36
	v_pk_fma_f32 v[38:39], v[60:61], v[88:89], v[38:39]
	v_mul_f32_e32 v33, v33, v37
	v_pk_fma_f32 v[38:39], v[84:85], v[48:49], v[38:39]
	v_mul_f32_e32 v32, v32, v40
	v_pk_add_f32 v[38:39], v[80:81], v[38:39]
	s_movk_i32 s4, 0x1600
	v_mul_f32_e32 v33, v33, v39
	v_mul_f32_e32 v32, v32, v38
	v_cvt_pk_bf16_f32 v32, v32, v33
	v_cvt_pk_bf16_f32 v33, v34, v35
	v_mov_b64_e32 v[34:35], s[88:89]
	v_mad_i64_i32 v[34:35], s[4:5], v99, s4, v[34:35]
	v_lshl_add_u64 v[34:35], v[190:191], 1, v[34:35]
	global_store_dwordx2 v[34:35], v[32:33], off

; __device__ __forceinline__ u32x2 pack4(f32x4 a) { u32x2 w; w.x = cvt_pk_bf16(a[0], a[1]); w.y = cvt_pk_bf16(a[2], a[3]); return w; }
; __device__ __forceinline__ float dpp_ror1(float v) { return __builtin_bit_cast(float, __builtin_amdgcn_update_dpp(0, __builtin_bit_cast(int, v), 0x121, 0xf, 0xf, false)); }
; __device__ __forceinline__ float dpp_ror15(float v) { return __builtin_bit_cast(float, __builtin_amdgcn_update_dpp(0, __builtin_bit_cast(int, v), 0x12F, 0xf, 0xf, false)); }
;     template <bool BND> __device__ __forceinline__ void conv_gate(f32x4 (&acc)[2][2][4][2], const Unit& u, int wr, int wc, int fr, int fq, int tok0, int pcol) const {
;     ...
;                 for (int m = 0; m < 4; ++m) {
;                     const int r = ai * 128 + wr * 64 + m * 16 + fr, tok = tok0 + r;
;                     bool isfirst = false, islast = false;
;                     if (BND) { const int S1 = (tok < NPROMPT ? SEQP : SEQS) - 1, pos = tok & S1; isfirst = pos == 0; islast = pos == S1; }
;                     f32x4 cv[2];
; #pragma unroll
;                     for (int bj = 0; bj < 2; ++bj) {
;                         const f32x4 cur = acc[ai][bj][m][n];
;                         const f32x4 ups = m > 0 ? acc[ai][bj][m > 0 ? m - 1 : 0][n] : pe[bj];
;                         const f32x4 dns = m < 3 ? acc[ai][bj][m < 3 ? m + 1 : 3][n] : ne[bj];
;                         f32x4 prev, next;
; #pragma unroll
;                         for (int j = 0; j < 4; ++j) {
;                             const float t1 = fr == 15 ? ups[j] : cur[j]; float pv = dpp_ror1(t1);
;                             const float t2 = fr == 0 ? dns[j] : cur[j]; float nx = dpp_ror15(t2);
;                             if (BND) { prev[j] = isfirst ? 0.f : pv; next[j] = islast ? 0.f : nx; } else { prev[j] = pv; next[j] = nx; }
;                         }
;                         cv[bj] = w0[bj] * prev + w1[bj] * cur + w2[bj] * next + bb[bj];
;                     }
;                     f32x4 a;
; #pragma unroll
;                     for (int j = 0; j < 4; ++j) { const float g = cv[0][j]; const float sg = __builtin_amdgcn_rcpf(1.0f + __builtin_amdgcn_exp2f(-1.4426950408889634f * g)); a[j] = g * sg * cv[1][j]; }
;                     if (r >= 1 && r <= 254 && (!BND || tok < MTOK)) *(u32x2*)(act + (size_t)tok * DFF + fcol + 4 * n) = pack4(a);
;                     asm volatile("" ::: "memory");
.LBB0_736:
	s_waitcnt lgkmcnt(0)
	v_cndmask_b32_e64 v72, v0, v72, s[8:9]
	v_cndmask_b32_e64 v81, v0, v160, s[6:7]
	v_cndmask_b32_e64 v73, v1, v73, s[8:9]
	v_mov_b32_dpp v80, v72 row_ror:1 row_mask:0xf bank_mask:0xf
	v_cndmask_b32_e64 v82, v1, v161, s[6:7]
	v_cndmask_b32_e64 v74, v2, v74, s[8:9]
	v_mov_b32_dpp v72, v81 row_ror:15 row_mask:0xf bank_mask:0xf
	v_cndmask_b32_e64 v83, v2, v158, s[6:7]
	v_cndmask_b32_e64 v75, v3, v75, s[8:9]
	v_mov_b32_dpp v81, v73 row_ror:1 row_mask:0xf bank_mask:0xf
	v_cndmask_b32_e64 v84, v3, v159, s[6:7]
	v_cndmask_b32_e64 v85, v4, v164, s[6:7]
	v_mov_b32_dpp v73, v82 row_ror:15 row_mask:0xf bank_mask:0xf
	v_cndmask_b32_e64 v86, v5, v165, s[6:7]
	v_cndmask_b32_e64 v87, v6, v162, s[6:7]
	v_mov_b32_dpp v82, v74 row_ror:1 row_mask:0xf bank_mask:0xf
	v_cndmask_b32_e64 v88, v7, v163, s[6:7]
	s_nop 0
	v_mov_b32_dpp v74, v83 row_ror:15 row_mask:0xf bank_mask:0xf
	v_mov_b32_dpp v83, v75 row_ror:1 row_mask:0xf bank_mask:0xf
	v_mov_b32_dpp v75, v84 row_ror:15 row_mask:0xf bank_mask:0xf
	v_cndmask_b32_e64 v84, v4, v76, s[8:9]
	s_nop 1
	v_mov_b32_dpp v76, v84 row_ror:1 row_mask:0xf bank_mask:0xf
	v_mov_b32_dpp v84, v85 row_ror:15 row_mask:0xf bank_mask:0xf
	v_cndmask_b32_e64 v85, v5, v77, s[8:9]
	s_nop 1
	v_mov_b32_dpp v77, v85 row_ror:1 row_mask:0xf bank_mask:0xf
	v_mov_b32_dpp v85, v86 row_ror:15 row_mask:0xf bank_mask:0xf
	v_cndmask_b32_e64 v86, v6, v78, s[8:9]
	s_nop 1
	v_mov_b32_dpp v78, v86 row_ror:1 row_mask:0xf bank_mask:0xf
	v_mov_b32_dpp v86, v87 row_ror:15 row_mask:0xf bank_mask:0xf
	v_cndmask_b32_e64 v87, v7, v79, s[8:9]
	s_nop 1
	v_mov_b32_dpp v79, v87 row_ror:1 row_mask:0xf bank_mask:0xf
	v_mov_b32_dpp v87, v88 row_ror:15 row_mask:0xf bank_mask:0xf
	s_and_saveexec_b64 s[10:11], s[0:1]
	s_mov_b32 s38, s93
	s_cbranch_execz .LBB0_738
	v_cndmask_b32_e64 v82, v82, 0, s[20:21]
	v_cndmask_b32_e64 v83, v83, 0, s[20:21]
	s_waitcnt vmcnt(7)
	v_pk_mul_f32 v[82:83], v[42:43], v[82:83]
	v_cndmask_b32_e64 v74, v74, 0, s[12:13]
	s_waitcnt vmcnt(6)
	v_pk_fma_f32 v[82:83], v[2:3], v[46:47], v[82:83]
	v_cndmask_b32_e64 v75, v75, 0, s[12:13]
	s_waitcnt vmcnt(5)
	v_pk_fma_f32 v[74:75], v[38:39], v[74:75], v[82:83]
	v_cndmask_b32_e64 v80, v80, 0, s[20:21]
	s_waitcnt vmcnt(4)
	v_pk_add_f32 v[74:75], v[34:35], v[74:75]
	v_cndmask_b32_e64 v81, v81, 0, s[20:21]
	v_mul_f32_e32 v82, 0xbfb8aa3b, v75
	v_exp_f32_e32 v82, v82
	v_pk_mul_f32 v[80:81], v[40:41], v[80:81]
	v_cndmask_b32_e64 v72, v72, 0, s[12:13]
	v_pk_fma_f32 v[80:81], v[0:1], v[44:45], v[80:81]
	v_cndmask_b32_e64 v73, v73, 0, s[12:13]
	v_pk_fma_f32 v[72:73], v[36:37], v[72:73], v[80:81]
	v_add_f32_e32 v80, 1.0, v82
	v_cndmask_b32_e64 v78, v78, 0, s[20:21]
	v_cndmask_b32_e64 v79, v79, 0, s[20:21]
	v_rcp_f32_e32 v80, v80
	v_mul_f32_e32 v81, 0xbfb8aa3b, v74
	s_waitcnt vmcnt(3)
	v_pk_mul_f32 v[78:79], v[62:63], v[78:79]
	v_exp_f32_e32 v81, v81
	v_cndmask_b32_e64 v86, v86, 0, s[12:13]
	v_cndmask_b32_e64 v87, v87, 0, s[12:13]
	s_waitcnt vmcnt(2)
	v_pk_fma_f32 v[78:79], v[6:7], v[58:59], v[78:79]
	v_pk_add_f32 v[72:73], v[32:33], v[72:73]
	s_waitcnt vmcnt(1)
	v_pk_fma_f32 v[78:79], v[54:55], v[86:87], v[78:79]
	v_mul_f32_e32 v75, v75, v80
	s_waitcnt vmcnt(0)
	v_pk_add_f32 v[78:79], v[50:51], v[78:79]
	v_mul_f32_e32 v80, 0xbfb8aa3b, v73
	v_mul_f32_e32 v75, v75, v79
	v_add_f32_e32 v79, 1.0, v81
	v_mul_f32_e32 v81, 0xbfb8aa3b, v72
	v_rcp_f32_e32 v79, v79
	v_exp_f32_e32 v80, v80
	v_exp_f32_e32 v81, v81
	v_cndmask_b32_e64 v76, v76, 0, s[20:21]
	v_mul_f32_e32 v74, v74, v79
	v_add_f32_e32 v79, 1.0, v80
	v_add_f32_e32 v80, 1.0, v81
	v_cndmask_b32_e64 v77, v77, 0, s[20:21]
	v_rcp_f32_e32 v79, v79
	v_rcp_f32_e32 v80, v80
	v_pk_mul_f32 v[76:77], v[60:61], v[76:77]
	v_cndmask_b32_e64 v84, v84, 0, s[12:13]
	v_cndmask_b32_e64 v85, v85, 0, s[12:13]
	v_pk_fma_f32 v[76:77], v[4:5], v[56:57], v[76:77]
	v_mul_f32_e32 v73, v73, v79
	v_pk_fma_f32 v[76:77], v[52:53], v[84:85], v[76:77]
	v_mul_f32_e32 v72, v72, v80
	v_pk_add_f32 v[76:77], v[48:49], v[76:77]
	v_mul_f32_e32 v74, v74, v78
	v_mul_f32_e32 v73, v73, v77
	v_mul_f32_e32 v72, v72, v76
	v_cvt_pk_bf16_f32 v72, v72, v73
	v_cvt_pk_bf16_f32 v73, v74, v75
	v_mov_b64_e32 v[74:75], s[88:89]
	s_movk_i32 s0, 0x1600
	v_mad_i64_i32 v[74:75], s[0:1], v152, s0, v[74:75]
	v_lshl_add_u64 v[74:75], v[190:191], 1, v[74:75]
	global_store_dwordx2 v[74:75], v[72:73], off offset:8
; __device__ __forceinline__ u32x2 pack4(f32x4 a) { u32x2 w; w.x = cvt_pk_bf16(a[0], a[1]); w.y = cvt_pk_bf16(a[2], a[3]); return w; }
; __device__ __forceinline__ float dpp_ror1(float v) { return __builtin_bit_cast(float, __builtin_amdgcn_update_dpp(0, __builtin_bit_cast(int, v), 0x121, 0xf, 0xf, false)); }
; __device__ __forceinline__ float dpp_ror15(float v) { return __builtin_bit_cast(float, __builtin_amdgcn_update_dpp(0, __builtin_bit_cast(int, v), 0x12F, 0xf, 0xf, false)); }
;     template <bool BND> __device__ __forceinline__ void conv_gate(f32x4 (&acc)[2][2][4][2], const Unit& u, int wr, int wc, int fr, int fq, int tok0, int pcol) const {
;     ...
;                 for (int m = 0; m < 4; ++m) {
;                     const int r = ai * 128 + wr * 64 + m * 16 + fr, tok = tok0 + r;
;                     bool isfirst = false, islast = false;
;                     if (BND) { const int S1 = (tok < NPROMPT ? SEQP : SEQS) - 1, pos = tok & S1; isfirst = pos == 0; islast = pos == S1; }
;                     f32x4 cv[2];
; #pragma unroll
;                     for (int bj = 0; bj < 2; ++bj) {
;                         const f32x4 cur = acc[ai][bj][m][n];
;                         const f32x4 ups = m > 0 ? acc[ai][bj][m > 0 ? m - 1 : 0][n] : pe[bj];
;                         const f32x4 dns = m < 3 ? acc[ai][bj][m < 3 ? m + 1 : 3][n] : ne[bj];
;                         f32x4 prev, next;
; #pragma unroll
;                         for (int j = 0; j < 4; ++j) {
;                             const float t1 = fr == 15 ? ups[j] : cur[j]; float pv = dpp_ror1(t1);
;                             const float t2 = fr == 0 ? dns[j] : cur[j]; float nx = dpp_ror15(t2);
;                             if (BND) { prev[j] = isfirst ? 0.f : pv; next[j] = islast ? 0.f : nx; } else { prev[j] = pv; next[j] = nx; }
;                         }
;                         cv[bj] = w0[bj] * prev + w1[bj] * cur + w2[bj] * next + bb[bj];
;                     }
;                     f32x4 a;
; #pragma unroll
;                     for (int j = 0; j < 4; ++j) { const float g = cv[0][j]; const float sg = __builtin_amdgcn_rcpf(1.0f + __builtin_amdgcn_exp2f(-1.4426950408889634f * g)); a[j] = g * sg * cv[1][j]; }
;                     if (r >= 1 && r <= 254 && (!BND || tok < MTOK)) *(u32x2*)(act + (size_t)tok * DFF + fcol + 4 * n) = pack4(a);
;                     asm volatile("" ::: "memory");
.LBB0_738:
	s_or_b64 exec, exec, s[10:11]
	v_cndmask_b32_e64 v0, v160, v0, s[8:9]
	v_cndmask_b32_e64 v73, v160, v168, s[6:7]
	v_cndmask_b32_e64 v1, v161, v1, s[8:9]
	v_mov_b32_dpp v72, v0 row_ror:1 row_mask:0xf bank_mask:0xf
	v_cndmask_b32_e64 v74, v161, v169, s[6:7]
	v_cndmask_b32_e64 v2, v158, v2, s[8:9]
	v_mov_b32_dpp v0, v73 row_ror:15 row_mask:0xf bank_mask:0xf
	v_cndmask_b32_e64 v75, v158, v166, s[6:7]
	v_cndmask_b32_e64 v3, v159, v3, s[8:9]
	v_mov_b32_dpp v73, v1 row_ror:1 row_mask:0xf bank_mask:0xf
	v_cndmask_b32_e64 v76, v159, v167, s[6:7]
	v_cndmask_b32_e64 v77, v164, v172, s[6:7]
	v_mov_b32_dpp v1, v74 row_ror:15 row_mask:0xf bank_mask:0xf
	v_cndmask_b32_e64 v78, v165, v173, s[6:7]
	v_cndmask_b32_e64 v79, v162, v170, s[6:7]
	v_mov_b32_dpp v74, v2 row_ror:1 row_mask:0xf bank_mask:0xf
	v_cndmask_b32_e64 v80, v163, v171, s[6:7]
	s_nop 0
	v_mov_b32_dpp v2, v75 row_ror:15 row_mask:0xf bank_mask:0xf
	v_mov_b32_dpp v75, v3 row_ror:1 row_mask:0xf bank_mask:0xf
	v_mov_b32_dpp v3, v76 row_ror:15 row_mask:0xf bank_mask:0xf
	v_cndmask_b32_e64 v76, v164, v4, s[8:9]
	s_nop 1
	v_mov_b32_dpp v4, v76 row_ror:1 row_mask:0xf bank_mask:0xf
	v_mov_b32_dpp v76, v77 row_ror:15 row_mask:0xf bank_mask:0xf
	v_cndmask_b32_e64 v77, v165, v5, s[8:9]
	s_nop 1
	v_mov_b32_dpp v5, v77 row_ror:1 row_mask:0xf bank_mask:0xf
	v_mov_b32_dpp v77, v78 row_ror:15 row_mask:0xf bank_mask:0xf
	v_cndmask_b32_e64 v78, v162, v6, s[8:9]
	s_nop 1
	v_mov_b32_dpp v6, v78 row_ror:1 row_mask:0xf bank_mask:0xf
	v_mov_b32_dpp v78, v79 row_ror:15 row_mask:0xf bank_mask:0xf
	v_cndmask_b32_e64 v79, v163, v7, s[8:9]
	s_nop 1
	v_mov_b32_dpp v7, v79 row_ror:1 row_mask:0xf bank_mask:0xf
	v_mov_b32_dpp v79, v80 row_ror:15 row_mask:0xf bank_mask:0xf
	s_and_saveexec_b64 s[0:1], s[52:53]
	v_readlane_b32 s62, v255, 36
	v_readlane_b32 s93, v255, 38
	v_readlane_b32 s63, v255, 37
	s_cbranch_execz .LBB0_740
	v_cndmask_b32_e64 v74, v74, 0, s[22:23]
	v_cndmask_b32_e64 v75, v75, 0, s[22:23]
	s_waitcnt vmcnt(7)
	v_pk_mul_f32 v[74:75], v[42:43], v[74:75]
	v_cndmask_b32_e64 v2, v2, 0, s[14:15]
	s_waitcnt vmcnt(6)
	v_pk_fma_f32 v[74:75], v[158:159], v[46:47], v[74:75]
	v_cndmask_b32_e64 v3, v3, 0, s[14:15]
	s_waitcnt vmcnt(5)
	v_pk_fma_f32 v[2:3], v[38:39], v[2:3], v[74:75]
	v_cndmask_b32_e64 v72, v72, 0, s[22:23]
	s_waitcnt vmcnt(4)
	v_pk_add_f32 v[2:3], v[34:35], v[2:3]
	v_cndmask_b32_e64 v73, v73, 0, s[22:23]
	v_mul_f32_e32 v74, 0xbfb8aa3b, v3
	v_exp_f32_e32 v74, v74
	v_pk_mul_f32 v[72:73], v[40:41], v[72:73]
	v_cndmask_b32_e64 v0, v0, 0, s[14:15]
	v_pk_fma_f32 v[72:73], v[160:161], v[44:45], v[72:73]
	v_cndmask_b32_e64 v1, v1, 0, s[14:15]
	v_pk_fma_f32 v[0:1], v[36:37], v[0:1], v[72:73]
	v_add_f32_e32 v72, 1.0, v74
	v_cndmask_b32_e64 v6, v6, 0, s[22:23]
	v_cndmask_b32_e64 v7, v7, 0, s[22:23]
	v_rcp_f32_e32 v72, v72
	v_mul_f32_e32 v73, 0xbfb8aa3b, v2
	s_waitcnt vmcnt(3)
	v_pk_mul_f32 v[6:7], v[62:63], v[6:7]
	v_exp_f32_e32 v73, v73
	v_cndmask_b32_e64 v78, v78, 0, s[14:15]
	v_cndmask_b32_e64 v79, v79, 0, s[14:15]
	s_waitcnt vmcnt(2)
	v_pk_fma_f32 v[6:7], v[162:163], v[58:59], v[6:7]
	v_pk_add_f32 v[0:1], v[32:33], v[0:1]
	s_waitcnt vmcnt(1)
	v_pk_fma_f32 v[6:7], v[54:55], v[78:79], v[6:7]
	v_mul_f32_e32 v3, v3, v72
	s_waitcnt vmcnt(0)
	v_pk_add_f32 v[6:7], v[50:51], v[6:7]
	v_mul_f32_e32 v72, 0xbfb8aa3b, v1
	v_mul_f32_e32 v3, v3, v7
	v_add_f32_e32 v7, 1.0, v73
	v_mul_f32_e32 v73, 0xbfb8aa3b, v0
	v_rcp_f32_e32 v7, v7
	v_exp_f32_e32 v72, v72
	v_exp_f32_e32 v73, v73
	v_cndmask_b32_e64 v4, v4, 0, s[22:23]
	v_mul_f32_e32 v2, v2, v7
	v_add_f32_e32 v7, 1.0, v72
	v_add_f32_e32 v72, 1.0, v73
	v_cndmask_b32_e64 v5, v5, 0, s[22:23]
	v_rcp_f32_e32 v7, v7
	v_rcp_f32_e32 v72, v72
	v_pk_mul_f32 v[4:5], v[60:61], v[4:5]
	v_cndmask_b32_e64 v76, v76, 0, s[14:15]
	v_cndmask_b32_e64 v77, v77, 0, s[14:15]
	v_pk_fma_f32 v[4:5], v[164:165], v[56:57], v[4:5]
	v_mul_f32_e32 v1, v1, v7
	v_pk_fma_f32 v[4:5], v[52:53], v[76:77], v[4:5]
	v_mul_f32_e32 v0, v0, v72
	v_pk_add_f32 v[4:5], v[48:49], v[4:5]
	v_mul_f32_e32 v2, v2, v6
	v_mul_f32_e32 v1, v1, v5
	v_mul_f32_e32 v0, v0, v4
	v_cvt_pk_bf16_f32 v0, v0, v1
	v_cvt_pk_bf16_f32 v1, v2, v3
	v_mov_b64_e32 v[2:3], s[88:89]
	s_movk_i32 s4, 0x1600
	v_mad_i64_i32 v[2:3], s[4:5], v104, s4, v[2:3]
	v_lshl_add_u64 v[2:3], v[190:191], 1, v[2:3]
	global_store_dwordx2 v[2:3], v[0:1], off offset:8
; __device__ __forceinline__ u32x2 pack4(f32x4 a) { u32x2 w; w.x = cvt_pk_bf16(a[0], a[1]); w.y = cvt_pk_bf16(a[2], a[3]); return w; }
; __device__ __forceinline__ float dpp_ror1(float v) { return __builtin_bit_cast(float, __builtin_amdgcn_update_dpp(0, __builtin_bit_cast(int, v), 0x121, 0xf, 0xf, false)); }
; __device__ __forceinline__ float dpp_ror15(float v) { return __builtin_bit_cast(float, __builtin_amdgcn_update_dpp(0, __builtin_bit_cast(int, v), 0x12F, 0xf, 0xf, false)); }
;     template <bool BND> __device__ __forceinline__ void conv_gate(f32x4 (&acc)[2][2][4][2], const Unit& u, int wr, int wc, int fr, int fq, int tok0, int pcol) const {
;     ...
;                 for (int m = 0; m < 4; ++m) {
;                     const int r = ai * 128 + wr * 64 + m * 16 + fr, tok = tok0 + r;
;                     bool isfirst = false, islast = false;
;                     if (BND) { const int S1 = (tok < NPROMPT ? SEQP : SEQS) - 1, pos = tok & S1; isfirst = pos == 0; islast = pos == S1; }
;                     f32x4 cv[2];
; #pragma unroll
;                     for (int bj = 0; bj < 2; ++bj) {
;                         const f32x4 cur = acc[ai][bj][m][n];
;                         const f32x4 ups = m > 0 ? acc[ai][bj][m > 0 ? m - 1 : 0][n] : pe[bj];
;                         const f32x4 dns = m < 3 ? acc[ai][bj][m < 3 ? m + 1 : 3][n] : ne[bj];
;                         f32x4 prev, next;
; #pragma unroll
;                         for (int j = 0; j < 4; ++j) {
;                             const float t1 = fr == 15 ? ups[j] : cur[j]; float pv = dpp_ror1(t1);
;                             const float t2 = fr == 0 ? dns[j] : cur[j]; float nx = dpp_ror15(t2);
;                             if (BND) { prev[j] = isfirst ? 0.f : pv; next[j] = islast ? 0.f : nx; } else { prev[j] = pv; next[j] = nx; }
;                         }
;                         cv[bj] = w0[bj] * prev + w1[bj] * cur + w2[bj] * next + bb[bj];
;                     }
;                     f32x4 a;
; #pragma unroll
;                     for (int j = 0; j < 4; ++j) { const float g = cv[0][j]; const float sg = __builtin_amdgcn_rcpf(1.0f + __builtin_amdgcn_exp2f(-1.4426950408889634f * g)); a[j] = g * sg * cv[1][j]; }
;                     if (r >= 1 && r <= 254 && (!BND || tok < MTOK)) *(u32x2*)(act + (size_t)tok * DFF + fcol + 4 * n) = pack4(a);
;                     asm volatile("" ::: "memory");
.LBB0_740:
	s_or_b64 exec, exec, s[0:1]
	v_cndmask_b32_e64 v0, v168, v160, s[8:9]
	v_cndmask_b32_e64 v1, v168, v16, s[6:7]
	s_nop 0
	v_mov_b32_dpp v3, v0 row_ror:1 row_mask:0xf bank_mask:0xf
	v_cndmask_b32_e64 v2, v169, v17, s[6:7]
	v_mov_b32_dpp v0, v1 row_ror:15 row_mask:0xf bank_mask:0xf
	v_cndmask_b32_e64 v1, v169, v161, s[8:9]
	v_cndmask_b32_e64 v4, v166, v18, s[6:7]
	s_nop 0
	v_mov_b32_dpp v5, v1 row_ror:1 row_mask:0xf bank_mask:0xf
	v_cndmask_b32_e64 v72, v167, v19, s[6:7]
	v_cndmask_b32_e64 v73, v172, v164, s[8:9]
	v_mov_b32_dpp v1, v2 row_ror:15 row_mask:0xf bank_mask:0xf
	v_cndmask_b32_e64 v2, v166, v158, s[8:9]
	v_cndmask_b32_e64 v75, v173, v165, s[8:9]
	s_nop 0
	v_mov_b32_dpp v6, v2 row_ror:1 row_mask:0xf bank_mask:0xf
	v_cndmask_b32_e64 v77, v170, v162, s[8:9]
	v_mov_b32_dpp v2, v4 row_ror:15 row_mask:0xf bank_mask:0xf
	v_cndmask_b32_e64 v4, v167, v159, s[8:9]
	v_cndmask_b32_e64 v79, v171, v163, s[8:9]
	s_nop 0
	v_mov_b32_dpp v7, v4 row_ror:1 row_mask:0xf bank_mask:0xf
	v_cndmask_b32_e64 v80, v171, v23, s[6:7]
	s_nop 0
	v_mov_b32_dpp v4, v72 row_ror:15 row_mask:0xf bank_mask:0xf
	v_mov_b32_dpp v72, v73 row_ror:1 row_mask:0xf bank_mask:0xf
	v_cndmask_b32_e64 v73, v172, v20, s[6:7]
	s_nop 1
	v_mov_b32_dpp v74, v73 row_ror:15 row_mask:0xf bank_mask:0xf
	v_mov_b32_dpp v73, v75 row_ror:1 row_mask:0xf bank_mask:0xf
	v_cndmask_b32_e64 v75, v173, v21, s[6:7]
	s_nop 1
	v_mov_b32_dpp v76, v75 row_ror:15 row_mask:0xf bank_mask:0xf
	v_mov_b32_dpp v75, v77 row_ror:1 row_mask:0xf bank_mask:0xf
	v_cndmask_b32_e64 v77, v170, v22, s[6:7]
	s_nop 1
	v_mov_b32_dpp v78, v77 row_ror:15 row_mask:0xf bank_mask:0xf
	v_mov_b32_dpp v77, v79 row_ror:1 row_mask:0xf bank_mask:0xf
	v_mov_b32_dpp v79, v80 row_ror:15 row_mask:0xf bank_mask:0xf
	s_and_saveexec_b64 s[0:1], s[84:85]
	s_cbranch_execz .LBB0_742
	v_cndmask_b32_e64 v6, v6, 0, s[26:27]
	v_cndmask_b32_e64 v7, v7, 0, s[26:27]
	s_waitcnt vmcnt(7)
	v_pk_mul_f32 v[6:7], v[42:43], v[6:7]
	v_cndmask_b32_e64 v81, v76, 0, s[16:17]
	v_cndmask_b32_e64 v76, v3, 0, s[26:27]
	s_waitcnt vmcnt(6)
	v_pk_fma_f32 v[6:7], v[166:167], v[46:47], v[6:7]
	v_cndmask_b32_e64 v2, v2, 0, s[16:17]
	v_cndmask_b32_e64 v3, v4, 0, s[16:17]
	s_waitcnt vmcnt(5)
	v_pk_fma_f32 v[2:3], v[38:39], v[2:3], v[6:7]
	v_cndmask_b32_e64 v80, v74, 0, s[16:17]
	s_waitcnt vmcnt(4)
	v_pk_add_f32 v[2:3], v[34:35], v[2:3]
	v_cndmask_b32_e64 v74, v75, 0, s[26:27]
	v_mul_f32_e32 v4, 0xbfb8aa3b, v3
	v_exp_f32_e32 v4, v4
	v_cndmask_b32_e64 v75, v77, 0, s[26:27]
	v_cndmask_b32_e64 v77, v5, 0, s[26:27]
	v_mul_f32_e32 v5, 0xbfb8aa3b, v2
	v_add_f32_e32 v4, 1.0, v4
	v_pk_mul_f32 v[76:77], v[40:41], v[76:77]
	v_rcp_f32_e32 v4, v4
	v_exp_f32_e32 v5, v5
	v_pk_fma_f32 v[76:77], v[168:169], v[44:45], v[76:77]
	v_cndmask_b32_e64 v0, v0, 0, s[16:17]
	v_cndmask_b32_e64 v1, v1, 0, s[16:17]
	v_pk_fma_f32 v[0:1], v[36:37], v[0:1], v[76:77]
	v_mul_f32_e32 v3, v3, v4
	v_pk_add_f32 v[0:1], v[32:33], v[0:1]
	v_add_f32_e32 v4, 1.0, v5
	v_mul_f32_e32 v5, 0xbfb8aa3b, v1
	v_mul_f32_e32 v6, 0xbfb8aa3b, v0
	v_rcp_f32_e32 v4, v4
	v_exp_f32_e32 v5, v5
	v_exp_f32_e32 v6, v6
	v_cndmask_b32_e64 v72, v72, 0, s[26:27]
	v_mul_f32_e32 v2, v2, v4
	v_add_f32_e32 v4, 1.0, v5
	v_add_f32_e32 v5, 1.0, v6
	v_cndmask_b32_e64 v73, v73, 0, s[26:27]
	v_rcp_f32_e32 v4, v4
	v_rcp_f32_e32 v5, v5
	s_waitcnt vmcnt(3)
	v_pk_mul_f32 v[74:75], v[62:63], v[74:75]
	v_pk_mul_f32 v[72:73], v[60:61], v[72:73]
	v_cndmask_b32_e64 v78, v78, 0, s[16:17]
	v_cndmask_b32_e64 v79, v79, 0, s[16:17]
	s_waitcnt vmcnt(2)
	v_pk_fma_f32 v[72:73], v[172:173], v[56:57], v[72:73]
	v_pk_fma_f32 v[74:75], v[170:171], v[58:59], v[74:75]
	s_waitcnt vmcnt(1)
	v_pk_fma_f32 v[72:73], v[52:53], v[80:81], v[72:73]
	v_pk_fma_f32 v[74:75], v[54:55], v[78:79], v[74:75]
	s_waitcnt vmcnt(0)
	v_pk_add_f32 v[72:73], v[48:49], v[72:73]
	v_pk_add_f32 v[74:75], v[50:51], v[74:75]
	v_mul_f32_e32 v1, v1, v4
	v_mul_f32_e32 v0, v0, v5
	v_mul_f32_e32 v3, v3, v75
	v_mul_f32_e32 v2, v2, v74
	v_mul_f32_e32 v1, v1, v73
	v_mul_f32_e32 v0, v0, v72
	v_cvt_pk_bf16_f32 v0, v0, v1
	v_cvt_pk_bf16_f32 v1, v2, v3
	v_mov_b64_e32 v[2:3], s[88:89]
	s_movk_i32 s4, 0x1600
	v_mad_i64_i32 v[2:3], s[4:5], v105, s4, v[2:3]
	v_lshl_add_u64 v[2:3], v[190:191], 1, v[2:3]
	global_store_dwordx2 v[2:3], v[0:1], off offset:8
; __device__ __forceinline__ u32x2 pack4(f32x4 a) { u32x2 w; w.x = cvt_pk_bf16(a[0], a[1]); w.y = cvt_pk_bf16(a[2], a[3]); return w; }
; __device__ __forceinline__ float dpp_ror1(float v) { return __builtin_bit_cast(float, __builtin_amdgcn_update_dpp(0, __builtin_bit_cast(int, v), 0x121, 0xf, 0xf, false)); }
; __device__ __forceinline__ float dpp_ror15(float v) { return __builtin_bit_cast(float, __builtin_amdgcn_update_dpp(0, __builtin_bit_cast(int, v), 0x12F, 0xf, 0xf, false)); }
;     template <bool BND> __device__ __forceinline__ void conv_gate(f32x4 (&acc)[2][2][4][2], const Unit& u, int wr, int wc, int fr, int fq, int tok0, int pcol) const {
;     ...
;                 for (int m = 0; m < 4; ++m) {
;                     const int r = ai * 128 + wr * 64 + m * 16 + fr, tok = tok0 + r;
;                     bool isfirst = false, islast = false;
;                     if (BND) { const int S1 = (tok < NPROMPT ? SEQP : SEQS) - 1, pos = tok & S1; isfirst = pos == 0; islast = pos == S1; }
;                     f32x4 cv[2];
; #pragma unroll
;                     for (int bj = 0; bj < 2; ++bj) {
;                         const f32x4 cur = acc[ai][bj][m][n];
;                         const f32x4 ups = m > 0 ? acc[ai][bj][m > 0 ? m - 1 : 0][n] : pe[bj];
;                         const f32x4 dns = m < 3 ? acc[ai][bj][m < 3 ? m + 1 : 3][n] : ne[bj];
;                         f32x4 prev, next;
; #pragma unroll
;                         for (int j = 0; j < 4; ++j) {
;                             const float t1 = fr == 15 ? ups[j] : cur[j]; float pv = dpp_ror1(t1);
;                             const float t2 = fr == 0 ? dns[j] : cur[j]; float nx = dpp_ror15(t2);
;                             if (BND) { prev[j] = isfirst ? 0.f : pv; next[j] = islast ? 0.f : nx; } else { prev[j] = pv; next[j] = nx; }
;                         }
;                         cv[bj] = w0[bj] * prev + w1[bj] * cur + w2[bj] * next + bb[bj];
;                     }
;                     f32x4 a;
; #pragma unroll
;                     for (int j = 0; j < 4; ++j) { const float g = cv[0][j]; const float sg = __builtin_amdgcn_rcpf(1.0f + __builtin_amdgcn_exp2f(-1.4426950408889634f * g)); a[j] = g * sg * cv[1][j]; }
;                     if (r >= 1 && r <= 254 && (!BND || tok < MTOK)) *(u32x2*)(act + (size_t)tok * DFF + fcol + 4 * n) = pack4(a);
;                     asm volatile("" ::: "memory");
.LBB0_742:
	s_or_b64 exec, exec, s[0:1]
	v_cndmask_b32_e64 v0, v16, v168, s[8:9]
	v_cndmask_b32_e64 v1, v16, v64, s[6:7]
	s_nop 0
	v_mov_b32_dpp v3, v0 row_ror:1 row_mask:0xf bank_mask:0xf
	v_cndmask_b32_e64 v2, v17, v65, s[6:7]
	v_mov_b32_dpp v0, v1 row_ror:15 row_mask:0xf bank_mask:0xf
	v_cndmask_b32_e64 v1, v17, v169, s[8:9]
	v_cndmask_b32_e64 v4, v18, v66, s[6:7]
	s_nop 0
	v_mov_b32_dpp v5, v1 row_ror:1 row_mask:0xf bank_mask:0xf
	v_cndmask_b32_e64 v64, v19, v67, s[6:7]
	v_cndmask_b32_e64 v65, v20, v172, s[8:9]
	v_mov_b32_dpp v1, v2 row_ror:15 row_mask:0xf bank_mask:0xf
	v_cndmask_b32_e64 v2, v18, v166, s[8:9]
	v_cndmask_b32_e64 v67, v21, v173, s[8:9]
	s_nop 0
	v_mov_b32_dpp v6, v2 row_ror:1 row_mask:0xf bank_mask:0xf
	v_cndmask_b32_e64 v72, v23, v171, s[8:9]
	s_nop 0
	v_mov_b32_dpp v2, v4 row_ror:15 row_mask:0xf bank_mask:0xf
	v_cndmask_b32_e64 v4, v19, v167, s[8:9]
	s_nop 1
	v_mov_b32_dpp v7, v4 row_ror:1 row_mask:0xf bank_mask:0xf
	v_mov_b32_dpp v4, v64 row_ror:15 row_mask:0xf bank_mask:0xf
	v_mov_b32_dpp v64, v65 row_ror:1 row_mask:0xf bank_mask:0xf
	v_cndmask_b32_e64 v65, v20, v68, s[6:7]
	s_nop 0
	s_nop 0
	v_mov_b32_dpp v66, v65 row_ror:15 row_mask:0xf bank_mask:0xf
	v_mov_b32_dpp v65, v67 row_ror:1 row_mask:0xf bank_mask:0xf
	v_cndmask_b32_e64 v67, v21, v69, s[6:7]
	v_cndmask_b32_e64 v69, v22, v170, s[8:9]
	s_nop 0
	v_mov_b32_dpp v68, v67 row_ror:15 row_mask:0xf bank_mask:0xf
	v_mov_b32_dpp v67, v69 row_ror:1 row_mask:0xf bank_mask:0xf
	v_cndmask_b32_e64 v69, v22, v70, s[6:7]
	s_nop 1
	v_mov_b32_dpp v70, v69 row_ror:15 row_mask:0xf bank_mask:0xf
	v_mov_b32_dpp v69, v72 row_ror:1 row_mask:0xf bank_mask:0xf
	v_cndmask_b32_e64 v72, v23, v71, s[6:7]
	s_nop 1
	v_mov_b32_dpp v71, v72 row_ror:15 row_mask:0xf bank_mask:0xf
	s_and_saveexec_b64 s[0:1], s[90:91]
	s_cbranch_execz .LBB0_744
	v_cndmask_b32_e64 v64, v64, 0, s[30:31]
	v_cndmask_b32_e64 v65, v65, 0, s[30:31]
	v_cndmask_b32_e64 v6, v6, 0, s[30:31]
	v_cndmask_b32_e64 v7, v7, 0, s[30:31]
	s_waitcnt vmcnt(3)
	v_pk_mul_f32 v[64:65], v[60:61], v[64:65]
	v_pk_mul_f32 v[6:7], v[42:43], v[6:7]
	s_waitcnt vmcnt(2)
	v_pk_fma_f32 v[20:21], v[20:21], v[56:57], v[64:65]
	v_cndmask_b32_e64 v64, v3, 0, s[30:31]
	v_pk_fma_f32 v[6:7], v[18:19], v[46:47], v[6:7]
	v_cndmask_b32_e64 v2, v2, 0, s[18:19]
	v_cndmask_b32_e64 v3, v4, 0, s[18:19]
	v_pk_fma_f32 v[2:3], v[38:39], v[2:3], v[6:7]
	v_cndmask_b32_e64 v65, v5, 0, s[30:31]
	v_pk_add_f32 v[2:3], v[34:35], v[2:3]
	v_pk_mul_f32 v[64:65], v[40:41], v[64:65]
	v_mul_f32_e32 v4, 0xbfb8aa3b, v3
	v_exp_f32_e32 v4, v4
	v_mul_f32_e32 v5, 0xbfb8aa3b, v2
	v_exp_f32_e32 v5, v5
	v_pk_fma_f32 v[16:17], v[16:17], v[44:45], v[64:65]
	v_add_f32_e32 v4, 1.0, v4
	v_rcp_f32_e32 v4, v4
	v_cndmask_b32_e64 v0, v0, 0, s[18:19]
	v_cndmask_b32_e64 v1, v1, 0, s[18:19]
	v_pk_fma_f32 v[0:1], v[36:37], v[0:1], v[16:17]
	v_mul_f32_e32 v3, v3, v4
	v_pk_add_f32 v[0:1], v[32:33], v[0:1]
	v_add_f32_e32 v4, 1.0, v5
	v_mul_f32_e32 v5, 0xbfb8aa3b, v1
	v_mul_f32_e32 v6, 0xbfb8aa3b, v0
	v_rcp_f32_e32 v4, v4
	v_exp_f32_e32 v5, v5
	v_exp_f32_e32 v6, v6
	v_cndmask_b32_e64 v72, v66, 0, s[18:19]
	v_mul_f32_e32 v2, v2, v4
	v_add_f32_e32 v4, 1.0, v5
	v_add_f32_e32 v5, 1.0, v6
	v_cndmask_b32_e64 v66, v67, 0, s[30:31]
	v_cndmask_b32_e64 v67, v69, 0, s[30:31]
	v_rcp_f32_e32 v4, v4
	v_rcp_f32_e32 v5, v5
	v_pk_mul_f32 v[66:67], v[62:63], v[66:67]
	v_cndmask_b32_e64 v73, v68, 0, s[18:19]
	v_cndmask_b32_e64 v70, v70, 0, s[18:19]
	v_cndmask_b32_e64 v71, v71, 0, s[18:19]
	v_pk_fma_f32 v[22:23], v[22:23], v[58:59], v[66:67]
	s_waitcnt vmcnt(1)
	v_pk_fma_f32 v[20:21], v[52:53], v[72:73], v[20:21]
	v_pk_fma_f32 v[22:23], v[54:55], v[70:71], v[22:23]
	s_waitcnt vmcnt(0)
	v_pk_add_f32 v[20:21], v[48:49], v[20:21]
	v_pk_add_f32 v[22:23], v[50:51], v[22:23]
	v_mul_f32_e32 v1, v1, v4
	v_mul_f32_e32 v0, v0, v5
	v_mul_f32_e32 v3, v3, v23
	v_mul_f32_e32 v2, v2, v22
	v_mul_f32_e32 v1, v1, v21
	v_mul_f32_e32 v0, v0, v20
	v_cvt_pk_bf16_f32 v0, v0, v1
	v_cvt_pk_bf16_f32 v1, v2, v3
	v_mov_b64_e32 v[2:3], s[88:89]
	s_movk_i32 s4, 0x1600
	v_mad_i64_i32 v[2:3], s[4:5], v106, s4, v[2:3]
	v_lshl_add_u64 v[2:3], v[190:191], 1, v[2:3]
	global_store_dwordx2 v[2:3], v[0:1], off offset:8

; __device__ __forceinline__ u32x2 pack4(f32x4 a) { u32x2 w; w.x = cvt_pk_bf16(a[0], a[1]); w.y = cvt_pk_bf16(a[2], a[3]); return w; }
; __device__ __forceinline__ float dpp_ror1(float v) { return __builtin_bit_cast(float, __builtin_amdgcn_update_dpp(0, __builtin_bit_cast(int, v), 0x121, 0xf, 0xf, false)); }
; __device__ __forceinline__ float dpp_ror15(float v) { return __builtin_bit_cast(float, __builtin_amdgcn_update_dpp(0, __builtin_bit_cast(int, v), 0x12F, 0xf, 0xf, false)); }
;     template <bool BND> __device__ __forceinline__ void conv_gate(f32x4 (&acc)[2][2][4][2], const Unit& u, int wr, int wc, int fr, int fq, int tok0, int pcol) const {
;     ...
;                 for (int m = 0; m < 4; ++m) {
;                     const int r = ai * 128 + wr * 64 + m * 16 + fr, tok = tok0 + r;
;                     bool isfirst = false, islast = false;
;                     if (BND) { const int S1 = (tok < NPROMPT ? SEQP : SEQS) - 1, pos = tok & S1; isfirst = pos == 0; islast = pos == S1; }
;                     f32x4 cv[2];
; #pragma unroll
;                     for (int bj = 0; bj < 2; ++bj) {
;                         const f32x4 cur = acc[ai][bj][m][n];
;                         const f32x4 ups = m > 0 ? acc[ai][bj][m > 0 ? m - 1 : 0][n] : pe[bj];
;                         const f32x4 dns = m < 3 ? acc[ai][bj][m < 3 ? m + 1 : 3][n] : ne[bj];
;                         f32x4 prev, next;
; #pragma unroll
;                         for (int j = 0; j < 4; ++j) {
;                             const float t1 = fr == 15 ? ups[j] : cur[j]; float pv = dpp_ror1(t1);
;                             const float t2 = fr == 0 ? dns[j] : cur[j]; float nx = dpp_ror15(t2);
;                             if (BND) { prev[j] = isfirst ? 0.f : pv; next[j] = islast ? 0.f : nx; } else { prev[j] = pv; next[j] = nx; }
;                         }
;                         cv[bj] = w0[bj] * prev + w1[bj] * cur + w2[bj] * next + bb[bj];
;                     }
;                     f32x4 a;
; #pragma unroll
;                     for (int j = 0; j < 4; ++j) { const float g = cv[0][j]; const float sg = __builtin_amdgcn_rcpf(1.0f + __builtin_amdgcn_exp2f(-1.4426950408889634f * g)); a[j] = g * sg * cv[1][j]; }
;                     if (r >= 1 && r <= 254 && (!BND || tok < MTOK)) *(u32x2*)(act + (size_t)tok * DFF + fcol + 4 * n) = pack4(a);
;                     asm volatile("" ::: "memory");
.LBB0_752:
	s_waitcnt lgkmcnt(0)
	v_cndmask_b32_e64 v16, v8, v16, s[8:9]
	v_cndmask_b32_e64 v65, v8, v176, s[6:7]
	v_cndmask_b32_e64 v17, v9, v17, s[8:9]
	v_mov_b32_dpp v64, v16 row_ror:1 row_mask:0xf bank_mask:0xf
	v_cndmask_b32_e64 v66, v9, v177, s[6:7]
	v_cndmask_b32_e64 v18, v10, v18, s[8:9]
	v_mov_b32_dpp v16, v65 row_ror:15 row_mask:0xf bank_mask:0xf
	v_cndmask_b32_e64 v67, v10, v174, s[6:7]
	v_cndmask_b32_e64 v19, v11, v19, s[8:9]
	v_mov_b32_dpp v65, v17 row_ror:1 row_mask:0xf bank_mask:0xf
	v_cndmask_b32_e64 v68, v11, v175, s[6:7]
	v_cndmask_b32_e64 v69, v12, v180, s[6:7]
	v_mov_b32_dpp v17, v66 row_ror:15 row_mask:0xf bank_mask:0xf
	v_cndmask_b32_e64 v70, v13, v181, s[6:7]
	v_cndmask_b32_e64 v71, v14, v178, s[6:7]
	v_mov_b32_dpp v66, v18 row_ror:1 row_mask:0xf bank_mask:0xf
	v_cndmask_b32_e64 v72, v15, v179, s[6:7]
	s_nop 0
	v_mov_b32_dpp v18, v67 row_ror:15 row_mask:0xf bank_mask:0xf
	v_mov_b32_dpp v67, v19 row_ror:1 row_mask:0xf bank_mask:0xf
	v_mov_b32_dpp v19, v68 row_ror:15 row_mask:0xf bank_mask:0xf
	v_cndmask_b32_e64 v68, v12, v20, s[8:9]
	s_nop 1
	v_mov_b32_dpp v20, v68 row_ror:1 row_mask:0xf bank_mask:0xf
	v_mov_b32_dpp v68, v69 row_ror:15 row_mask:0xf bank_mask:0xf
	v_cndmask_b32_e64 v69, v13, v21, s[8:9]
	s_nop 1
	v_mov_b32_dpp v21, v69 row_ror:1 row_mask:0xf bank_mask:0xf
	v_mov_b32_dpp v69, v70 row_ror:15 row_mask:0xf bank_mask:0xf
	v_cndmask_b32_e64 v70, v14, v22, s[8:9]
	s_nop 1
	v_mov_b32_dpp v22, v70 row_ror:1 row_mask:0xf bank_mask:0xf
	v_mov_b32_dpp v70, v71 row_ror:15 row_mask:0xf bank_mask:0xf
	v_cndmask_b32_e64 v71, v15, v23, s[8:9]
	s_nop 1
	v_mov_b32_dpp v23, v71 row_ror:1 row_mask:0xf bank_mask:0xf
	v_mov_b32_dpp v71, v72 row_ror:15 row_mask:0xf bank_mask:0xf
	s_and_saveexec_b64 s[0:1], s[66:67]
	s_mov_b32 s48, s79
	s_mov_b32 s50, s74
	s_movk_i32 s84, 0xfe
	s_cbranch_execz .LBB0_754
	v_cndmask_b32_e64 v66, v66, 0, s[40:41]
	v_cndmask_b32_e64 v67, v67, 0, s[40:41]
	s_waitcnt vmcnt(7)
	v_pk_mul_f32 v[66:67], v[42:43], v[66:67]
	v_cndmask_b32_e64 v18, v18, 0, s[24:25]
	s_waitcnt vmcnt(6)
	v_pk_fma_f32 v[66:67], v[10:11], v[46:47], v[66:67]
	v_cndmask_b32_e64 v19, v19, 0, s[24:25]
	s_waitcnt vmcnt(5)
	v_pk_fma_f32 v[18:19], v[38:39], v[18:19], v[66:67]
	v_cndmask_b32_e64 v64, v64, 0, s[40:41]
	s_waitcnt vmcnt(4)
	v_pk_add_f32 v[18:19], v[34:35], v[18:19]
	v_cndmask_b32_e64 v65, v65, 0, s[40:41]
	v_mul_f32_e32 v66, 0xbfb8aa3b, v19
	v_exp_f32_e32 v66, v66
	v_pk_mul_f32 v[64:65], v[40:41], v[64:65]
	v_cndmask_b32_e64 v16, v16, 0, s[24:25]
	v_pk_fma_f32 v[64:65], v[8:9], v[44:45], v[64:65]
	v_cndmask_b32_e64 v17, v17, 0, s[24:25]
	v_pk_fma_f32 v[16:17], v[36:37], v[16:17], v[64:65]
	v_add_f32_e32 v64, 1.0, v66
	v_cndmask_b32_e64 v22, v22, 0, s[40:41]
	v_cndmask_b32_e64 v23, v23, 0, s[40:41]
	v_rcp_f32_e32 v64, v64
	v_mul_f32_e32 v65, 0xbfb8aa3b, v18
	s_waitcnt vmcnt(3)
	v_pk_mul_f32 v[22:23], v[62:63], v[22:23]
	v_exp_f32_e32 v65, v65
	v_cndmask_b32_e64 v70, v70, 0, s[24:25]
	v_cndmask_b32_e64 v71, v71, 0, s[24:25]
	s_waitcnt vmcnt(2)
	v_pk_fma_f32 v[22:23], v[14:15], v[58:59], v[22:23]
	v_pk_add_f32 v[16:17], v[32:33], v[16:17]
	s_waitcnt vmcnt(1)
	v_pk_fma_f32 v[22:23], v[54:55], v[70:71], v[22:23]
	v_mul_f32_e32 v19, v19, v64
	s_waitcnt vmcnt(0)
	v_pk_add_f32 v[22:23], v[50:51], v[22:23]
	v_mul_f32_e32 v64, 0xbfb8aa3b, v17
	v_mul_f32_e32 v19, v19, v23
	v_add_f32_e32 v23, 1.0, v65
	v_mul_f32_e32 v65, 0xbfb8aa3b, v16
	v_rcp_f32_e32 v23, v23
	v_exp_f32_e32 v64, v64
	v_exp_f32_e32 v65, v65
	v_cndmask_b32_e64 v20, v20, 0, s[40:41]
	v_mul_f32_e32 v18, v18, v23
	v_add_f32_e32 v23, 1.0, v64
	v_add_f32_e32 v64, 1.0, v65
	v_cndmask_b32_e64 v21, v21, 0, s[40:41]
	v_rcp_f32_e32 v23, v23
	v_rcp_f32_e32 v64, v64
	v_pk_mul_f32 v[20:21], v[60:61], v[20:21]
	v_cndmask_b32_e64 v68, v68, 0, s[24:25]
	v_cndmask_b32_e64 v69, v69, 0, s[24:25]
	v_pk_fma_f32 v[20:21], v[12:13], v[56:57], v[20:21]
	v_mul_f32_e32 v17, v17, v23
	v_pk_fma_f32 v[20:21], v[52:53], v[68:69], v[20:21]
	v_mul_f32_e32 v16, v16, v64
	v_pk_add_f32 v[20:21], v[48:49], v[20:21]
	v_mul_f32_e32 v18, v18, v22
	v_mul_f32_e32 v17, v17, v21
	v_mul_f32_e32 v16, v16, v20
	v_cvt_pk_bf16_f32 v16, v16, v17
	v_cvt_pk_bf16_f32 v17, v18, v19
	v_mov_b64_e32 v[18:19], s[88:89]
	s_movk_i32 s4, 0x1600
	v_mad_i64_i32 v[18:19], s[4:5], v96, s4, v[18:19]
	v_lshl_add_u64 v[18:19], v[190:191], 1, v[18:19]
	global_store_dwordx2 v[18:19], v[16:17], off offset:8
; __device__ __forceinline__ u32x2 pack4(f32x4 a) { u32x2 w; w.x = cvt_pk_bf16(a[0], a[1]); w.y = cvt_pk_bf16(a[2], a[3]); return w; }
; __device__ __forceinline__ float dpp_ror1(float v) { return __builtin_bit_cast(float, __builtin_amdgcn_update_dpp(0, __builtin_bit_cast(int, v), 0x121, 0xf, 0xf, false)); }
; __device__ __forceinline__ float dpp_ror15(float v) { return __builtin_bit_cast(float, __builtin_amdgcn_update_dpp(0, __builtin_bit_cast(int, v), 0x12F, 0xf, 0xf, false)); }
;     template <bool BND> __device__ __forceinline__ void conv_gate(f32x4 (&acc)[2][2][4][2], const Unit& u, int wr, int wc, int fr, int fq, int tok0, int pcol) const {
;     ...
;                 for (int m = 0; m < 4; ++m) {
;                     const int r = ai * 128 + wr * 64 + m * 16 + fr, tok = tok0 + r;
;                     bool isfirst = false, islast = false;
;                     if (BND) { const int S1 = (tok < NPROMPT ? SEQP : SEQS) - 1, pos = tok & S1; isfirst = pos == 0; islast = pos == S1; }
;                     f32x4 cv[2];
; #pragma unroll
;                     for (int bj = 0; bj < 2; ++bj) {
;                         const f32x4 cur = acc[ai][bj][m][n];
;                         const f32x4 ups = m > 0 ? acc[ai][bj][m > 0 ? m - 1 : 0][n] : pe[bj];
;                         const f32x4 dns = m < 3 ? acc[ai][bj][m < 3 ? m + 1 : 3][n] : ne[bj];
;                         f32x4 prev, next;
; #pragma unroll
;                         for (int j = 0; j < 4; ++j) {
;                             const float t1 = fr == 15 ? ups[j] : cur[j]; float pv = dpp_ror1(t1);
;                             const float t2 = fr == 0 ? dns[j] : cur[j]; float nx = dpp_ror15(t2);
;                             if (BND) { prev[j] = isfirst ? 0.f : pv; next[j] = islast ? 0.f : nx; } else { prev[j] = pv; next[j] = nx; }
;                         }
;                         cv[bj] = w0[bj] * prev + w1[bj] * cur + w2[bj] * next + bb[bj];
;                     }
;                     f32x4 a;
; #pragma unroll
;                     for (int j = 0; j < 4; ++j) { const float g = cv[0][j]; const float sg = __builtin_amdgcn_rcpf(1.0f + __builtin_amdgcn_exp2f(-1.4426950408889634f * g)); a[j] = g * sg * cv[1][j]; }
;                     if (r >= 1 && r <= 254 && (!BND || tok < MTOK)) *(u32x2*)(act + (size_t)tok * DFF + fcol + 4 * n) = pack4(a);
;                     asm volatile("" ::: "memory");
.LBB0_754:
	s_or_b64 exec, exec, s[0:1]
	v_cndmask_b32_e64 v8, v176, v8, s[8:9]
	v_cndmask_b32_e64 v17, v176, v184, s[6:7]
	v_cndmask_b32_e64 v9, v177, v9, s[8:9]
	v_mov_b32_dpp v16, v8 row_ror:1 row_mask:0xf bank_mask:0xf
	v_cndmask_b32_e64 v18, v177, v185, s[6:7]
	v_cndmask_b32_e64 v10, v174, v10, s[8:9]
	v_mov_b32_dpp v8, v17 row_ror:15 row_mask:0xf bank_mask:0xf
	v_cndmask_b32_e64 v19, v174, v182, s[6:7]
	v_cndmask_b32_e64 v11, v175, v11, s[8:9]
	v_mov_b32_dpp v17, v9 row_ror:1 row_mask:0xf bank_mask:0xf
	v_cndmask_b32_e64 v20, v175, v183, s[6:7]
	v_cndmask_b32_e64 v21, v180, v188, s[6:7]
	v_mov_b32_dpp v9, v18 row_ror:15 row_mask:0xf bank_mask:0xf
	v_cndmask_b32_e64 v22, v181, v189, s[6:7]
	v_cndmask_b32_e64 v23, v178, v186, s[6:7]
	v_mov_b32_dpp v18, v10 row_ror:1 row_mask:0xf bank_mask:0xf
	v_cndmask_b32_e64 v64, v179, v187, s[6:7]
	s_nop 0
	v_mov_b32_dpp v10, v19 row_ror:15 row_mask:0xf bank_mask:0xf
	v_mov_b32_dpp v19, v11 row_ror:1 row_mask:0xf bank_mask:0xf
	v_mov_b32_dpp v11, v20 row_ror:15 row_mask:0xf bank_mask:0xf
	v_cndmask_b32_e64 v20, v180, v12, s[8:9]
	s_nop 1
	v_mov_b32_dpp v12, v20 row_ror:1 row_mask:0xf bank_mask:0xf
	v_mov_b32_dpp v20, v21 row_ror:15 row_mask:0xf bank_mask:0xf
	v_cndmask_b32_e64 v21, v181, v13, s[8:9]
	s_nop 1
	v_mov_b32_dpp v13, v21 row_ror:1 row_mask:0xf bank_mask:0xf
	v_mov_b32_dpp v21, v22 row_ror:15 row_mask:0xf bank_mask:0xf
	v_cndmask_b32_e64 v22, v178, v14, s[8:9]
	s_nop 1
	v_mov_b32_dpp v14, v22 row_ror:1 row_mask:0xf bank_mask:0xf
	v_mov_b32_dpp v22, v23 row_ror:15 row_mask:0xf bank_mask:0xf
	v_cndmask_b32_e64 v23, v179, v15, s[8:9]
	s_nop 1
	v_mov_b32_dpp v15, v23 row_ror:1 row_mask:0xf bank_mask:0xf
	v_mov_b32_dpp v23, v64 row_ror:15 row_mask:0xf bank_mask:0xf
	s_and_saveexec_b64 s[0:1], s[68:69]
	v_readlane_b32 s60, v255, 12
	v_readlane_b32 s61, v255, 13
	s_mov_b32 s56, 0x10000
	v_readlane_b32 s51, v255, 39
	v_readlane_b32 s57, v255, 40
	v_readlane_b32 s68, v255, 41
	s_mov_b32 s69, 0x20000
	v_readlane_b32 s74, v255, 42
	v_readlane_b32 s79, v255, 43
	s_cbranch_execz .LBB0_756
	v_cndmask_b32_e64 v18, v18, 0, s[42:43]
	v_cndmask_b32_e64 v19, v19, 0, s[42:43]
	s_waitcnt vmcnt(7)
	v_pk_mul_f32 v[18:19], v[42:43], v[18:19]
	v_cndmask_b32_e64 v10, v10, 0, s[28:29]
	s_waitcnt vmcnt(6)
	v_pk_fma_f32 v[18:19], v[174:175], v[46:47], v[18:19]
	v_cndmask_b32_e64 v11, v11, 0, s[28:29]
	s_waitcnt vmcnt(5)
	v_pk_fma_f32 v[10:11], v[38:39], v[10:11], v[18:19]
	v_cndmask_b32_e64 v16, v16, 0, s[42:43]
	s_waitcnt vmcnt(4)
	v_pk_add_f32 v[10:11], v[34:35], v[10:11]
	v_cndmask_b32_e64 v17, v17, 0, s[42:43]
	v_mul_f32_e32 v18, 0xbfb8aa3b, v11
	v_exp_f32_e32 v18, v18
	v_pk_mul_f32 v[16:17], v[40:41], v[16:17]
	v_cndmask_b32_e64 v8, v8, 0, s[28:29]
	v_pk_fma_f32 v[16:17], v[176:177], v[44:45], v[16:17]
	v_cndmask_b32_e64 v9, v9, 0, s[28:29]
	v_pk_fma_f32 v[8:9], v[36:37], v[8:9], v[16:17]
	v_add_f32_e32 v16, 1.0, v18
	v_cndmask_b32_e64 v14, v14, 0, s[42:43]
	v_cndmask_b32_e64 v15, v15, 0, s[42:43]
	v_rcp_f32_e32 v16, v16
	v_mul_f32_e32 v17, 0xbfb8aa3b, v10
	s_waitcnt vmcnt(3)
	v_pk_mul_f32 v[14:15], v[62:63], v[14:15]
	v_exp_f32_e32 v17, v17
	v_cndmask_b32_e64 v22, v22, 0, s[28:29]
	v_cndmask_b32_e64 v23, v23, 0, s[28:29]
	s_waitcnt vmcnt(2)
	v_pk_fma_f32 v[14:15], v[178:179], v[58:59], v[14:15]
	v_pk_add_f32 v[8:9], v[32:33], v[8:9]
	s_waitcnt vmcnt(1)
	v_pk_fma_f32 v[14:15], v[54:55], v[22:23], v[14:15]
	v_mul_f32_e32 v11, v11, v16
	s_waitcnt vmcnt(0)
	v_pk_add_f32 v[14:15], v[50:51], v[14:15]
	v_mul_f32_e32 v16, 0xbfb8aa3b, v9
	v_mul_f32_e32 v11, v11, v15
	v_add_f32_e32 v15, 1.0, v17
	v_mul_f32_e32 v17, 0xbfb8aa3b, v8
	v_rcp_f32_e32 v15, v15
	v_exp_f32_e32 v16, v16
	v_exp_f32_e32 v17, v17
	v_cndmask_b32_e64 v12, v12, 0, s[42:43]
	v_mul_f32_e32 v10, v10, v15
	v_add_f32_e32 v15, 1.0, v16
	v_add_f32_e32 v16, 1.0, v17
	v_cndmask_b32_e64 v13, v13, 0, s[42:43]
	v_rcp_f32_e32 v15, v15
	v_rcp_f32_e32 v16, v16
	v_pk_mul_f32 v[12:13], v[60:61], v[12:13]
	v_cndmask_b32_e64 v20, v20, 0, s[28:29]
	v_cndmask_b32_e64 v21, v21, 0, s[28:29]
	v_pk_fma_f32 v[12:13], v[180:181], v[56:57], v[12:13]
	v_mul_f32_e32 v9, v9, v15
	v_pk_fma_f32 v[12:13], v[52:53], v[20:21], v[12:13]
	v_mul_f32_e32 v8, v8, v16
	v_pk_add_f32 v[12:13], v[48:49], v[12:13]
	v_mul_f32_e32 v10, v10, v14
	v_mul_f32_e32 v9, v9, v13
	v_mul_f32_e32 v8, v8, v12
	v_cvt_pk_bf16_f32 v8, v8, v9
	v_cvt_pk_bf16_f32 v9, v10, v11
	v_mov_b64_e32 v[10:11], s[88:89]
	s_movk_i32 s4, 0x1600
	v_mad_i64_i32 v[10:11], s[4:5], v97, s4, v[10:11]
	v_lshl_add_u64 v[10:11], v[190:191], 1, v[10:11]
	global_store_dwordx2 v[10:11], v[8:9], off offset:8
; __device__ __forceinline__ u32x2 pack4(f32x4 a) { u32x2 w; w.x = cvt_pk_bf16(a[0], a[1]); w.y = cvt_pk_bf16(a[2], a[3]); return w; }
; __device__ __forceinline__ float dpp_ror1(float v) { return __builtin_bit_cast(float, __builtin_amdgcn_update_dpp(0, __builtin_bit_cast(int, v), 0x121, 0xf, 0xf, false)); }
; __device__ __forceinline__ float dpp_ror15(float v) { return __builtin_bit_cast(float, __builtin_amdgcn_update_dpp(0, __builtin_bit_cast(int, v), 0x12F, 0xf, 0xf, false)); }
;     template <bool BND> __device__ __forceinline__ void conv_gate(f32x4 (&acc)[2][2][4][2], const Unit& u, int wr, int wc, int fr, int fq, int tok0, int pcol) const {
;     ...
;                 for (int m = 0; m < 4; ++m) {
;                     const int r = ai * 128 + wr * 64 + m * 16 + fr, tok = tok0 + r;
;                     bool isfirst = false, islast = false;
;                     if (BND) { const int S1 = (tok < NPROMPT ? SEQP : SEQS) - 1, pos = tok & S1; isfirst = pos == 0; islast = pos == S1; }
;                     f32x4 cv[2];
; #pragma unroll
;                     for (int bj = 0; bj < 2; ++bj) {
;                         const f32x4 cur = acc[ai][bj][m][n];
;                         const f32x4 ups = m > 0 ? acc[ai][bj][m > 0 ? m - 1 : 0][n] : pe[bj];
;                         const f32x4 dns = m < 3 ? acc[ai][bj][m < 3 ? m + 1 : 3][n] : ne[bj];
;                         f32x4 prev, next;
; #pragma unroll
;                         for (int j = 0; j < 4; ++j) {
;                             const float t1 = fr == 15 ? ups[j] : cur[j]; float pv = dpp_ror1(t1);
;                             const float t2 = fr == 0 ? dns[j] : cur[j]; float nx = dpp_ror15(t2);
;                             if (BND) { prev[j] = isfirst ? 0.f : pv; next[j] = islast ? 0.f : nx; } else { prev[j] = pv; next[j] = nx; }
;                         }
;                         cv[bj] = w0[bj] * prev + w1[bj] * cur + w2[bj] * next + bb[bj];
;                     }
;                     f32x4 a;
; #pragma unroll
;                     for (int j = 0; j < 4; ++j) { const float g = cv[0][j]; const float sg = __builtin_amdgcn_rcpf(1.0f + __builtin_amdgcn_exp2f(-1.4426950408889634f * g)); a[j] = g * sg * cv[1][j]; }
;                     if (r >= 1 && r <= 254 && (!BND || tok < MTOK)) *(u32x2*)(act + (size_t)tok * DFF + fcol + 4 * n) = pack4(a);
;                     asm volatile("" ::: "memory");
.LBB0_756:
	s_or_b64 exec, exec, s[0:1]
	v_cndmask_b32_e64 v8, v184, v176, s[8:9]
	v_cndmask_b32_e64 v9, v184, v24, s[6:7]
	s_nop 0
	v_mov_b32_dpp v11, v8 row_ror:1 row_mask:0xf bank_mask:0xf
	v_cndmask_b32_e64 v10, v185, v25, s[6:7]
	v_mov_b32_dpp v8, v9 row_ror:15 row_mask:0xf bank_mask:0xf
	v_cndmask_b32_e64 v9, v185, v177, s[8:9]
	v_cndmask_b32_e64 v12, v182, v26, s[6:7]
	s_nop 0
	v_mov_b32_dpp v13, v9 row_ror:1 row_mask:0xf bank_mask:0xf
	v_cndmask_b32_e64 v16, v183, v27, s[6:7]
	v_cndmask_b32_e64 v17, v188, v180, s[8:9]
	v_mov_b32_dpp v9, v10 row_ror:15 row_mask:0xf bank_mask:0xf
	v_cndmask_b32_e64 v10, v182, v174, s[8:9]
	v_cndmask_b32_e64 v19, v189, v181, s[8:9]
	s_nop 0
	v_mov_b32_dpp v14, v10 row_ror:1 row_mask:0xf bank_mask:0xf
	v_cndmask_b32_e64 v21, v186, v178, s[8:9]
	v_mov_b32_dpp v10, v12 row_ror:15 row_mask:0xf bank_mask:0xf
	v_cndmask_b32_e64 v12, v183, v175, s[8:9]
	v_cndmask_b32_e64 v23, v187, v179, s[8:9]
	s_nop 0
	v_mov_b32_dpp v15, v12 row_ror:1 row_mask:0xf bank_mask:0xf
	v_cndmask_b32_e64 v64, v187, v31, s[6:7]
	s_nop 0
	v_mov_b32_dpp v12, v16 row_ror:15 row_mask:0xf bank_mask:0xf
	v_mov_b32_dpp v16, v17 row_ror:1 row_mask:0xf bank_mask:0xf
	v_cndmask_b32_e64 v17, v188, v28, s[6:7]
	s_nop 1
	v_mov_b32_dpp v18, v17 row_ror:15 row_mask:0xf bank_mask:0xf
	v_mov_b32_dpp v17, v19 row_ror:1 row_mask:0xf bank_mask:0xf
	v_cndmask_b32_e64 v19, v189, v29, s[6:7]
	s_nop 1
	v_mov_b32_dpp v20, v19 row_ror:15 row_mask:0xf bank_mask:0xf
	v_mov_b32_dpp v19, v21 row_ror:1 row_mask:0xf bank_mask:0xf
	v_cndmask_b32_e64 v21, v186, v30, s[6:7]
	s_nop 1
	v_mov_b32_dpp v22, v21 row_ror:15 row_mask:0xf bank_mask:0xf
	v_mov_b32_dpp v21, v23 row_ror:1 row_mask:0xf bank_mask:0xf
	v_mov_b32_dpp v23, v64 row_ror:15 row_mask:0xf bank_mask:0xf
	s_and_saveexec_b64 s[0:1], s[70:71]
	s_cbranch_execz .LBB0_758
	v_cndmask_b32_e64 v14, v14, 0, s[44:45]
	v_cndmask_b32_e64 v15, v15, 0, s[44:45]
	s_waitcnt vmcnt(7)
	v_pk_mul_f32 v[14:15], v[42:43], v[14:15]
	v_cndmask_b32_e64 v65, v20, 0, s[34:35]
	v_cndmask_b32_e64 v20, v11, 0, s[44:45]
	s_waitcnt vmcnt(6)
	v_pk_fma_f32 v[14:15], v[182:183], v[46:47], v[14:15]
	v_cndmask_b32_e64 v10, v10, 0, s[34:35]
	v_cndmask_b32_e64 v11, v12, 0, s[34:35]
	s_waitcnt vmcnt(5)
	v_pk_fma_f32 v[10:11], v[38:39], v[10:11], v[14:15]
	v_cndmask_b32_e64 v64, v18, 0, s[34:35]
	s_waitcnt vmcnt(4)
	v_pk_add_f32 v[10:11], v[34:35], v[10:11]
	v_cndmask_b32_e64 v18, v19, 0, s[44:45]
	v_mul_f32_e32 v12, 0xbfb8aa3b, v11
	v_exp_f32_e32 v12, v12
	v_cndmask_b32_e64 v19, v21, 0, s[44:45]
	v_cndmask_b32_e64 v21, v13, 0, s[44:45]
	v_mul_f32_e32 v13, 0xbfb8aa3b, v10
	v_add_f32_e32 v12, 1.0, v12
	v_pk_mul_f32 v[20:21], v[40:41], v[20:21]
	v_rcp_f32_e32 v12, v12
	v_exp_f32_e32 v13, v13
	v_pk_fma_f32 v[20:21], v[184:185], v[44:45], v[20:21]
	v_cndmask_b32_e64 v8, v8, 0, s[34:35]
	v_cndmask_b32_e64 v9, v9, 0, s[34:35]
	v_pk_fma_f32 v[8:9], v[36:37], v[8:9], v[20:21]
	v_mul_f32_e32 v11, v11, v12
	v_pk_add_f32 v[8:9], v[32:33], v[8:9]
	v_add_f32_e32 v12, 1.0, v13
	v_mul_f32_e32 v13, 0xbfb8aa3b, v9
	v_mul_f32_e32 v14, 0xbfb8aa3b, v8
	v_rcp_f32_e32 v12, v12
	v_exp_f32_e32 v13, v13
	v_exp_f32_e32 v14, v14
	v_cndmask_b32_e64 v16, v16, 0, s[44:45]
	v_mul_f32_e32 v10, v10, v12
	v_add_f32_e32 v12, 1.0, v13
	v_add_f32_e32 v13, 1.0, v14
	v_cndmask_b32_e64 v17, v17, 0, s[44:45]
	v_rcp_f32_e32 v12, v12
	v_rcp_f32_e32 v13, v13
	s_waitcnt vmcnt(3)
	v_pk_mul_f32 v[18:19], v[62:63], v[18:19]
	v_pk_mul_f32 v[16:17], v[60:61], v[16:17]
	v_cndmask_b32_e64 v22, v22, 0, s[34:35]
	v_cndmask_b32_e64 v23, v23, 0, s[34:35]
	s_waitcnt vmcnt(2)
	v_pk_fma_f32 v[16:17], v[188:189], v[56:57], v[16:17]
	v_pk_fma_f32 v[18:19], v[186:187], v[58:59], v[18:19]
	s_waitcnt vmcnt(1)
	v_pk_fma_f32 v[16:17], v[52:53], v[64:65], v[16:17]
	v_pk_fma_f32 v[18:19], v[54:55], v[22:23], v[18:19]
	s_waitcnt vmcnt(0)
	v_pk_add_f32 v[16:17], v[48:49], v[16:17]
	v_pk_add_f32 v[18:19], v[50:51], v[18:19]
	v_mul_f32_e32 v9, v9, v12
	v_mul_f32_e32 v8, v8, v13
	v_mul_f32_e32 v11, v11, v19
	v_mul_f32_e32 v10, v10, v18
	v_mul_f32_e32 v9, v9, v17
	v_mul_f32_e32 v8, v8, v16
	v_cvt_pk_bf16_f32 v8, v8, v9
	v_cvt_pk_bf16_f32 v9, v10, v11
	v_mov_b64_e32 v[10:11], s[88:89]
	s_movk_i32 s4, 0x1600
	v_mad_i64_i32 v[10:11], s[4:5], v98, s4, v[10:11]
	v_lshl_add_u64 v[10:11], v[190:191], 1, v[10:11]
	global_store_dwordx2 v[10:11], v[8:9], off offset:8
; __device__ __forceinline__ u32x2 pack4(f32x4 a) { u32x2 w; w.x = cvt_pk_bf16(a[0], a[1]); w.y = cvt_pk_bf16(a[2], a[3]); return w; }
; __device__ __forceinline__ float dpp_ror1(float v) { return __builtin_bit_cast(float, __builtin_amdgcn_update_dpp(0, __builtin_bit_cast(int, v), 0x121, 0xf, 0xf, false)); }
; __device__ __forceinline__ float dpp_ror15(float v) { return __builtin_bit_cast(float, __builtin_amdgcn_update_dpp(0, __builtin_bit_cast(int, v), 0x12F, 0xf, 0xf, false)); }
;     template <bool BND> __device__ __forceinline__ void conv_gate(f32x4 (&acc)[2][2][4][2], const Unit& u, int wr, int wc, int fr, int fq, int tok0, int pcol) const {
;     ...
;                 for (int m = 0; m < 4; ++m) {
;                     const int r = ai * 128 + wr * 64 + m * 16 + fr, tok = tok0 + r;
;                     bool isfirst = false, islast = false;
;                     if (BND) { const int S1 = (tok < NPROMPT ? SEQP : SEQS) - 1, pos = tok & S1; isfirst = pos == 0; islast = pos == S1; }
;                     f32x4 cv[2];
; #pragma unroll
;                     for (int bj = 0; bj < 2; ++bj) {
;                         const f32x4 cur = acc[ai][bj][m][n];
;                         const f32x4 ups = m > 0 ? acc[ai][bj][m > 0 ? m - 1 : 0][n] : pe[bj];
;                         const f32x4 dns = m < 3 ? acc[ai][bj][m < 3 ? m + 1 : 3][n] : ne[bj];
;                         f32x4 prev, next;
; #pragma unroll
;                         for (int j = 0; j < 4; ++j) {
;                             const float t1 = fr == 15 ? ups[j] : cur[j]; float pv = dpp_ror1(t1);
;                             const float t2 = fr == 0 ? dns[j] : cur[j]; float nx = dpp_ror15(t2);
;                             if (BND) { prev[j] = isfirst ? 0.f : pv; next[j] = islast ? 0.f : nx; } else { prev[j] = pv; next[j] = nx; }
;                         }
;                         cv[bj] = w0[bj] * prev + w1[bj] * cur + w2[bj] * next + bb[bj];
;                     }
;                     f32x4 a;
; #pragma unroll
;                     for (int j = 0; j < 4; ++j) { const float g = cv[0][j]; const float sg = __builtin_amdgcn_rcpf(1.0f + __builtin_amdgcn_exp2f(-1.4426950408889634f * g)); a[j] = g * sg * cv[1][j]; }
;                     if (r >= 1 && r <= 254 && (!BND || tok < MTOK)) *(u32x2*)(act + (size_t)tok * DFF + fcol + 4 * n) = pack4(a);
;                     asm volatile("" ::: "memory");
.LBB0_758:
	s_or_b64 exec, exec, s[0:1]
	v_cndmask_b32_e64 v9, v24, v184, s[8:9]
	v_cndmask_b32_e64 v10, v25, v185, s[8:9]
	v_cndmask_b32_e64 v11, v26, v182, s[8:9]
	v_mov_b32_dpp v8, v9 row_ror:1 row_mask:0xf bank_mask:0xf
	v_cndmask_b32_e64 v9, v24, v0, s[6:7]
	v_cndmask_b32_e64 v12, v27, v183, s[8:9]
	v_cndmask_b32_e64 v13, v28, v188, s[8:9]
	v_mov_b32_dpp v0, v9 row_ror:15 row_mask:0xf bank_mask:0xf
	v_cndmask_b32_e64 v14, v29, v189, s[8:9]
	v_cndmask_b32_e64 v15, v30, v186, s[8:9]
	v_mov_b32_dpp v9, v10 row_ror:1 row_mask:0xf bank_mask:0xf
	v_cndmask_b32_e64 v10, v25, v1, s[6:7]
	v_cndmask_b32_e64 v16, v31, v187, s[8:9]
	s_nop 0
	v_mov_b32_dpp v1, v10 row_ror:15 row_mask:0xf bank_mask:0xf
	v_mov_b32_dpp v10, v11 row_ror:1 row_mask:0xf bank_mask:0xf
	v_cndmask_b32_e64 v11, v26, v2, s[6:7]
	s_nop 1
	v_mov_b32_dpp v2, v11 row_ror:15 row_mask:0xf bank_mask:0xf
	v_mov_b32_dpp v11, v12 row_ror:1 row_mask:0xf bank_mask:0xf
	v_cndmask_b32_e64 v12, v27, v3, s[6:7]
	s_nop 1
	v_mov_b32_dpp v3, v12 row_ror:15 row_mask:0xf bank_mask:0xf
	v_mov_b32_dpp v12, v13 row_ror:1 row_mask:0xf bank_mask:0xf
	v_cndmask_b32_e64 v13, v28, v4, s[6:7]
	s_nop 1
	v_mov_b32_dpp v4, v13 row_ror:15 row_mask:0xf bank_mask:0xf
	v_mov_b32_dpp v13, v14 row_ror:1 row_mask:0xf bank_mask:0xf
	v_cndmask_b32_e64 v14, v29, v5, s[6:7]
	s_nop 1
	v_mov_b32_dpp v5, v14 row_ror:15 row_mask:0xf bank_mask:0xf
	v_mov_b32_dpp v14, v15 row_ror:1 row_mask:0xf bank_mask:0xf
	v_cndmask_b32_e64 v15, v30, v6, s[6:7]
	s_nop 1
	v_mov_b32_dpp v6, v15 row_ror:15 row_mask:0xf bank_mask:0xf
	v_mov_b32_dpp v15, v16 row_ror:1 row_mask:0xf bank_mask:0xf
	v_cndmask_b32_e64 v16, v31, v7, s[6:7]
	s_nop 1
	v_mov_b32_dpp v7, v16 row_ror:15 row_mask:0xf bank_mask:0xf
	s_and_saveexec_b64 s[0:1], s[54:55]
	s_cbranch_execz .LBB0_760
	v_cndmask_b32_e64 v10, v10, 0, s[46:47]
	v_cndmask_b32_e64 v11, v11, 0, s[46:47]
	s_waitcnt vmcnt(7)
	v_pk_mul_f32 v[10:11], v[42:43], v[10:11]
	v_cndmask_b32_e64 v2, v2, 0, s[36:37]
	s_waitcnt vmcnt(6)
	v_pk_fma_f32 v[10:11], v[26:27], v[46:47], v[10:11]
	v_cndmask_b32_e64 v3, v3, 0, s[36:37]
	s_waitcnt vmcnt(5)
	v_pk_fma_f32 v[2:3], v[38:39], v[2:3], v[10:11]
	v_cndmask_b32_e64 v8, v8, 0, s[46:47]
	s_waitcnt vmcnt(4)
	v_pk_add_f32 v[2:3], v[34:35], v[2:3]
	v_cndmask_b32_e64 v9, v9, 0, s[46:47]
	v_mul_f32_e32 v10, 0xbfb8aa3b, v3
	v_exp_f32_e32 v10, v10
	v_pk_mul_f32 v[8:9], v[40:41], v[8:9]
	v_cndmask_b32_e64 v0, v0, 0, s[36:37]
	v_pk_fma_f32 v[8:9], v[24:25], v[44:45], v[8:9]
	v_cndmask_b32_e64 v1, v1, 0, s[36:37]
	v_pk_fma_f32 v[0:1], v[36:37], v[0:1], v[8:9]
	v_add_f32_e32 v8, 1.0, v10
	v_cndmask_b32_e64 v14, v14, 0, s[46:47]
	v_cndmask_b32_e64 v15, v15, 0, s[46:47]
	v_rcp_f32_e32 v8, v8
	v_mul_f32_e32 v9, 0xbfb8aa3b, v2
	s_waitcnt vmcnt(3)
	v_pk_mul_f32 v[14:15], v[62:63], v[14:15]
	v_exp_f32_e32 v9, v9
	s_waitcnt vmcnt(2)
	v_pk_fma_f32 v[14:15], v[30:31], v[58:59], v[14:15]
	v_cndmask_b32_e64 v6, v6, 0, s[36:37]
	v_cndmask_b32_e64 v7, v7, 0, s[36:37]
	s_waitcnt vmcnt(1)
	v_pk_fma_f32 v[6:7], v[54:55], v[6:7], v[14:15]
	v_pk_add_f32 v[0:1], v[32:33], v[0:1]
	s_waitcnt vmcnt(0)
	v_pk_add_f32 v[6:7], v[50:51], v[6:7]
	v_mul_f32_e32 v3, v3, v8
	v_mul_f32_e32 v3, v3, v7
	v_add_f32_e32 v7, 1.0, v9
	v_mul_f32_e32 v8, 0xbfb8aa3b, v1
	v_mul_f32_e32 v9, 0xbfb8aa3b, v0
	v_rcp_f32_e32 v7, v7
	v_exp_f32_e32 v8, v8
	v_exp_f32_e32 v9, v9
	v_cndmask_b32_e64 v12, v12, 0, s[46:47]
	v_mul_f32_e32 v2, v2, v7
	v_add_f32_e32 v7, 1.0, v8
	v_add_f32_e32 v8, 1.0, v9
	v_cndmask_b32_e64 v13, v13, 0, s[46:47]
	v_rcp_f32_e32 v7, v7
	v_rcp_f32_e32 v8, v8
	v_pk_mul_f32 v[12:13], v[60:61], v[12:13]
	v_cndmask_b32_e64 v4, v4, 0, s[36:37]
	v_pk_fma_f32 v[12:13], v[28:29], v[56:57], v[12:13]
	v_cndmask_b32_e64 v5, v5, 0, s[36:37]
	v_pk_fma_f32 v[4:5], v[52:53], v[4:5], v[12:13]
	v_mul_f32_e32 v1, v1, v7
	v_pk_add_f32 v[4:5], v[48:49], v[4:5]
	v_mul_f32_e32 v0, v0, v8
	v_mul_f32_e32 v2, v2, v6
	v_mul_f32_e32 v1, v1, v5
	v_mul_f32_e32 v0, v0, v4
	v_cvt_pk_bf16_f32 v0, v0, v1
	v_cvt_pk_bf16_f32 v1, v2, v3
	v_mov_b64_e32 v[2:3], s[88:89]
	s_movk_i32 s4, 0x1600
	v_mad_i64_i32 v[2:3], s[4:5], v99, s4, v[2:3]
	v_lshl_add_u64 v[2:3], v[190:191], 1, v[2:3]
	global_store_dwordx2 v[2:3], v[0:1], off offset:8
